# prep phase and out-projection residual epilogue: read-once f32 loads marked non-temporal so they do not displace inter-phase data in the caches
# speedup vs baseline: 1.0191x; 1.0081x over previous
; __device__ __forceinline__ void rmsnorm_2rows_bf16(const float* x, const float* g, u16* out, int row, int lane) {
;   const float4* xr = (const float4*)(x + (size_t)row * DM);
;   float4 v[2][4]; float ss[2] = {0.f, 0.f};
; #pragma unroll
;   for (int t = 0; t < 2; ++t)
; #pragma unroll
;     for (int i = 0; i < 4; ++i) {
;       const f32x4 w_ = __builtin_nontemporal_load((const f32x4*)(xr + t * (DM / 4) + lane + 64 * i)); v[t][i] = make_float4(w_[0], w_[1], w_[2], w_[3]); }
; #pragma unroll
;   for (int t = 0; t < 2; ++t)
; #pragma unroll
;     for (int i = 0; i < 4; ++i) ss[t] += v[t][i].x * v[t][i].x + v[t][i].y * v[t][i].y + v[t][i].z * v[t][i].z + v[t][i].w * v[t][i].w;
; #pragma unroll
;   for (int off = 32; off >= 1; off >>= 1) { ss[0] += __shfl_xor(ss[0], off); ss[1] += __shfl_xor(ss[1], off); }
; __device__ __forceinline__ void phase_prep(const Params& p, u16* sm) {
;     ...
;       const int r = (it - n_tr - n_rope - n_bias) * 8 + (tid >> 6) * 2;
;       rmsnorm_2rows_bf16(p.x, p.norm_mix, p.hn, r, tid & 63);
.LBB0_12:
	v_cmp_lt_i32_e32 vcc, s28, v1
	s_and_saveexec_b64 s[4:5], vcc
	s_xor_b64 s[38:39], exec, s[4:5]
	s_cbranch_execz .LBB0_36
	s_movk_i32 s4, 0x1c01
	v_cmp_lt_u32_e32 vcc, s4, v1
	s_and_saveexec_b64 s[4:5], vcc
	s_xor_b64 s[6:7], exec, s[4:5]
	s_cbranch_execz .LBB0_25
	s_movk_i32 s4, 0x1c41
	v_cmp_lt_u32_e32 vcc, s4, v1
	s_and_saveexec_b64 s[4:5], vcc
	s_xor_b64 s[8:9], exec, s[4:5]
	s_cbranch_execz .LBB0_16
	v_lshl_add_u32 v34, v1, 13, v163
	v_mov_b32_e32 v35, v38
	v_lshl_add_u64 v[2:3], v[34:35], 2, v[48:49]
	global_load_dwordx4 v[30:33], v[2:3], off nt
	global_load_dwordx4 v[26:29], v[2:3], off offset:1024 nt
	global_load_dwordx4 v[22:25], v[2:3], off offset:2048 nt
	global_load_dwordx4 v[18:21], v[2:3], off offset:3072 nt
	v_add_co_u32_e32 v2, vcc, 0x1000, v2
	s_mov_b32 s4, 0x3a800000
	s_nop 0
	v_addc_co_u32_e32 v3, vcc, 0, v3, vcc
	global_load_dwordx4 v[14:17], v[2:3], off nt
	global_load_dwordx4 v[10:13], v[2:3], off offset:1024 nt
	global_load_dwordx4 v[6:9], v[2:3], off offset:2048 nt
	s_nop 0
	global_load_dwordx4 v[2:5], v[2:3], off offset:3072 nt
	v_cmp_lt_i32_e32 vcc, v170, v169
	v_mov_b32_e32 v119, v38
	v_mov_b32_e32 v121, v38
	v_mov_b32_e32 v123, v38
	v_mov_b32_e32 v125, v38
	s_waitcnt vmcnt(7)
	v_mov_b32_e32 v128, v31
	s_waitcnt vmcnt(6)
	v_mov_b32_e32 v129, v27
	v_mov_b32_e32 v36, v30
	v_mov_b32_e32 v37, v26
	v_pk_mul_f32 v[128:129], v[128:129], v[128:129]
	s_nop 0
	v_pk_fma_f32 v[36:37], v[36:37], v[36:37], v[128:129]
	v_mov_b32_e32 v128, v32
	v_mov_b32_e32 v129, v28
	v_pk_fma_f32 v[36:37], v[128:129], v[128:129], v[36:37]
	v_mov_b32_e32 v128, v33
	v_mov_b32_e32 v129, v29
	v_pk_fma_f32 v[140:141], v[128:129], v[128:129], v[36:37]
	s_waitcnt vmcnt(5)
	v_mov_b32_e32 v128, v23
	s_waitcnt vmcnt(4)
	v_mov_b32_e32 v129, v19
	v_mov_b32_e32 v36, v22
	v_mov_b32_e32 v37, v18
	v_pk_mul_f32 v[128:129], v[128:129], v[128:129]
	v_mov_b32_e32 v183, v140
	v_pk_fma_f32 v[36:37], v[36:37], v[36:37], v[128:129]
	v_mov_b32_e32 v128, v24
	v_mov_b32_e32 v129, v20
	v_pk_fma_f32 v[36:37], v[128:129], v[128:129], v[36:37]
	v_mov_b32_e32 v128, v25
	v_mov_b32_e32 v129, v21
	v_pk_fma_f32 v[136:137], v[128:129], v[128:129], v[36:37]
	s_waitcnt vmcnt(3)
	v_mov_b32_e32 v128, v15
	s_waitcnt vmcnt(2)
	v_mov_b32_e32 v129, v11
	v_mov_b32_e32 v36, v14
	v_mov_b32_e32 v37, v10
	v_pk_mul_f32 v[128:129], v[128:129], v[128:129]
	s_nop 0
	v_pk_fma_f32 v[36:37], v[36:37], v[36:37], v[128:129]
	v_mov_b32_e32 v128, v16
	v_mov_b32_e32 v129, v12
	v_pk_fma_f32 v[36:37], v[128:129], v[128:129], v[36:37]
	v_mov_b32_e32 v128, v17
	v_mov_b32_e32 v129, v13
	v_pk_fma_f32 v[142:143], v[128:129], v[128:129], v[36:37]
	s_waitcnt vmcnt(1)
	v_mov_b32_e32 v128, v7
	s_waitcnt vmcnt(0)
	v_mov_b32_e32 v129, v3
	v_mov_b32_e32 v36, v6
	v_mov_b32_e32 v37, v2
	v_pk_mul_f32 v[128:129], v[128:129], v[128:129]
	v_mov_b32_e32 v182, v142
	v_pk_fma_f32 v[36:37], v[36:37], v[36:37], v[128:129]
	v_mov_b32_e32 v128, v8
	v_mov_b32_e32 v129, v4
	v_pk_fma_f32 v[36:37], v[128:129], v[128:129], v[36:37]
	v_mov_b32_e32 v128, v9
	v_mov_b32_e32 v129, v5
	v_pk_fma_f32 v[138:139], v[128:129], v[128:129], v[36:37]
	v_cndmask_b32_e32 v36, v168, v170, vcc
	v_cmp_lt_i32_e32 vcc, v171, v169
	v_lshlrev_b32_e32 v39, 2, v36
	v_lshl_add_u64 v[128:129], v[34:35], 1, s[64:65]
	v_cndmask_b32_e32 v36, v168, v171, vcc
	v_cmp_lt_i32_e32 vcc, v172, v169
	v_lshlrev_b32_e32 v144, 2, v36
	v_mov_b32_e32 v140, v143
	v_cndmask_b32_e32 v36, v168, v172, vcc
	v_cmp_lt_i32_e32 vcc, v173, v169
	v_lshlrev_b32_e32 v146, 2, v36
	v_pk_add_f32 v[140:141], v[182:183], v[140:141]
	v_cndmask_b32_e32 v36, v168, v173, vcc
	v_cmp_lt_i32_e32 vcc, v174, v169
	v_lshlrev_b32_e32 v148, 2, v36
	v_mov_b32_e32 v142, v138
	v_cndmask_b32_e32 v36, v168, v174, vcc
	v_cmp_lt_i32_e32 vcc, v175, v169
	v_lshlrev_b32_e32 v181, 2, v36
	v_mov_b32_e32 v143, v136
	v_cndmask_b32_e32 v36, v168, v175, vcc
	v_lshlrev_b32_e32 v184, 2, v36
	global_load_dwordx4 v[34:37], v[54:55], off nt
	v_pk_add_f32 v[140:141], v[140:141], v[142:143]
	v_mov_b32_e32 v136, v139
	v_pk_add_f32 v[136:137], v[140:141], v[136:137]
	ds_bpermute_b32 v139, v39, v137
	ds_bpermute_b32 v138, v39, v136
	v_lshl_add_u64 v[134:135], v[128:129], 0, v[118:119]
	v_lshl_add_u64 v[132:133], v[128:129], 0, v[120:121]
	v_lshl_add_u64 v[130:131], v[128:129], 0, v[122:123]
	v_lshl_add_u64 v[128:129], v[128:129], 0, v[124:125]
	s_waitcnt lgkmcnt(0)
; __device__ __forceinline__ void rmsnorm_2rows_bf16(const float* x, const float* g, u16* out, int row, int lane) {
;     ...
;   for (int off = 32; off >= 1; off >>= 1) { ss[0] += __shfl_xor(ss[0], off); ss[1] += __shfl_xor(ss[1], off); }
; #pragma unroll
;   for (int t = 0; t < 2; ++t) {
;     const float rs = rsqrtf(ss[t] * (1.f / DM) + 1e-6f);
; #pragma unroll
;     for (int i = 0; i < 4; ++i) {
;       const float4 gg = ((const float4*)g)[lane + 64 * i];
;       const uint2 pk = make_uint2(pack2(v[t][i].x * rs * gg.x, v[t][i].y * rs * gg.y), pack2(v[t][i].z * rs * gg.z, v[t][i].w * rs * gg.w));
;       *(uint2*)(out + (size_t)(row + t) * DM + (lane + 64 * i) * 4) = pk;
;     }
;   }
	v_pk_add_f32 v[136:137], v[136:137], v[138:139]
	ds_bpermute_b32 v139, v144, v137
	ds_bpermute_b32 v138, v144, v136
	s_waitcnt lgkmcnt(0)
	v_pk_add_f32 v[136:137], v[136:137], v[138:139]
	ds_bpermute_b32 v139, v146, v137
	ds_bpermute_b32 v138, v146, v136
	s_waitcnt lgkmcnt(0)
	v_pk_add_f32 v[136:137], v[136:137], v[138:139]
	ds_bpermute_b32 v139, v148, v137
	ds_bpermute_b32 v138, v148, v136
	s_waitcnt lgkmcnt(0)
	v_pk_add_f32 v[136:137], v[136:137], v[138:139]
	ds_bpermute_b32 v139, v181, v137
	ds_bpermute_b32 v138, v181, v136
	s_waitcnt lgkmcnt(0)
	v_pk_add_f32 v[136:137], v[136:137], v[138:139]
	ds_bpermute_b32 v139, v184, v137
	ds_bpermute_b32 v138, v184, v136
	s_waitcnt lgkmcnt(0)
	v_pk_add_f32 v[136:137], v[136:137], v[138:139]
	s_nop 0
	v_pk_fma_f32 v[136:137], v[136:137], s[4:5], v[126:127] op_sel_hi:[1,0,0]
	s_mov_b32 s4, 0x800000
	v_mul_f32_e32 v39, 0x4b800000, v137
	v_cmp_gt_f32_e32 vcc, s4, v136
	v_cmp_gt_f32_e64 s[4:5], s4, v137
	s_nop 1
	v_cndmask_b32_e64 v39, v137, v39, s[4:5]
	v_rsq_f32_e32 v39, v39
	s_nop 0
	v_mul_f32_e32 v119, 0x45800000, v39
	v_cndmask_b32_e64 v138, v39, v119, s[4:5]
	v_pk_mul_f32 v[30:31], v[30:31], v[138:139] op_sel_hi:[1,0]
	v_pk_mul_f32 v[32:33], v[32:33], v[138:139] op_sel_hi:[1,0]
	v_pk_mul_f32 v[26:27], v[26:27], v[138:139] op_sel_hi:[1,0]
	v_pk_mul_f32 v[28:29], v[28:29], v[138:139] op_sel_hi:[1,0]
	v_pk_mul_f32 v[22:23], v[22:23], v[138:139] op_sel_hi:[1,0]
	v_pk_mul_f32 v[24:25], v[24:25], v[138:139] op_sel_hi:[1,0]
	v_pk_mul_f32 v[18:19], v[18:19], v[138:139] op_sel_hi:[1,0]
	v_pk_mul_f32 v[20:21], v[20:21], v[138:139] op_sel_hi:[1,0]
	s_waitcnt vmcnt(0)
	v_pk_mul_f32 v[30:31], v[34:35], v[30:31]
	v_pk_mul_f32 v[32:33], v[36:37], v[32:33]
	v_cvt_pk_bf16_f32 v30, v30, v31
	v_cvt_pk_bf16_f32 v31, v32, v33
	global_store_dwordx2 v[134:135], v[30:31], off
	global_load_dwordx4 v[30:33], v[54:55], off offset:1024 nt
	s_waitcnt vmcnt(0)
	v_pk_mul_f32 v[26:27], v[30:31], v[26:27]
	v_pk_mul_f32 v[28:29], v[32:33], v[28:29]
	v_cvt_pk_bf16_f32 v26, v26, v27
	v_cvt_pk_bf16_f32 v27, v28, v29
	global_store_dwordx2 v[132:133], v[26:27], off
	global_load_dwordx4 v[26:29], v[54:55], off offset:2048 nt
	s_waitcnt vmcnt(0)
	v_pk_mul_f32 v[22:23], v[22:23], v[26:27]
	v_pk_mul_f32 v[24:25], v[24:25], v[28:29]
	v_cvt_pk_bf16_f32 v22, v22, v23
	v_cvt_pk_bf16_f32 v23, v24, v25
	global_store_dwordx2 v[130:131], v[22:23], off
	global_load_dwordx4 v[22:25], v[54:55], off offset:3072 nt
	s_waitcnt vmcnt(0)
	v_pk_mul_f32 v[18:19], v[18:19], v[22:23]
	v_pk_mul_f32 v[20:21], v[20:21], v[24:25]
	v_cvt_pk_bf16_f32 v18, v18, v19
	v_cvt_pk_bf16_f32 v19, v20, v21
	global_store_dwordx2 v[128:129], v[18:19], off
	v_mul_f32_e32 v18, 0x4b800000, v136
	v_cndmask_b32_e32 v18, v136, v18, vcc
	v_rsq_f32_e32 v18, v18
	s_nop 0
	v_mul_f32_e32 v19, 0x45800000, v18
	v_cndmask_b32_e32 v22, v18, v19, vcc
	global_load_dwordx4 v[18:21], v[54:55], off nt
	v_pk_mul_f32 v[14:15], v[14:15], v[22:23] op_sel_hi:[1,0]
	v_pk_mul_f32 v[16:17], v[16:17], v[22:23] op_sel_hi:[1,0]
	v_pk_mul_f32 v[10:11], v[10:11], v[22:23] op_sel_hi:[1,0]
	v_pk_mul_f32 v[12:13], v[12:13], v[22:23] op_sel_hi:[1,0]
	v_pk_mul_f32 v[6:7], v[6:7], v[22:23] op_sel_hi:[1,0]
	v_pk_mul_f32 v[8:9], v[8:9], v[22:23] op_sel_hi:[1,0]
	v_pk_mul_f32 v[2:3], v[2:3], v[22:23] op_sel_hi:[1,0]
	v_pk_mul_f32 v[4:5], v[4:5], v[22:23] op_sel_hi:[1,0]
	s_waitcnt vmcnt(0)
	v_pk_mul_f32 v[14:15], v[14:15], v[18:19]
	v_pk_mul_f32 v[16:17], v[16:17], v[20:21]
	v_cvt_pk_bf16_f32 v14, v14, v15
	v_cvt_pk_bf16_f32 v15, v16, v17
	global_store_dwordx2 v[134:135], v[14:15], off offset:2048
	global_load_dwordx4 v[14:17], v[54:55], off offset:1024 nt
	s_waitcnt vmcnt(0)
	v_pk_mul_f32 v[10:11], v[10:11], v[14:15]
	v_pk_mul_f32 v[12:13], v[12:13], v[16:17]
	v_cvt_pk_bf16_f32 v10, v10, v11
	v_cvt_pk_bf16_f32 v11, v12, v13
	global_store_dwordx2 v[132:133], v[10:11], off offset:2048
	global_load_dwordx4 v[10:13], v[54:55], off offset:2048 nt
	s_waitcnt vmcnt(0)
	v_pk_mul_f32 v[6:7], v[6:7], v[10:11]
	v_pk_mul_f32 v[8:9], v[8:9], v[12:13]
	v_cvt_pk_bf16_f32 v6, v6, v7
	v_cvt_pk_bf16_f32 v7, v8, v9
	global_store_dwordx2 v[130:131], v[6:7], off offset:2048
	global_load_dwordx4 v[6:9], v[54:55], off offset:3072 nt
	s_waitcnt vmcnt(0)
	v_pk_mul_f32 v[2:3], v[2:3], v[6:7]
	v_pk_mul_f32 v[4:5], v[4:5], v[8:9]
	v_cvt_pk_bf16_f32 v2, v2, v3
	v_cvt_pk_bf16_f32 v3, v4, v5
	global_store_dwordx2 v[128:129], v[2:3], off offset:2048

; __device__ __forceinline__ void phase_prep(const Params& p, u16* sm) {
;     ...
;     } else if (it < n_tr + n_rope + n_bias) {
;       const int bi = it - n_tr - n_rope, which = bi >> 5, ch = bi & 31;
;       const float* pe = which ? p.pe_v : p.pe_k;
;       const float* w1 = which ? p.cv_w1 : p.ck_w1;
;       const int n = tid & 127, hf = tid >> 7;
;       const int kk0 = ch * 64 + hf * 32;
;       float s0 = 0.f;
; #pragma unroll 8
;       for (int kk = 0; kk < 32; ++kk) s0 += pe[kk0 + kk] * w1[(size_t)(kk0 + kk) * 128 + n];
;       float* red = (float*)sm;
;       if (hf) red[n] = s0;
;       __syncthreads();
;       if (!hf) p.bpart[(which * 32 + ch) * 128 + n] = s0 + red[n];
;       __syncthreads();
.LBB0_18:
	v_lshl_add_u64 v[12:13], v[2:3], 0, s[8:9]
	global_load_dwordx4 v[8:11], v[12:13], off offset:16 nt
	s_nop 0
	global_load_dwordx4 v[12:15], v[12:13], off nt
	s_nop 0
	global_load_dword v16, v[4:5], off offset:-2048
	s_add_u32 s8, s8, 32
	s_addc_u32 s9, s9, 0
	s_mov_b64 s[34:35], 0x1000
	s_cmpk_eq_i32 s8, 0x80
	s_waitcnt vmcnt(0)
	v_fmac_f32_e32 v7, v12, v16
	global_load_dword v12, v[4:5], off offset:-1536
	s_waitcnt vmcnt(0)
	v_fmac_f32_e32 v7, v13, v12
	global_load_dword v12, v[4:5], off offset:-1024
	s_waitcnt vmcnt(0)
	v_fmac_f32_e32 v7, v14, v12
	global_load_dword v12, v[4:5], off offset:-512
	s_waitcnt vmcnt(0)
	v_fmac_f32_e32 v7, v15, v12
	global_load_dword v12, v[4:5], off
	s_waitcnt vmcnt(0)
	v_fmac_f32_e32 v7, v8, v12
	global_load_dword v8, v[4:5], off offset:512
	s_waitcnt vmcnt(0)
	v_fmac_f32_e32 v7, v9, v8
	global_load_dword v8, v[4:5], off offset:1024
	s_waitcnt vmcnt(0)
	v_fmac_f32_e32 v7, v10, v8
	global_load_dword v8, v[4:5], off offset:1536
	v_lshl_add_u64 v[4:5], v[4:5], 0, s[34:35]
	s_waitcnt vmcnt(0)
	v_fmac_f32_e32 v7, v11, v8
	s_cbranch_scc0 .LBB0_18
	s_mov_b64 s[8:9], exec
	v_readlane_b32 s34, v253, 42
	v_readlane_b32 s35, v253, 43
	s_and_b64 s[34:35], s[8:9], s[34:35]
	s_mov_b64 exec, s[34:35]
	ds_write_b32 v145, v7
	s_or_b64 exec, exec, s[8:9]
	s_waitcnt lgkmcnt(0)
	s_barrier
	s_and_saveexec_b64 s[8:9], s[96:97]
	v_readlane_b32 s56, v253, 32
	v_readlane_b32 s58, v253, 34
	v_readlane_b32 s59, v253, 35
	v_readlane_b32 s57, v253, 33
	v_readlane_b32 s60, v253, 36
	v_readlane_b32 s61, v253, 37
	v_readlane_b32 s62, v253, 38
	v_readlane_b32 s63, v253, 39
	s_cbranch_execz .LBB0_23
	ds_read_b32 v4, v145
	v_readlane_b32 s34, v253, 28
	v_lshl_or_b32 v2, v6, 7, v47
	v_mov_b32_e32 v3, v38
	v_readlane_b32 s35, v253, 29
	s_waitcnt lgkmcnt(0)
	v_add_f32_e32 v4, v7, v4
	v_lshl_add_u64 v[2:3], v[2:3], 2, s[34:35]
	global_store_dword v[2:3], v4, off

; __device__ __forceinline__ void transpose_tile2(const float* tsrc, u16* tdst, int tK, int tN, int tNpad, int tile, u16* sm, const bool rp0 = false, const bool rp1 = false, const bool upperm = false, const float* gk = nullptr) {
;   const int nNt = tNpad >> 6;
;   const int tid = threadIdx.x & 255;
;   const int c4 = tid & 15, r = tid >> 4;
;   float4 v[2][4];
;   int k0s[2], n0s[2];
; #pragma unroll
;   for (int t = 0; t < 2; ++t) {
;     const int kt = (tile + t) / nNt, nt = (tile + t) - kt * nNt;
;     k0s[t] = kt * 64; n0s[t] = nt * 64;
; #pragma unroll
;     for (int i = 0; i < 4; ++i) {
;       const int nsrc0 = upperm ? (((n0s[t] >> 7) & 1) * DFF + 128 * (n0s[t] >> 8) + (n0s[t] & 127)) : n0s[t];
;       const int k = r + 16 * i, n = nsrc0 + c4 * 4;
;       v[t][i] = make_float4(0.f, 0.f, 0.f, 0.f);
;       if (n < tN) v[t][i] = *(const float4*)(tsrc + (size_t)(k0s[t] + k) * tN + n);
;       if (gk) { const float gs = gk[k0s[t] + k]; v[t][i].x *= gs; v[t][i].y *= gs; v[t][i].z *= gs; v[t][i].w *= gs; }
;     }
;   }
; #pragma unroll
;   for (int t = 0; t < 2; ++t)
; #pragma unroll
;     for (int i = 0; i < 4; ++i) {
;       const int k = r + 16 * i;
;       u16* d = sm + t * 64 * LDSP;
;       const uint32_t p01 = pack2(v[t][i].x, v[t][i].y), p23 = pack2(v[t][i].z, v[t][i].w);
;       d[(c4 * 4 + 0) * LDSP + k] = (u16)(p01 & 0xffff);
;       d[(c4 * 4 + 1) * LDSP + k] = (u16)(p01 >> 16);
;       d[(c4 * 4 + 2) * LDSP + k] = (u16)(p23 & 0xffff);
;       d[(c4 * 4 + 3) * LDSP + k] = (u16)(p23 >> 16);
;     }
;   __syncthreads();
;   const int c8 = tid & 7, rn = tid >> 3;
; #pragma unroll
;   for (int t = 0; t < 2; ++t) {
;     const bool ropeperm = t ? rp1 : rp0;
; #pragma unroll
;     for (int i = 0; i < 2; ++i) {
;       const int n = rn + 32 * i;
;       const int nsrc = ropeperm ? (16 * (n >> 5) + (n & 15) + 32 * ((n >> 4) & 1)) : n;
;       const uint4 w = *(const uint4*)(sm + t * 64 * LDSP + nsrc * LDSP + c8 * 8);
;       *(uint4*)(tdst + (size_t)(n0s[t] + n) * tK + k0s[t] + c8 * 8) = w;
;     }
;   }
;   __syncthreads();
.LBB0_36:
	s_andn2_saveexec_b64 s[8:9], s[38:39]
	s_cbranch_execz .LBB0_11
	s_movk_i32 s4, 0x17f
	v_lshlrev_b32_e32 v119, 1, v1
	v_cmp_lt_i32_e32 vcc, s4, v1
	s_and_saveexec_b64 s[4:5], vcc
	s_xor_b64 s[94:95], exec, s[4:5]
	s_cbranch_execz .LBB0_226
	s_movk_i32 s4, 0x1ff
	v_cmp_lt_u32_e32 vcc, s4, v1
	s_and_saveexec_b64 s[4:5], vcc
	s_xor_b64 s[38:39], exec, s[4:5]
	s_cbranch_execz .LBB0_207
	s_movk_i32 s4, 0x2ff
	v_cmp_lt_u32_e32 vcc, s4, v1
	s_and_saveexec_b64 s[4:5], vcc
	s_xor_b64 s[50:51], exec, s[4:5]
	s_cbranch_execz .LBB0_188
	s_movk_i32 s4, 0x37f
	v_cmp_lt_u32_e32 vcc, s4, v1
	s_and_saveexec_b64 s[4:5], vcc
	s_xor_b64 s[40:41], exec, s[4:5]
	s_cbranch_execz .LBB0_169
	s_movk_i32 s4, 0x63f
	v_cmp_lt_u32_e32 vcc, s4, v1
	s_and_saveexec_b64 s[4:5], vcc
	s_xor_b64 s[4:5], exec, s[4:5]
	s_cbranch_execz .LBB0_131
	s_movk_i32 s6, 0x8ff
	v_cmp_lt_u32_e32 vcc, s6, v1
	s_and_saveexec_b64 s[6:7], vcc
	s_xor_b64 s[6:7], exec, s[6:7]
	s_cbranch_execz .LBB0_112
	s_movk_i32 s34, 0xa5f
	v_cmp_lt_u32_e32 vcc, s34, v1
	s_and_saveexec_b64 s[34:35], vcc
	s_xor_b64 s[52:53], exec, s[34:35]
	s_cbranch_execz .LBB0_93
	s_movk_i32 s34, 0xbbf
	v_cmp_lt_u32_e32 vcc, s34, v1
	s_and_saveexec_b64 s[34:35], vcc
	s_xor_b64 s[48:49], exec, s[34:35]
	s_cbranch_execz .LBB0_74
	s_movk_i32 s34, 0xbdf
	v_cmp_lt_u32_e32 vcc, s34, v1
	s_and_saveexec_b64 s[34:35], vcc
	s_xor_b64 s[56:57], exec, s[34:35]
	v_writelane_b32 v253, s48, 52
	s_nop 1
	v_writelane_b32 v253, s49, 53
	s_cbranch_execz .LBB0_63
	s_movk_i32 s34, 0xbff
	v_cmp_lt_u32_e32 vcc, s34, v1
	s_and_saveexec_b64 s[34:35], vcc
	s_xor_b64 s[54:55], exec, s[34:35]
	s_cbranch_execz .LBB0_52
	v_cmp_ne_u32_e32 vcc, s28, v1
	s_and_saveexec_b64 s[34:35], vcc
	s_xor_b64 vcc, exec, s[34:35]
	s_cbranch_execz .LBB0_49
	global_load_dwordx4 v[2:5], v[56:57], off nt
	global_load_dwordx4 v[6:9], v[58:59], off nt
	global_load_dwordx4 v[10:13], v[60:61], off nt
	global_load_dwordx4 v[14:17], v[62:63], off nt
	global_load_dwordx4 v[18:21], v[64:65], off nt
	global_load_dwordx4 v[22:25], v[66:67], off nt
	global_load_dwordx4 v[26:29], v[68:69], off nt
	global_load_dwordx4 v[30:33], v[70:71], off nt
	s_waitcnt vmcnt(7)
	v_cvt_pk_bf16_f32 v2, v2, v3
	v_cvt_pk_bf16_f32 v3, v4, v5
	s_waitcnt vmcnt(6)
	v_cvt_pk_bf16_f32 v4, v6, v7
	v_cvt_pk_bf16_f32 v5, v8, v9
	s_waitcnt vmcnt(5)
	v_cvt_pk_bf16_f32 v6, v10, v11
	v_cvt_pk_bf16_f32 v7, v12, v13
	s_waitcnt vmcnt(4)
	v_cvt_pk_bf16_f32 v8, v14, v15
	v_cvt_pk_bf16_f32 v9, v16, v17
	s_waitcnt vmcnt(3)
	v_cvt_pk_bf16_f32 v10, v18, v19
	v_cvt_pk_bf16_f32 v11, v20, v21
	s_waitcnt vmcnt(2)
	v_cvt_pk_bf16_f32 v12, v22, v23
	v_cvt_pk_bf16_f32 v13, v24, v25
	s_waitcnt vmcnt(1)
	v_cvt_pk_bf16_f32 v14, v26, v27
	v_cvt_pk_bf16_f32 v15, v28, v29
	s_waitcnt vmcnt(0)
	v_cvt_pk_bf16_f32 v16, v30, v31
	v_cvt_pk_bf16_f32 v17, v32, v33
	ds_write_b16 v152, v2
	ds_write_b16_d16_hi v152, v2 offset:144
	ds_write_b16 v152, v3 offset:288
	ds_write_b16_d16_hi v152, v3 offset:432
	ds_write_b16 v152, v4 offset:32
	ds_write_b16_d16_hi v153, v4 offset:144
	ds_write_b16 v153, v5 offset:288
	ds_write_b16_d16_hi v153, v5 offset:432
	ds_write_b16 v152, v6 offset:64
	ds_write_b16_d16_hi v154, v6 offset:144
	ds_write_b16 v154, v7 offset:288
	ds_write_b16_d16_hi v154, v7 offset:432
	ds_write_b16 v152, v8 offset:96
	ds_write_b16_d16_hi v155, v8 offset:144
	ds_write_b16 v155, v9 offset:288
	ds_write_b16_d16_hi v155, v9 offset:432
	ds_write_b16 v152, v10 offset:9216
	ds_write_b16_d16_hi v152, v10 offset:9360
	ds_write_b16 v152, v11 offset:9504
	ds_write_b16_d16_hi v152, v11 offset:9648
	ds_write_b16 v152, v12 offset:9248
	ds_write_b16_d16_hi v153, v12 offset:9360
	ds_write_b16 v153, v13 offset:9504
	ds_write_b16_d16_hi v153, v13 offset:9648
	ds_write_b16 v152, v14 offset:9280
	ds_write_b16_d16_hi v154, v14 offset:9360
	ds_write_b16 v154, v15 offset:9504
	ds_write_b16_d16_hi v154, v15 offset:9648
	ds_write_b16 v152, v16 offset:9312
	ds_write_b16_d16_hi v155, v16 offset:9360
	ds_write_b16 v155, v17 offset:9504
	ds_write_b16_d16_hi v155, v17 offset:9648
	s_waitcnt lgkmcnt(0)
	s_barrier
	ds_read_b128 v[2:5], v158
	ds_read_b128 v[6:9], v158 offset:4608
	ds_read_b128 v[10:13], v158 offset:9216
	ds_read_b128 v[14:17], v158 offset:13824
	s_waitcnt lgkmcnt(3)
	global_store_dwordx4 v[72:73], v[2:5], off
	s_waitcnt lgkmcnt(2)
	global_store_dwordx4 v[74:75], v[6:9], off
	s_waitcnt lgkmcnt(1)
	global_store_dwordx4 v[72:73], v[10:13], off offset:128
	s_waitcnt lgkmcnt(0)
	global_store_dwordx4 v[74:75], v[14:17], off offset:128
	s_barrier
; __device__ __forceinline__ void transpose_tile2(const float* tsrc, u16* tdst, int tK, int tN, int tNpad, int tile, u16* sm, const bool rp0 = false, const bool rp1 = false, const bool upperm = false, const float* gk = nullptr) {
;   const int nNt = tNpad >> 6;
;   const int tid = threadIdx.x & 255;
;   const int c4 = tid & 15, r = tid >> 4;
;   float4 v[2][4];
;   int k0s[2], n0s[2];
; #pragma unroll
;   for (int t = 0; t < 2; ++t) {
;     const int kt = (tile + t) / nNt, nt = (tile + t) - kt * nNt;
;     k0s[t] = kt * 64; n0s[t] = nt * 64;
; #pragma unroll
;     for (int i = 0; i < 4; ++i) {
;       const int nsrc0 = upperm ? (((n0s[t] >> 7) & 1) * DFF + 128 * (n0s[t] >> 8) + (n0s[t] & 127)) : n0s[t];
;       const int k = r + 16 * i, n = nsrc0 + c4 * 4;
;       v[t][i] = make_float4(0.f, 0.f, 0.f, 0.f);
;       if (n < tN) v[t][i] = *(const float4*)(tsrc + (size_t)(k0s[t] + k) * tN + n);
;       if (gk) { const float gs = gk[k0s[t] + k]; v[t][i].x *= gs; v[t][i].y *= gs; v[t][i].z *= gs; v[t][i].w *= gs; }
;     }
;   }
; #pragma unroll
;   for (int t = 0; t < 2; ++t)
; #pragma unroll
;     for (int i = 0; i < 4; ++i) {
;       const int k = r + 16 * i;
;       u16* d = sm + t * 64 * LDSP;
;       const uint32_t p01 = pack2(v[t][i].x, v[t][i].y), p23 = pack2(v[t][i].z, v[t][i].w);
;       d[(c4 * 4 + 0) * LDSP + k] = (u16)(p01 & 0xffff);
;       d[(c4 * 4 + 1) * LDSP + k] = (u16)(p01 >> 16);
;       d[(c4 * 4 + 2) * LDSP + k] = (u16)(p23 & 0xffff);
;       d[(c4 * 4 + 3) * LDSP + k] = (u16)(p23 >> 16);
;     }
;   __syncthreads();
;   const int c8 = tid & 7, rn = tid >> 3;
; #pragma unroll
;   for (int t = 0; t < 2; ++t) {
;     const bool ropeperm = t ? rp1 : rp0;
; #pragma unroll
;     for (int i = 0; i < 2; ++i) {
;       const int n = rn + 32 * i;
;       const int nsrc = ropeperm ? (16 * (n >> 5) + (n & 15) + 32 * ((n >> 4) & 1)) : n;
;       const uint4 w = *(const uint4*)(sm + t * 64 * LDSP + nsrc * LDSP + c8 * 8);
;       *(uint4*)(tdst + (size_t)(n0s[t] + n) * tK + k0s[t] + c8 * 8) = w;
;     }
;   }
;   __syncthreads();
.LBB0_49:
	s_andn2_saveexec_b64 vcc, vcc
	s_cbranch_execz .LBB0_51
	global_load_dwordx4 v[2:5], v[76:77], off nt
	global_load_dwordx4 v[6:9], v[78:79], off nt
	global_load_dwordx4 v[10:13], v[80:81], off nt
	global_load_dwordx4 v[14:17], v[82:83], off nt
	global_load_dwordx4 v[18:21], v[84:85], off nt
	global_load_dwordx4 v[22:25], v[86:87], off nt
	global_load_dwordx4 v[26:29], v[88:89], off nt
	global_load_dwordx4 v[30:33], v[90:91], off nt
	s_waitcnt vmcnt(7)
	v_cvt_pk_bf16_f32 v2, v2, v3
	v_cvt_pk_bf16_f32 v3, v4, v5
	s_waitcnt vmcnt(6)
	v_cvt_pk_bf16_f32 v4, v6, v7
	v_cvt_pk_bf16_f32 v5, v8, v9
	s_waitcnt vmcnt(5)
	v_cvt_pk_bf16_f32 v6, v10, v11
	v_cvt_pk_bf16_f32 v7, v12, v13
	s_waitcnt vmcnt(4)
	v_cvt_pk_bf16_f32 v8, v14, v15
	v_cvt_pk_bf16_f32 v9, v16, v17
	s_waitcnt vmcnt(3)
	v_cvt_pk_bf16_f32 v10, v18, v19
	v_cvt_pk_bf16_f32 v11, v20, v21
	s_waitcnt vmcnt(2)
	v_cvt_pk_bf16_f32 v12, v22, v23
	v_cvt_pk_bf16_f32 v13, v24, v25
	s_waitcnt vmcnt(1)
	v_cvt_pk_bf16_f32 v14, v26, v27
	v_cvt_pk_bf16_f32 v15, v28, v29
	s_waitcnt vmcnt(0)
	v_cvt_pk_bf16_f32 v16, v30, v31
	v_cvt_pk_bf16_f32 v17, v32, v33
	ds_write_b16 v152, v2
	ds_write_b16_d16_hi v152, v2 offset:144
	ds_write_b16 v152, v3 offset:288
	ds_write_b16_d16_hi v152, v3 offset:432
	ds_write_b16 v152, v4 offset:32
	ds_write_b16_d16_hi v153, v4 offset:144
	ds_write_b16 v153, v5 offset:288
	ds_write_b16_d16_hi v153, v5 offset:432
	ds_write_b16 v152, v6 offset:64
	ds_write_b16_d16_hi v154, v6 offset:144
	ds_write_b16 v154, v7 offset:288
	ds_write_b16_d16_hi v154, v7 offset:432
	ds_write_b16 v152, v8 offset:96
	ds_write_b16_d16_hi v155, v8 offset:144
	ds_write_b16 v155, v9 offset:288
	ds_write_b16_d16_hi v155, v9 offset:432
	ds_write_b16 v152, v10 offset:9216
	ds_write_b16_d16_hi v152, v10 offset:9360
	ds_write_b16 v152, v11 offset:9504
	ds_write_b16_d16_hi v152, v11 offset:9648
	ds_write_b16 v152, v12 offset:9248
	ds_write_b16_d16_hi v153, v12 offset:9360
	ds_write_b16 v153, v13 offset:9504
	ds_write_b16_d16_hi v153, v13 offset:9648
	ds_write_b16 v152, v14 offset:9280
	ds_write_b16_d16_hi v154, v14 offset:9360
	ds_write_b16 v154, v15 offset:9504
	ds_write_b16_d16_hi v154, v15 offset:9648
	ds_write_b16 v152, v16 offset:9312
	ds_write_b16_d16_hi v155, v16 offset:9360
	ds_write_b16 v155, v17 offset:9504
	ds_write_b16_d16_hi v155, v17 offset:9648
	s_waitcnt lgkmcnt(0)
	s_barrier
	ds_read_b128 v[2:5], v158
	ds_read_b128 v[6:9], v158 offset:4608
	ds_read_b128 v[10:13], v158 offset:9216
	ds_read_b128 v[14:17], v158 offset:13824
	s_waitcnt lgkmcnt(3)
	global_store_dwordx4 v[92:93], v[2:5], off
	s_waitcnt lgkmcnt(2)
	global_store_dwordx4 v[94:95], v[6:9], off
	s_waitcnt lgkmcnt(1)
	global_store_dwordx4 v[92:93], v[10:13], off offset:128
	s_waitcnt lgkmcnt(0)
	global_store_dwordx4 v[94:95], v[14:17], off offset:128
	s_barrier

; __device__ __forceinline__ void transpose_tile2(const float* tsrc, u16* tdst, int tK, int tN, int tNpad, int tile, u16* sm, const bool rp0 = false, const bool rp1 = false, const bool upperm = false, const float* gk = nullptr) {
;     ...
;   for (int t = 0; t < 2; ++t) {
;     const int kt = (tile + t) / nNt, nt = (tile + t) - kt * nNt;
;     k0s[t] = kt * 64; n0s[t] = nt * 64;
; #pragma unroll
;     for (int i = 0; i < 4; ++i) {
;       const int nsrc0 = upperm ? (((n0s[t] >> 7) & 1) * DFF + 128 * (n0s[t] >> 8) + (n0s[t] & 127)) : n0s[t];
;       const int k = r + 16 * i, n = nsrc0 + c4 * 4;
;       v[t][i] = make_float4(0.f, 0.f, 0.f, 0.f);
;       if (n < tN) v[t][i] = *(const float4*)(tsrc + (size_t)(k0s[t] + k) * tN + n);
;       if (gk) { const float gs = gk[k0s[t] + k]; v[t][i].x *= gs; v[t][i].y *= gs; v[t][i].z *= gs; v[t][i].w *= gs; }
;     }
;   }
.LBB0_52:
	s_or_saveexec_b64 s[34:35], s[54:55]
	v_writelane_b32 v253, s34, 54
	s_nop 1
	v_writelane_b32 v253, s35, 55
	s_xor_b64 exec, exec, s[34:35]
	s_cbranch_execz .LBB0_62
	v_lshl_add_u32 v18, v1, 6, v179
	v_or_b32_e32 v2, v18, v40
	v_mov_b32_e32 v3, v38
	v_or_b32_e32 v4, v18, v149
	v_mov_b32_e32 v5, v38
	v_or_b32_e32 v6, v18, v150
	v_mov_b32_e32 v7, v38
	v_or_b32_e32 v8, v18, v151
	v_mov_b32_e32 v9, v38
	v_lshlrev_b64 v[2:3], 9, v[2:3]
	v_lshlrev_b64 v[4:5], 9, v[4:5]
	v_lshlrev_b64 v[6:7], 9, v[6:7]
	v_lshlrev_b64 v[8:9], 9, v[8:9]
	v_lshl_add_u64 v[2:3], v[50:51], 0, v[2:3]
	v_lshl_add_u64 v[4:5], v[50:51], 0, v[4:5]
	v_lshl_add_u64 v[6:7], v[50:51], 0, v[6:7]
	v_lshl_add_u64 v[8:9], v[50:51], 0, v[8:9]
	global_load_dwordx4 v[10:13], v[2:3], off nt
	s_nop 0
	global_load_dwordx4 v[2:5], v[4:5], off nt
	s_nop 0
	global_load_dwordx4 v[14:17], v[6:7], off nt
	s_nop 0
	global_load_dwordx4 v[6:9], v[8:9], off nt
	v_add_u32_e32 v19, 0xffffe841, v119
	v_lshrrev_b32_e32 v20, 31, v19
	v_add_u32_e32 v20, v19, v20
	v_ashrrev_i32_e32 v21, 1, v20
	v_lshlrev_b32_e32 v20, 6, v21
	v_lshlrev_b32_e32 v21, 7, v21
	v_lshlrev_b32_e32 v19, 6, v19
	v_sub_u32_e32 v24, v19, v21
	v_or_b32_e32 v22, v24, v42
	s_movk_i32 s34, 0x80
	v_cmp_gt_i32_e32 vcc, s34, v22
	v_mov_b32_e32 v19, 0
	v_ashrrev_i32_e32 v23, 31, v22
	v_mov_b32_e32 v21, 0
	v_mov_b32_e32 v25, 0
	s_and_saveexec_b64 s[76:77], vcc
	s_mov_b64 s[54:55], s[56:57]
	s_cbranch_execz .LBB0_55
	v_or_b32_e32 v26, v20, v40
	v_ashrrev_i32_e32 v27, 31, v26
	s_mov_b64 s[34:35], s[68:69]
	s_mov_b64 s[48:49], s[70:71]
	v_readlane_b32 s56, v253, 2
	v_lshlrev_b64 v[26:27], 9, v[26:27]
	v_readlane_b32 s60, v253, 6
	v_readlane_b32 s61, v253, 7
	v_readlane_b32 s57, v253, 3
	v_readlane_b32 s58, v253, 4
	v_lshl_add_u64 v[26:27], s[60:61], 0, v[26:27]
	v_lshl_add_u64 v[26:27], v[22:23], 2, v[26:27]
	global_load_dwordx4 v[26:29], v[26:27], off nt
	v_readlane_b32 s59, v253, 5
	v_readlane_b32 s62, v253, 8
	v_readlane_b32 s63, v253, 9
	v_readlane_b32 s64, v253, 10
	v_readlane_b32 s65, v253, 11
	v_readlane_b32 s70, v253, 16
	v_readlane_b32 s71, v253, 17
	v_readlane_b32 s56, v253, 32
	v_readlane_b32 s68, v253, 14
	v_readlane_b32 s69, v253, 15
	v_readlane_b32 s64, v253, 40
	s_mov_b64 s[70:71], s[48:49]
	v_readlane_b32 s48, v253, 52
	v_readlane_b32 s57, v253, 33
	v_readlane_b32 s65, v253, 41
	v_readlane_b32 s49, v253, 53
	s_mov_b64 s[68:69], s[34:35]
	v_readlane_b32 s58, v253, 34
	v_readlane_b32 s59, v253, 35
	s_mov_b64 s[56:57], s[54:55]
	v_readlane_b32 s66, v253, 12
	v_readlane_b32 s67, v253, 13
	v_readlane_b32 s60, v253, 36
	v_readlane_b32 s61, v253, 37
	v_readlane_b32 s62, v253, 38
	v_readlane_b32 s63, v253, 39
	s_waitcnt vmcnt(0)
	v_cvt_pk_bf16_f32 v25, v26, v27
	v_cvt_pk_bf16_f32 v21, v28, v29
.LBB0_55:
	s_or_b64 exec, exec, s[76:77]
	v_mov_b32_e32 v26, 0
	s_and_saveexec_b64 s[76:77], vcc
	s_cbranch_execz .LBB0_57
	v_or_b32_e32 v26, v20, v149
	v_ashrrev_i32_e32 v27, 31, v26
	s_mov_b64 s[34:35], s[68:69]
	s_mov_b64 s[48:49], s[70:71]
	v_readlane_b32 s56, v253, 2
	v_lshlrev_b64 v[26:27], 9, v[26:27]
	v_readlane_b32 s60, v253, 6
	v_readlane_b32 s61, v253, 7
	v_readlane_b32 s57, v253, 3
	v_readlane_b32 s58, v253, 4
	v_lshl_add_u64 v[26:27], s[60:61], 0, v[26:27]
	v_lshl_add_u64 v[26:27], v[22:23], 2, v[26:27]
	global_load_dwordx4 v[26:29], v[26:27], off nt
	v_readlane_b32 s59, v253, 5
	v_readlane_b32 s62, v253, 8
	v_readlane_b32 s63, v253, 9
	v_readlane_b32 s64, v253, 10
	v_readlane_b32 s65, v253, 11
	v_readlane_b32 s70, v253, 16
	v_readlane_b32 s71, v253, 17
	v_readlane_b32 s56, v253, 32
	v_readlane_b32 s68, v253, 14
	v_readlane_b32 s69, v253, 15
	v_readlane_b32 s64, v253, 40
	s_mov_b64 s[70:71], s[48:49]
	v_readlane_b32 s48, v253, 52
	v_readlane_b32 s57, v253, 33
	v_readlane_b32 s65, v253, 41
	v_readlane_b32 s49, v253, 53
	s_mov_b64 s[68:69], s[34:35]
	v_readlane_b32 s58, v253, 34
	v_readlane_b32 s59, v253, 35
	s_mov_b64 s[56:57], s[54:55]
	v_readlane_b32 s66, v253, 12
	v_readlane_b32 s67, v253, 13
	v_readlane_b32 s60, v253, 36
	v_readlane_b32 s61, v253, 37
	v_readlane_b32 s62, v253, 38
	v_readlane_b32 s63, v253, 39
	s_waitcnt vmcnt(0)
	v_cvt_pk_bf16_f32 v26, v26, v27
	v_cvt_pk_bf16_f32 v19, v28, v29
; __device__ __forceinline__ void transpose_tile2(const float* tsrc, u16* tdst, int tK, int tN, int tNpad, int tile, u16* sm, const bool rp0 = false, const bool rp1 = false, const bool upperm = false, const float* gk = nullptr) {
;     ...
;   for (int t = 0; t < 2; ++t) {
;     const int kt = (tile + t) / nNt, nt = (tile + t) - kt * nNt;
;     k0s[t] = kt * 64; n0s[t] = nt * 64;
; #pragma unroll
;     for (int i = 0; i < 4; ++i) {
;       const int nsrc0 = upperm ? (((n0s[t] >> 7) & 1) * DFF + 128 * (n0s[t] >> 8) + (n0s[t] & 127)) : n0s[t];
;       const int k = r + 16 * i, n = nsrc0 + c4 * 4;
;       v[t][i] = make_float4(0.f, 0.f, 0.f, 0.f);
;       if (n < tN) v[t][i] = *(const float4*)(tsrc + (size_t)(k0s[t] + k) * tN + n);
;       if (gk) { const float gs = gk[k0s[t] + k]; v[t][i].x *= gs; v[t][i].y *= gs; v[t][i].z *= gs; v[t][i].w *= gs; }
;     }
;   }
.LBB0_57:
	s_or_b64 exec, exec, s[76:77]
	v_mov_b32_e32 v27, 0
	v_mov_b32_e32 v28, 0
	v_mov_b32_e32 v29, 0
	s_and_saveexec_b64 s[76:77], vcc
	s_cbranch_execz .LBB0_59
	v_or_b32_e32 v28, v20, v150
	v_ashrrev_i32_e32 v29, 31, v28
	s_mov_b64 s[34:35], s[68:69]
	s_mov_b64 s[48:49], s[70:71]
	v_readlane_b32 s56, v253, 2
	v_lshlrev_b64 v[28:29], 9, v[28:29]
	v_readlane_b32 s60, v253, 6
	v_readlane_b32 s61, v253, 7
	v_readlane_b32 s57, v253, 3
	v_readlane_b32 s58, v253, 4
	v_lshl_add_u64 v[28:29], s[60:61], 0, v[28:29]
	v_lshl_add_u64 v[28:29], v[22:23], 2, v[28:29]
	global_load_dwordx4 v[28:31], v[28:29], off nt
	v_readlane_b32 s59, v253, 5
	v_readlane_b32 s62, v253, 8
	v_readlane_b32 s63, v253, 9
	v_readlane_b32 s64, v253, 10
	v_readlane_b32 s65, v253, 11
	v_readlane_b32 s70, v253, 16
	v_readlane_b32 s71, v253, 17
	v_readlane_b32 s56, v253, 32
	v_readlane_b32 s68, v253, 14
	v_readlane_b32 s69, v253, 15
	v_readlane_b32 s64, v253, 40
	s_mov_b64 s[70:71], s[48:49]
	v_readlane_b32 s48, v253, 52
	v_readlane_b32 s57, v253, 33
	v_readlane_b32 s65, v253, 41
	v_readlane_b32 s49, v253, 53
	s_mov_b64 s[68:69], s[34:35]
	v_readlane_b32 s58, v253, 34
	v_readlane_b32 s59, v253, 35
	s_mov_b64 s[56:57], s[54:55]
	v_readlane_b32 s66, v253, 12
	v_readlane_b32 s67, v253, 13
	v_readlane_b32 s60, v253, 36
	v_readlane_b32 s61, v253, 37
	v_readlane_b32 s62, v253, 38
	v_readlane_b32 s63, v253, 39
	s_waitcnt vmcnt(0)
	v_cvt_pk_bf16_f32 v29, v28, v29
	v_cvt_pk_bf16_f32 v28, v30, v31
.LBB0_59:
	s_or_b64 exec, exec, s[76:77]
	v_mov_b32_e32 v30, 0
	s_and_saveexec_b64 s[76:77], vcc
	s_cbranch_execz .LBB0_61
	v_or_b32_e32 v30, v20, v151
	v_ashrrev_i32_e32 v31, 31, v30
	s_mov_b64 s[34:35], s[68:69]
	s_mov_b64 s[48:49], s[70:71]
	v_readlane_b32 s56, v253, 2
	v_lshlrev_b64 v[30:31], 9, v[30:31]
	v_readlane_b32 s60, v253, 6
	v_readlane_b32 s61, v253, 7
	v_readlane_b32 s57, v253, 3
	v_readlane_b32 s58, v253, 4
	v_lshl_add_u64 v[30:31], s[60:61], 0, v[30:31]
	v_lshl_add_u64 v[22:23], v[22:23], 2, v[30:31]
	global_load_dwordx4 v[30:33], v[22:23], off nt
	v_readlane_b32 s59, v253, 5
	v_readlane_b32 s62, v253, 8
	v_readlane_b32 s63, v253, 9
	v_readlane_b32 s64, v253, 10
	v_readlane_b32 s65, v253, 11
	v_readlane_b32 s70, v253, 16
	v_readlane_b32 s71, v253, 17
	v_readlane_b32 s56, v253, 32
	v_readlane_b32 s68, v253, 14
	v_readlane_b32 s69, v253, 15
	v_readlane_b32 s64, v253, 40
	s_mov_b64 s[70:71], s[48:49]
	v_readlane_b32 s48, v253, 52
	v_readlane_b32 s57, v253, 33
	v_readlane_b32 s65, v253, 41
	v_readlane_b32 s49, v253, 53
	s_mov_b64 s[68:69], s[34:35]
	v_readlane_b32 s58, v253, 34
	v_readlane_b32 s59, v253, 35
	s_mov_b64 s[56:57], s[54:55]
	v_readlane_b32 s66, v253, 12
	v_readlane_b32 s67, v253, 13
	v_readlane_b32 s60, v253, 36
	v_readlane_b32 s61, v253, 37
	v_readlane_b32 s62, v253, 38
	v_readlane_b32 s63, v253, 39
	s_waitcnt vmcnt(0)
	v_cvt_pk_bf16_f32 v30, v30, v31
	v_cvt_pk_bf16_f32 v27, v32, v33

; __device__ __forceinline__ void transpose_tile2(const float* tsrc, u16* tdst, int tK, int tN, int tNpad, int tile, u16* sm, const bool rp0 = false, const bool rp1 = false, const bool upperm = false, const float* gk = nullptr) {
;     ...
;   for (int t = 0; t < 2; ++t) {
;     const int kt = (tile + t) / nNt, nt = (tile + t) - kt * nNt;
;     k0s[t] = kt * 64; n0s[t] = nt * 64;
; #pragma unroll
;     for (int i = 0; i < 4; ++i) {
;       const int nsrc0 = upperm ? (((n0s[t] >> 7) & 1) * DFF + 128 * (n0s[t] >> 8) + (n0s[t] & 127)) : n0s[t];
;       const int k = r + 16 * i, n = nsrc0 + c4 * 4;
;       v[t][i] = make_float4(0.f, 0.f, 0.f, 0.f);
;       if (n < tN) v[t][i] = *(const float4*)(tsrc + (size_t)(k0s[t] + k) * tN + n);
;       if (gk) { const float gs = gk[k0s[t] + k]; v[t][i].x *= gs; v[t][i].y *= gs; v[t][i].z *= gs; v[t][i].w *= gs; }
;     }
;   }
.LBB0_63:
	s_andn2_saveexec_b64 s[54:55], s[56:57]
	s_cbranch_execz .LBB0_73
	v_lshl_add_u32 v18, v1, 6, v180
	v_or_b32_e32 v2, v18, v40
	v_mov_b32_e32 v3, v38
	v_or_b32_e32 v4, v18, v149
	v_mov_b32_e32 v5, v38
	v_or_b32_e32 v6, v18, v150
	v_mov_b32_e32 v7, v38
	v_or_b32_e32 v8, v18, v151
	v_mov_b32_e32 v9, v38
	v_lshlrev_b64 v[2:3], 9, v[2:3]
	v_lshlrev_b64 v[4:5], 9, v[4:5]
	v_lshlrev_b64 v[6:7], 9, v[6:7]
	v_lshlrev_b64 v[8:9], 9, v[8:9]
	v_lshl_add_u64 v[2:3], v[52:53], 0, v[2:3]
	v_lshl_add_u64 v[4:5], v[52:53], 0, v[4:5]
	v_lshl_add_u64 v[6:7], v[52:53], 0, v[6:7]
	v_lshl_add_u64 v[8:9], v[52:53], 0, v[8:9]
	global_load_dwordx4 v[10:13], v[2:3], off nt
	s_nop 0
	global_load_dwordx4 v[2:5], v[4:5], off nt
	s_nop 0
	global_load_dwordx4 v[14:17], v[6:7], off nt
	s_nop 0
	global_load_dwordx4 v[6:9], v[8:9], off nt
	v_add_u32_e32 v19, 0xffffe881, v119
	v_lshrrev_b32_e32 v20, 31, v19
	v_add_u32_e32 v20, v19, v20
	v_ashrrev_i32_e32 v21, 1, v20
	v_lshlrev_b32_e32 v20, 6, v21
	v_lshlrev_b32_e32 v21, 7, v21
	v_lshlrev_b32_e32 v19, 6, v19
	v_sub_u32_e32 v24, v19, v21
	v_or_b32_e32 v22, v24, v42
	s_movk_i32 s34, 0x80
	v_cmp_gt_i32_e32 vcc, s34, v22
	v_mov_b32_e32 v19, 0
	v_ashrrev_i32_e32 v23, 31, v22
	v_mov_b32_e32 v21, 0
	v_mov_b32_e32 v25, 0
	s_and_saveexec_b64 s[76:77], vcc
	s_cbranch_execz .LBB0_66
	v_or_b32_e32 v26, v20, v40
	v_ashrrev_i32_e32 v27, 31, v26
	s_mov_b64 s[34:35], s[68:69]
	s_mov_b64 s[48:49], s[70:71]
	v_readlane_b32 s56, v253, 2
	v_lshlrev_b64 v[26:27], 9, v[26:27]
	v_readlane_b32 s57, v253, 3
	v_readlane_b32 s58, v253, 4
	v_readlane_b32 s59, v253, 5
	v_lshl_add_u64 v[26:27], s[56:57], 0, v[26:27]
	v_lshl_add_u64 v[26:27], v[22:23], 2, v[26:27]
	global_load_dwordx4 v[26:29], v[26:27], off nt
	v_readlane_b32 s60, v253, 6
	v_readlane_b32 s61, v253, 7
	v_readlane_b32 s62, v253, 8
	v_readlane_b32 s63, v253, 9
	v_readlane_b32 s64, v253, 10
	v_readlane_b32 s65, v253, 11
	v_readlane_b32 s70, v253, 16
	v_readlane_b32 s71, v253, 17
	v_readlane_b32 s68, v253, 14
	v_readlane_b32 s69, v253, 15
	v_readlane_b32 s64, v253, 40
	s_mov_b64 s[70:71], s[48:49]
	v_readlane_b32 s48, v253, 52
	v_readlane_b32 s56, v253, 32
	v_readlane_b32 s65, v253, 41
	v_readlane_b32 s49, v253, 53
	s_mov_b64 s[68:69], s[34:35]
	v_readlane_b32 s58, v253, 34
	v_readlane_b32 s59, v253, 35
	v_readlane_b32 s66, v253, 12
	v_readlane_b32 s67, v253, 13
	v_readlane_b32 s57, v253, 33
	v_readlane_b32 s60, v253, 36
	v_readlane_b32 s61, v253, 37
	v_readlane_b32 s62, v253, 38
	v_readlane_b32 s63, v253, 39
	s_waitcnt vmcnt(0)
	v_cvt_pk_bf16_f32 v25, v26, v27
	v_cvt_pk_bf16_f32 v21, v28, v29
.LBB0_66:
	s_or_b64 exec, exec, s[76:77]
	v_mov_b32_e32 v26, 0
	s_and_saveexec_b64 s[76:77], vcc
	s_cbranch_execz .LBB0_68
	v_or_b32_e32 v26, v20, v149
	v_ashrrev_i32_e32 v27, 31, v26
	s_mov_b64 s[34:35], s[68:69]
	s_mov_b64 s[48:49], s[70:71]
	v_readlane_b32 s56, v253, 2
	v_lshlrev_b64 v[26:27], 9, v[26:27]
	v_readlane_b32 s57, v253, 3
	v_readlane_b32 s58, v253, 4
	v_readlane_b32 s59, v253, 5
	v_lshl_add_u64 v[26:27], s[56:57], 0, v[26:27]
	v_lshl_add_u64 v[26:27], v[22:23], 2, v[26:27]
	global_load_dwordx4 v[26:29], v[26:27], off nt
	v_readlane_b32 s60, v253, 6
	v_readlane_b32 s61, v253, 7
	v_readlane_b32 s62, v253, 8
	v_readlane_b32 s63, v253, 9
	v_readlane_b32 s64, v253, 10
	v_readlane_b32 s65, v253, 11
	v_readlane_b32 s70, v253, 16
	v_readlane_b32 s71, v253, 17
	v_readlane_b32 s68, v253, 14
	v_readlane_b32 s69, v253, 15
	v_readlane_b32 s64, v253, 40
	s_mov_b64 s[70:71], s[48:49]
	v_readlane_b32 s48, v253, 52
	v_readlane_b32 s56, v253, 32
	v_readlane_b32 s65, v253, 41
	v_readlane_b32 s49, v253, 53
	s_mov_b64 s[68:69], s[34:35]
	v_readlane_b32 s58, v253, 34
	v_readlane_b32 s59, v253, 35
	v_readlane_b32 s66, v253, 12
	v_readlane_b32 s67, v253, 13
	v_readlane_b32 s57, v253, 33
	v_readlane_b32 s60, v253, 36
	v_readlane_b32 s61, v253, 37
	v_readlane_b32 s62, v253, 38
	v_readlane_b32 s63, v253, 39
	s_waitcnt vmcnt(0)
	v_cvt_pk_bf16_f32 v26, v26, v27
	v_cvt_pk_bf16_f32 v19, v28, v29
.LBB0_68:
	s_or_b64 exec, exec, s[76:77]
	v_mov_b32_e32 v27, 0
	v_mov_b32_e32 v28, 0
	v_mov_b32_e32 v29, 0
	s_and_saveexec_b64 s[76:77], vcc
	s_cbranch_execz .LBB0_70
	v_or_b32_e32 v28, v20, v150
	v_ashrrev_i32_e32 v29, 31, v28
	s_mov_b64 s[34:35], s[68:69]
	s_mov_b64 s[48:49], s[70:71]
	v_readlane_b32 s56, v253, 2
	v_lshlrev_b64 v[28:29], 9, v[28:29]
	v_readlane_b32 s57, v253, 3
	v_readlane_b32 s58, v253, 4
	v_readlane_b32 s59, v253, 5
	v_lshl_add_u64 v[28:29], s[56:57], 0, v[28:29]
	v_lshl_add_u64 v[28:29], v[22:23], 2, v[28:29]
	global_load_dwordx4 v[28:31], v[28:29], off nt
	v_readlane_b32 s60, v253, 6
	v_readlane_b32 s61, v253, 7
	v_readlane_b32 s62, v253, 8
	v_readlane_b32 s63, v253, 9
	v_readlane_b32 s64, v253, 10
	v_readlane_b32 s65, v253, 11
	v_readlane_b32 s70, v253, 16
	v_readlane_b32 s71, v253, 17
	v_readlane_b32 s68, v253, 14
	v_readlane_b32 s69, v253, 15
	v_readlane_b32 s64, v253, 40
	s_mov_b64 s[70:71], s[48:49]
	v_readlane_b32 s48, v253, 52
	v_readlane_b32 s56, v253, 32
	v_readlane_b32 s65, v253, 41
	v_readlane_b32 s49, v253, 53
	s_mov_b64 s[68:69], s[34:35]
	v_readlane_b32 s58, v253, 34
	v_readlane_b32 s59, v253, 35
	v_readlane_b32 s66, v253, 12
	v_readlane_b32 s67, v253, 13
	v_readlane_b32 s57, v253, 33
	v_readlane_b32 s60, v253, 36
	v_readlane_b32 s61, v253, 37
	v_readlane_b32 s62, v253, 38
	v_readlane_b32 s63, v253, 39
	s_waitcnt vmcnt(0)
	v_cvt_pk_bf16_f32 v29, v28, v29
	v_cvt_pk_bf16_f32 v28, v30, v31
.LBB0_70:
	s_or_b64 exec, exec, s[76:77]
	v_mov_b32_e32 v30, 0
	s_and_saveexec_b64 s[76:77], vcc
	s_cbranch_execz .LBB0_72
	v_or_b32_e32 v30, v20, v151
	v_ashrrev_i32_e32 v31, 31, v30
	s_mov_b64 s[34:35], s[68:69]
	s_mov_b64 s[48:49], s[70:71]
	v_readlane_b32 s56, v253, 2
	v_lshlrev_b64 v[30:31], 9, v[30:31]
	v_readlane_b32 s57, v253, 3
	v_readlane_b32 s58, v253, 4
	v_readlane_b32 s59, v253, 5
	v_lshl_add_u64 v[30:31], s[56:57], 0, v[30:31]
	v_lshl_add_u64 v[22:23], v[22:23], 2, v[30:31]
	global_load_dwordx4 v[30:33], v[22:23], off nt
	v_readlane_b32 s60, v253, 6
	v_readlane_b32 s61, v253, 7
	v_readlane_b32 s62, v253, 8
	v_readlane_b32 s63, v253, 9
	v_readlane_b32 s64, v253, 10
	v_readlane_b32 s65, v253, 11
	v_readlane_b32 s70, v253, 16
	v_readlane_b32 s71, v253, 17
	v_readlane_b32 s68, v253, 14
	v_readlane_b32 s69, v253, 15
	v_readlane_b32 s64, v253, 40
	s_mov_b64 s[70:71], s[48:49]
	v_readlane_b32 s48, v253, 52
	v_readlane_b32 s56, v253, 32
	v_readlane_b32 s65, v253, 41
	v_readlane_b32 s49, v253, 53
	s_mov_b64 s[68:69], s[34:35]
	v_readlane_b32 s58, v253, 34
	v_readlane_b32 s59, v253, 35
	v_readlane_b32 s66, v253, 12
	v_readlane_b32 s67, v253, 13
	v_readlane_b32 s57, v253, 33
	v_readlane_b32 s60, v253, 36
	v_readlane_b32 s61, v253, 37
	v_readlane_b32 s62, v253, 38
	v_readlane_b32 s63, v253, 39
	s_waitcnt vmcnt(0)
	v_cvt_pk_bf16_f32 v30, v30, v31
	v_cvt_pk_bf16_f32 v27, v32, v33

; __device__ __forceinline__ void transpose_tile2(const float* tsrc, u16* tdst, int tK, int tN, int tNpad, int tile, u16* sm, const bool rp0 = false, const bool rp1 = false, const bool upperm = false, const float* gk = nullptr) {
;     ...
;   for (int t = 0; t < 2; ++t) {
;     const int kt = (tile + t) / nNt, nt = (tile + t) - kt * nNt;
;     k0s[t] = kt * 64; n0s[t] = nt * 64;
; #pragma unroll
;     for (int i = 0; i < 4; ++i) {
;       const int nsrc0 = upperm ? (((n0s[t] >> 7) & 1) * DFF + 128 * (n0s[t] >> 8) + (n0s[t] & 127)) : n0s[t];
;       const int k = r + 16 * i, n = nsrc0 + c4 * 4;
;       v[t][i] = make_float4(0.f, 0.f, 0.f, 0.f);
;       if (n < tN) v[t][i] = *(const float4*)(tsrc + (size_t)(k0s[t] + k) * tN + n);
;       if (gk) { const float gs = gk[k0s[t] + k]; v[t][i].x *= gs; v[t][i].y *= gs; v[t][i].z *= gs; v[t][i].w *= gs; }
;     }
;   }
.LBB0_74:
	s_andn2_saveexec_b64 s[54:55], s[48:49]
	s_cbranch_execz .LBB0_92
	v_add_u32_e32 v3, 0xffffeb40, v119
	v_ashrrev_i32_e32 v2, 31, v3
	v_lshrrev_b32_e32 v2, 28, v2
	v_add_u32_e32 v2, v3, v2
	v_ashrrev_i32_e32 v4, 4, v2
	v_lshlrev_b32_e32 v2, 6, v4
	v_lshlrev_b32_e32 v4, 10, v4
	v_lshlrev_b32_e32 v3, 6, v3
	v_sub_u32_e32 v8, v3, v4
	v_or_b32_e32 v4, v8, v42
	v_cmp_gt_i32_e32 vcc, s84, v4
	v_mov_b32_e32 v3, 0
	v_ashrrev_i32_e32 v5, 31, v4
	v_mov_b32_e32 v9, 0
	v_mov_b32_e32 v10, 0
	s_and_saveexec_b64 s[76:77], vcc
	s_cbranch_execz .LBB0_77
	v_or_b32_e32 v6, v2, v40
	v_ashrrev_i32_e32 v7, 31, v6
	v_readlane_b32 s34, v253, 44
	v_lshlrev_b64 v[6:7], 12, v[6:7]
	v_readlane_b32 s35, v253, 45
	s_nop 1
	v_lshl_add_u64 v[6:7], s[34:35], 0, v[6:7]
	v_lshl_add_u64 v[6:7], v[4:5], 2, v[6:7]
	global_load_dwordx4 v[10:13], v[6:7], off nt
	s_waitcnt vmcnt(0)
	v_cvt_pk_bf16_f32 v10, v10, v11
	v_cvt_pk_bf16_f32 v9, v12, v13
.LBB0_77:
	s_or_b64 exec, exec, s[76:77]
	v_mov_b32_e32 v11, 0
	s_and_saveexec_b64 s[76:77], vcc
	s_cbranch_execz .LBB0_79
	v_or_b32_e32 v6, v2, v149
	v_ashrrev_i32_e32 v7, 31, v6
	v_readlane_b32 s34, v253, 44
	v_lshlrev_b64 v[6:7], 12, v[6:7]
	v_readlane_b32 s35, v253, 45
	s_nop 1
	v_lshl_add_u64 v[6:7], s[34:35], 0, v[6:7]
	v_lshl_add_u64 v[6:7], v[4:5], 2, v[6:7]
	global_load_dwordx4 v[12:15], v[6:7], off nt
	s_waitcnt vmcnt(0)
	v_cvt_pk_bf16_f32 v11, v12, v13
	v_cvt_pk_bf16_f32 v3, v14, v15
.LBB0_79:
	s_or_b64 exec, exec, s[76:77]
	v_mov_b32_e32 v13, 0
	v_mov_b32_e32 v14, 0
	v_mov_b32_e32 v15, 0
	s_and_saveexec_b64 s[76:77], vcc
	s_cbranch_execz .LBB0_81
	v_or_b32_e32 v6, v2, v150
	v_ashrrev_i32_e32 v7, 31, v6
	v_readlane_b32 s34, v253, 44
	v_lshlrev_b64 v[6:7], 12, v[6:7]
	v_readlane_b32 s35, v253, 45
	s_nop 1
	v_lshl_add_u64 v[6:7], s[34:35], 0, v[6:7]
	v_lshl_add_u64 v[6:7], v[4:5], 2, v[6:7]
	global_load_dwordx4 v[14:17], v[6:7], off nt
	s_waitcnt vmcnt(0)
	v_cvt_pk_bf16_f32 v15, v14, v15
	v_cvt_pk_bf16_f32 v14, v16, v17
.LBB0_81:
	s_or_b64 exec, exec, s[76:77]
	v_mov_b32_e32 v16, 0
	s_and_saveexec_b64 s[76:77], vcc
	s_cbranch_execz .LBB0_83
	v_or_b32_e32 v6, v2, v151
	v_ashrrev_i32_e32 v7, 31, v6
	v_readlane_b32 s34, v253, 44
	v_lshlrev_b64 v[6:7], 12, v[6:7]
	v_readlane_b32 s35, v253, 45
	s_nop 1
	v_lshl_add_u64 v[6:7], s[34:35], 0, v[6:7]
	v_lshl_add_u64 v[4:5], v[4:5], 2, v[6:7]
	global_load_dwordx4 v[4:7], v[4:5], off nt
	s_waitcnt vmcnt(0)
	v_cvt_pk_bf16_f32 v16, v4, v5
	v_cvt_pk_bf16_f32 v13, v6, v7
.LBB0_83:
	s_or_b64 exec, exec, s[76:77]
	v_add_u32_e32 v5, 0xffffeb41, v119
	v_ashrrev_i32_e32 v4, 31, v5
	v_lshrrev_b32_e32 v4, 28, v4
	v_add_u32_e32 v4, v5, v4
	v_ashrrev_i32_e32 v6, 4, v4
	v_lshlrev_b32_e32 v4, 6, v6
	v_lshlrev_b32_e32 v6, 10, v6
	v_lshlrev_b32_e32 v5, 6, v5
	v_sub_u32_e32 v12, v5, v6
	v_or_b32_e32 v6, v12, v42
	v_cmp_gt_i32_e32 vcc, s84, v6
	v_mov_b32_e32 v5, 0
	v_ashrrev_i32_e32 v7, 31, v6
	v_mov_b32_e32 v17, 0
	v_mov_b32_e32 v18, 0
	s_and_saveexec_b64 s[76:77], vcc
	s_cbranch_execz .LBB0_85
	v_or_b32_e32 v18, v4, v40
	v_ashrrev_i32_e32 v19, 31, v18
	v_readlane_b32 s34, v253, 44
	v_lshlrev_b64 v[18:19], 12, v[18:19]
	v_readlane_b32 s35, v253, 45
	s_nop 1
	v_lshl_add_u64 v[18:19], s[34:35], 0, v[18:19]
	v_lshl_add_u64 v[18:19], v[6:7], 2, v[18:19]
	global_load_dwordx4 v[18:21], v[18:19], off nt
	s_waitcnt vmcnt(0)
	v_cvt_pk_bf16_f32 v18, v18, v19
	v_cvt_pk_bf16_f32 v17, v20, v21
.LBB0_85:
	s_or_b64 exec, exec, s[76:77]
	v_mov_b32_e32 v19, 0
	s_and_saveexec_b64 s[76:77], vcc
	s_cbranch_execz .LBB0_87
	v_or_b32_e32 v20, v4, v149
	v_ashrrev_i32_e32 v21, 31, v20
	v_readlane_b32 s34, v253, 44
	v_lshlrev_b64 v[20:21], 12, v[20:21]
	v_readlane_b32 s35, v253, 45
	s_nop 1
	v_lshl_add_u64 v[20:21], s[34:35], 0, v[20:21]
	v_lshl_add_u64 v[20:21], v[6:7], 2, v[20:21]
	global_load_dwordx4 v[20:23], v[20:21], off nt
	s_waitcnt vmcnt(0)
	v_cvt_pk_bf16_f32 v19, v20, v21
	v_cvt_pk_bf16_f32 v5, v22, v23
.LBB0_87:
	s_or_b64 exec, exec, s[76:77]
	v_mov_b32_e32 v20, 0
	v_mov_b32_e32 v21, 0
	v_mov_b32_e32 v22, 0
	s_and_saveexec_b64 s[76:77], vcc
	s_cbranch_execz .LBB0_89
	v_or_b32_e32 v22, v4, v150
	v_ashrrev_i32_e32 v23, 31, v22
	v_readlane_b32 s34, v253, 44
	v_lshlrev_b64 v[22:23], 12, v[22:23]
	v_readlane_b32 s35, v253, 45
	s_nop 1
	v_lshl_add_u64 v[22:23], s[34:35], 0, v[22:23]
	v_lshl_add_u64 v[22:23], v[6:7], 2, v[22:23]
	global_load_dwordx4 v[22:25], v[22:23], off nt
	s_waitcnt vmcnt(0)
	v_cvt_pk_bf16_f32 v22, v22, v23
	v_cvt_pk_bf16_f32 v21, v24, v25
.LBB0_89:
	s_or_b64 exec, exec, s[76:77]
	v_mov_b32_e32 v23, 0
	s_and_saveexec_b64 s[76:77], vcc
	s_cbranch_execz .LBB0_91
	v_or_b32_e32 v24, v4, v151
	v_ashrrev_i32_e32 v25, 31, v24
	v_readlane_b32 s34, v253, 44
	v_lshlrev_b64 v[24:25], 12, v[24:25]
	v_readlane_b32 s35, v253, 45
	s_nop 1
	v_lshl_add_u64 v[24:25], s[34:35], 0, v[24:25]
	v_lshl_add_u64 v[6:7], v[6:7], 2, v[24:25]
	global_load_dwordx4 v[24:27], v[6:7], off nt
	s_waitcnt vmcnt(0)
	v_cvt_pk_bf16_f32 v23, v24, v25
	v_cvt_pk_bf16_f32 v20, v26, v27

; __device__ __forceinline__ void transpose_tile2(const float* tsrc, u16* tdst, int tK, int tN, int tNpad, int tile, u16* sm, const bool rp0 = false, const bool rp1 = false, const bool upperm = false, const float* gk = nullptr) {
;     ...
;   for (int t = 0; t < 2; ++t) {
;     const int kt = (tile + t) / nNt, nt = (tile + t) - kt * nNt;
;     k0s[t] = kt * 64; n0s[t] = nt * 64;
; #pragma unroll
;     for (int i = 0; i < 4; ++i) {
;       const int nsrc0 = upperm ? (((n0s[t] >> 7) & 1) * DFF + 128 * (n0s[t] >> 8) + (n0s[t] & 127)) : n0s[t];
;       const int k = r + 16 * i, n = nsrc0 + c4 * 4;
;       v[t][i] = make_float4(0.f, 0.f, 0.f, 0.f);
;       if (n < tN) v[t][i] = *(const float4*)(tsrc + (size_t)(k0s[t] + k) * tN + n);
;       if (gk) { const float gs = gk[k0s[t] + k]; v[t][i].x *= gs; v[t][i].y *= gs; v[t][i].z *= gs; v[t][i].w *= gs; }
;     }
;   }
; #pragma unroll
;   for (int t = 0; t < 2; ++t)
; #pragma unroll
;     for (int i = 0; i < 4; ++i) {
;       const int k = r + 16 * i;
;       u16* d = sm + t * 64 * LDSP;
;       const uint32_t p01 = pack2(v[t][i].x, v[t][i].y), p23 = pack2(v[t][i].z, v[t][i].w);
.LBB0_93:
	s_andn2_saveexec_b64 s[54:55], s[52:53]
	s_cbranch_execz .LBB0_111
	v_add_u32_e32 v3, 0xffffee00, v119
	v_ashrrev_i32_e32 v2, 31, v3
	v_lshrrev_b32_e32 v2, 28, v2
	v_add_u32_e32 v2, v3, v2
	v_ashrrev_i32_e32 v4, 4, v2
	v_lshlrev_b32_e32 v2, 6, v4
	v_lshlrev_b32_e32 v4, 10, v4
	v_lshlrev_b32_e32 v3, 6, v3
	v_sub_u32_e32 v8, v3, v4
	v_or_b32_e32 v4, v8, v42
	v_cmp_gt_i32_e32 vcc, s84, v4
	v_mov_b32_e32 v3, 0
	v_ashrrev_i32_e32 v5, 31, v4
	v_mov_b32_e32 v9, 0
	v_mov_b32_e32 v10, 0
	s_and_saveexec_b64 s[76:77], vcc
	s_cbranch_execz .LBB0_96
	v_or_b32_e32 v6, v2, v40
	v_ashrrev_i32_e32 v7, 31, v6
	v_lshlrev_b64 v[6:7], 12, v[6:7]
	v_lshl_add_u64 v[6:7], s[58:59], 0, v[6:7]
	v_lshl_add_u64 v[6:7], v[4:5], 2, v[6:7]
	global_load_dwordx4 v[10:13], v[6:7], off nt
	s_waitcnt vmcnt(0)
	v_cvt_pk_bf16_f32 v10, v10, v11
	v_cvt_pk_bf16_f32 v9, v12, v13
.LBB0_96:
	s_or_b64 exec, exec, s[76:77]
	v_mov_b32_e32 v11, 0
	s_and_saveexec_b64 s[76:77], vcc
	s_cbranch_execz .LBB0_98
	v_or_b32_e32 v6, v2, v149
	v_ashrrev_i32_e32 v7, 31, v6
	v_lshlrev_b64 v[6:7], 12, v[6:7]
	v_lshl_add_u64 v[6:7], s[58:59], 0, v[6:7]
	v_lshl_add_u64 v[6:7], v[4:5], 2, v[6:7]
	global_load_dwordx4 v[12:15], v[6:7], off nt
	s_waitcnt vmcnt(0)
	v_cvt_pk_bf16_f32 v11, v12, v13
	v_cvt_pk_bf16_f32 v3, v14, v15
.LBB0_98:
	s_or_b64 exec, exec, s[76:77]
	v_mov_b32_e32 v13, 0
	v_mov_b32_e32 v14, 0
	v_mov_b32_e32 v15, 0
	s_and_saveexec_b64 s[76:77], vcc
	s_cbranch_execz .LBB0_100
	v_or_b32_e32 v6, v2, v150
	v_ashrrev_i32_e32 v7, 31, v6
	v_lshlrev_b64 v[6:7], 12, v[6:7]
	v_lshl_add_u64 v[6:7], s[58:59], 0, v[6:7]
	v_lshl_add_u64 v[6:7], v[4:5], 2, v[6:7]
	global_load_dwordx4 v[14:17], v[6:7], off nt
	s_waitcnt vmcnt(0)
	v_cvt_pk_bf16_f32 v15, v14, v15
	v_cvt_pk_bf16_f32 v14, v16, v17
.LBB0_100:
	s_or_b64 exec, exec, s[76:77]
	v_mov_b32_e32 v16, 0
	s_and_saveexec_b64 s[76:77], vcc
	s_cbranch_execz .LBB0_102
	v_or_b32_e32 v6, v2, v151
	v_ashrrev_i32_e32 v7, 31, v6
	v_lshlrev_b64 v[6:7], 12, v[6:7]
	v_lshl_add_u64 v[6:7], s[58:59], 0, v[6:7]
	v_lshl_add_u64 v[4:5], v[4:5], 2, v[6:7]
	global_load_dwordx4 v[4:7], v[4:5], off nt
	s_waitcnt vmcnt(0)
	v_cvt_pk_bf16_f32 v16, v4, v5
	v_cvt_pk_bf16_f32 v13, v6, v7
.LBB0_102:
	s_or_b64 exec, exec, s[76:77]
	v_add_u32_e32 v5, 0xffffee01, v119
	v_ashrrev_i32_e32 v4, 31, v5
	v_lshrrev_b32_e32 v4, 28, v4
	v_add_u32_e32 v4, v5, v4
	v_ashrrev_i32_e32 v6, 4, v4
	v_lshlrev_b32_e32 v4, 6, v6
	v_lshlrev_b32_e32 v6, 10, v6
	v_lshlrev_b32_e32 v5, 6, v5
	v_sub_u32_e32 v12, v5, v6
	v_or_b32_e32 v6, v12, v42
	v_cmp_gt_i32_e32 vcc, s84, v6
	v_mov_b32_e32 v5, 0
	v_ashrrev_i32_e32 v7, 31, v6
	v_mov_b32_e32 v17, 0
	v_mov_b32_e32 v18, 0
	s_and_saveexec_b64 s[76:77], vcc
	s_cbranch_execz .LBB0_104
	v_or_b32_e32 v18, v4, v40
	v_ashrrev_i32_e32 v19, 31, v18
	v_lshlrev_b64 v[18:19], 12, v[18:19]
	v_lshl_add_u64 v[18:19], s[58:59], 0, v[18:19]
	v_lshl_add_u64 v[18:19], v[6:7], 2, v[18:19]
	global_load_dwordx4 v[18:21], v[18:19], off nt
	s_waitcnt vmcnt(0)
	v_cvt_pk_bf16_f32 v18, v18, v19
	v_cvt_pk_bf16_f32 v17, v20, v21
.LBB0_104:
	s_or_b64 exec, exec, s[76:77]
	v_mov_b32_e32 v19, 0
	s_and_saveexec_b64 s[76:77], vcc
	s_cbranch_execz .LBB0_106
	v_or_b32_e32 v20, v4, v149
	v_ashrrev_i32_e32 v21, 31, v20
	v_lshlrev_b64 v[20:21], 12, v[20:21]
	v_lshl_add_u64 v[20:21], s[58:59], 0, v[20:21]
	v_lshl_add_u64 v[20:21], v[6:7], 2, v[20:21]
	global_load_dwordx4 v[20:23], v[20:21], off nt
	s_waitcnt vmcnt(0)
	v_cvt_pk_bf16_f32 v19, v20, v21
	v_cvt_pk_bf16_f32 v5, v22, v23
.LBB0_106:
	s_or_b64 exec, exec, s[76:77]
	v_mov_b32_e32 v20, 0
	v_mov_b32_e32 v21, 0
	v_mov_b32_e32 v22, 0
	s_and_saveexec_b64 s[76:77], vcc
	s_cbranch_execz .LBB0_108
	v_or_b32_e32 v22, v4, v150
	v_ashrrev_i32_e32 v23, 31, v22
	v_lshlrev_b64 v[22:23], 12, v[22:23]
	v_lshl_add_u64 v[22:23], s[58:59], 0, v[22:23]
	v_lshl_add_u64 v[22:23], v[6:7], 2, v[22:23]
	global_load_dwordx4 v[22:25], v[22:23], off nt
	s_waitcnt vmcnt(0)
	v_cvt_pk_bf16_f32 v22, v22, v23
	v_cvt_pk_bf16_f32 v21, v24, v25
.LBB0_108:
	s_or_b64 exec, exec, s[76:77]
	v_mov_b32_e32 v23, 0
	s_and_saveexec_b64 s[76:77], vcc
	s_cbranch_execz .LBB0_110
	v_or_b32_e32 v24, v4, v151
	v_ashrrev_i32_e32 v25, 31, v24
	v_lshlrev_b64 v[24:25], 12, v[24:25]
	v_lshl_add_u64 v[24:25], s[58:59], 0, v[24:25]
	v_lshl_add_u64 v[6:7], v[6:7], 2, v[24:25]
	global_load_dwordx4 v[24:27], v[6:7], off nt
	s_waitcnt vmcnt(0)
	v_cvt_pk_bf16_f32 v23, v24, v25
	v_cvt_pk_bf16_f32 v20, v26, v27

; __device__ __forceinline__ void transpose_tile2(const float* tsrc, u16* tdst, int tK, int tN, int tNpad, int tile, u16* sm, const bool rp0 = false, const bool rp1 = false, const bool upperm = false, const float* gk = nullptr) {
;     ...
;   for (int t = 0; t < 2; ++t) {
;     const int kt = (tile + t) / nNt, nt = (tile + t) - kt * nNt;
;     k0s[t] = kt * 64; n0s[t] = nt * 64;
; #pragma unroll
;     for (int i = 0; i < 4; ++i) {
;       const int nsrc0 = upperm ? (((n0s[t] >> 7) & 1) * DFF + 128 * (n0s[t] >> 8) + (n0s[t] & 127)) : n0s[t];
;       const int k = r + 16 * i, n = nsrc0 + c4 * 4;
;       v[t][i] = make_float4(0.f, 0.f, 0.f, 0.f);
;       if (n < tN) v[t][i] = *(const float4*)(tsrc + (size_t)(k0s[t] + k) * tN + n);
;       if (gk) { const float gs = gk[k0s[t] + k]; v[t][i].x *= gs; v[t][i].y *= gs; v[t][i].z *= gs; v[t][i].w *= gs; }
;     }
;   }
; #pragma unroll
;   for (int t = 0; t < 2; ++t)
; #pragma unroll
;     for (int i = 0; i < 4; ++i) {
;       const int k = r + 16 * i;
;       u16* d = sm + t * 64 * LDSP;
;       const uint32_t p01 = pack2(v[t][i].x, v[t][i].y), p23 = pack2(v[t][i].z, v[t][i].w);
.LBB0_112:
	s_andn2_saveexec_b64 s[6:7], s[6:7]
	s_cbranch_execz .LBB0_130
	v_add_u32_e32 v2, 0xfffff380, v119
	s_mov_b32 s34, 0x2e8ba2e9
	v_mul_hi_i32 v3, v2, s34
	v_lshrrev_b32_e32 v4, 31, v3
	v_ashrrev_i32_e32 v3, 4, v3
	v_add_u32_e32 v3, v3, v4
	s_movk_i32 s34, 0xffa8
	v_mad_u64_u32 v[128:129], s[34:35], v3, s34, v[2:3]
	v_lshlrev_b32_e32 v2, 5, v128
	v_and_b32_e32 v2, 0xffffff80, v2
	v_lshlrev_b32_e32 v34, 6, v3
	v_add_u32_e32 v18, v2, v164
	v_cmp_gt_i32_e32 vcc, s30, v18
	v_or_b32_e32 v6, v34, v40
	v_mov_b32_e32 v8, 0
	v_ashrrev_i32_e32 v19, 31, v18
	v_mov_b32_e32 v4, 0
	v_mov_b32_e32 v5, 0
	v_mov_b32_e32 v2, 0
	v_mov_b32_e32 v3, 0
	s_and_saveexec_b64 s[54:55], vcc
	s_cbranch_execz .LBB0_115
	v_mul_lo_u32 v2, v6, s30
	v_readlane_b32 s34, v253, 48
	v_ashrrev_i32_e32 v3, 31, v2
	v_readlane_b32 s35, v253, 49
	s_nop 1
	v_lshl_add_u64 v[2:3], v[2:3], 2, s[34:35]
	v_lshl_add_u64 v[2:3], v[18:19], 2, v[2:3]
	global_load_dwordx4 v[2:5], v[2:3], off nt
.LBB0_115:
	s_or_b64 exec, exec, s[54:55]
	v_ashrrev_i32_e32 v7, 31, v6
	v_lshl_add_u64 v[6:7], v[6:7], 2, s[92:93]
	global_load_dword v130, v[6:7], off
	v_or_b32_e32 v10, v34, v149
	v_mov_b32_e32 v9, 0
	v_mov_b32_e32 v6, 0
	v_mov_b32_e32 v7, 0
	s_and_saveexec_b64 s[54:55], vcc
	s_cbranch_execz .LBB0_117
	v_mul_lo_u32 v6, v10, s30
	v_readlane_b32 s34, v253, 48
	v_ashrrev_i32_e32 v7, 31, v6
	v_readlane_b32 s35, v253, 49
	s_nop 1
	v_lshl_add_u64 v[6:7], v[6:7], 2, s[34:35]
	v_lshl_add_u64 v[6:7], v[18:19], 2, v[6:7]
	global_load_dwordx4 v[6:9], v[6:7], off nt
.LBB0_117:
	s_or_b64 exec, exec, s[54:55]
	v_ashrrev_i32_e32 v11, 31, v10
	v_lshl_add_u64 v[10:11], v[10:11], 2, s[92:93]
	global_load_dword v132, v[10:11], off
	v_or_b32_e32 v14, v34, v150
	v_mov_b32_e32 v16, 0
	v_mov_b32_e32 v12, 0
	v_mov_b32_e32 v13, 0
	v_mov_b32_e32 v10, 0
	v_mov_b32_e32 v11, 0
	s_and_saveexec_b64 s[54:55], vcc
	s_cbranch_execz .LBB0_119
	v_mul_lo_u32 v10, v14, s30
	v_readlane_b32 s34, v253, 48
	v_ashrrev_i32_e32 v11, 31, v10
	v_readlane_b32 s35, v253, 49
	s_nop 1
	v_lshl_add_u64 v[10:11], v[10:11], 2, s[34:35]
	v_lshl_add_u64 v[10:11], v[18:19], 2, v[10:11]
	global_load_dwordx4 v[10:13], v[10:11], off nt
.LBB0_119:
	s_or_b64 exec, exec, s[54:55]
	v_ashrrev_i32_e32 v15, 31, v14
	v_lshl_add_u64 v[14:15], v[14:15], 2, s[92:93]
	global_load_dword v134, v[14:15], off
	v_or_b32_e32 v20, v34, v151
	v_mov_b32_e32 v17, 0
	v_mov_b32_e32 v14, 0
	v_mov_b32_e32 v15, 0
	s_and_saveexec_b64 s[54:55], vcc
	s_cbranch_execz .LBB0_121
	v_mul_lo_u32 v14, v20, s30
	v_readlane_b32 s34, v253, 48
	v_ashrrev_i32_e32 v15, 31, v14
	v_readlane_b32 s35, v253, 49
	s_nop 1
	v_lshl_add_u64 v[14:15], v[14:15], 2, s[34:35]
	v_lshl_add_u64 v[14:15], v[18:19], 2, v[14:15]
	global_load_dwordx4 v[14:17], v[14:15], off nt
.LBB0_121:
	s_or_b64 exec, exec, s[54:55]
	v_ashrrev_i32_e32 v21, 31, v20
	v_lshl_add_u64 v[18:19], v[20:21], 2, s[92:93]
	global_load_dword v136, v[18:19], off
	v_add_u32_e32 v18, 0xfffff381, v119
	s_mov_b32 s34, 0x2e8ba2e9
	v_mul_hi_i32 v19, v18, s34
	v_lshrrev_b32_e32 v20, 31, v19
	v_ashrrev_i32_e32 v19, 4, v19
	v_add_u32_e32 v19, v19, v20
	s_movk_i32 s34, 0xffa8
	v_mad_u64_u32 v[138:139], s[34:35], v19, s34, v[18:19]
	v_lshlrev_b32_e32 v36, 6, v19
	v_bfe_i32 v18, v18, 1, 1
	v_lshlrev_b32_e32 v19, 5, v138
	v_and_b32_e32 v18, 0xb00, v18
	v_and_b32_e32 v19, 0xffffff80, v19
	v_add_u32_e32 v140, v19, v18
	v_or_b32_e32 v18, v140, v160
	v_cmp_gt_i32_e32 vcc, s30, v18
	v_or_b32_e32 v18, v36, v40
	v_mov_b32_e32 v28, 0
	v_ashrrev_i32_e32 v141, 31, v140
	v_mov_b32_e32 v24, 0
	v_mov_b32_e32 v25, 0
	v_mov_b32_e32 v22, 0
	v_mov_b32_e32 v23, 0
	s_and_saveexec_b64 s[54:55], vcc
	s_cbranch_execz .LBB0_123
	v_mul_lo_u32 v20, v18, s30
	v_readlane_b32 s34, v253, 48
	v_ashrrev_i32_e32 v21, 31, v20
	v_readlane_b32 s35, v253, 49
	v_lshl_add_u64 v[22:23], v[140:141], 0, v[42:43]
	s_nop 0
	v_lshl_add_u64 v[20:21], v[20:21], 2, s[34:35]
	v_lshl_add_u64 v[20:21], v[22:23], 2, v[20:21]
	global_load_dwordx4 v[22:25], v[20:21], off offset:256 nt
.LBB0_123:
	s_or_b64 exec, exec, s[54:55]
	v_ashrrev_i32_e32 v19, 31, v18
	v_lshl_add_u64 v[18:19], v[18:19], 2, s[92:93]
	global_load_dword v144, v[18:19], off
	v_or_b32_e32 v18, v36, v149
	v_mov_b32_e32 v29, 0
	v_mov_b32_e32 v26, 0
	v_mov_b32_e32 v27, 0
	s_and_saveexec_b64 s[54:55], vcc
	s_cbranch_execz .LBB0_125
	v_mul_lo_u32 v20, v18, s30
	v_readlane_b32 s34, v253, 48
	v_ashrrev_i32_e32 v21, 31, v20
	v_readlane_b32 s35, v253, 49
	v_lshl_add_u64 v[26:27], v[140:141], 0, v[42:43]
	s_nop 0
	v_lshl_add_u64 v[20:21], v[20:21], 2, s[34:35]
	v_lshl_add_u64 v[20:21], v[26:27], 2, v[20:21]
	global_load_dwordx4 v[26:29], v[20:21], off offset:256 nt
.LBB0_125:
	s_or_b64 exec, exec, s[54:55]
	v_ashrrev_i32_e32 v19, 31, v18
	v_lshl_add_u64 v[18:19], v[18:19], 2, s[92:93]
	global_load_dword v146, v[18:19], off
	v_or_b32_e32 v18, v36, v150
	v_mov_b32_e32 v20, 0
	v_mov_b32_e32 v32, 0
	v_mov_b32_e32 v33, 0
	v_mov_b32_e32 v30, 0
	v_mov_b32_e32 v31, 0
	s_and_saveexec_b64 s[54:55], vcc
	s_cbranch_execz .LBB0_127
	v_mul_lo_u32 v30, v18, s30
	v_readlane_b32 s34, v253, 48
	v_ashrrev_i32_e32 v31, 31, v30
	v_readlane_b32 s35, v253, 49
	v_lshl_add_u64 v[32:33], v[140:141], 0, v[42:43]
	s_nop 0
	v_lshl_add_u64 v[30:31], v[30:31], 2, s[34:35]
	v_lshl_add_u64 v[30:31], v[32:33], 2, v[30:31]
	global_load_dwordx4 v[30:33], v[30:31], off offset:256 nt
.LBB0_127:
	s_or_b64 exec, exec, s[54:55]
	v_ashrrev_i32_e32 v19, 31, v18
	v_lshl_add_u64 v[18:19], v[18:19], 2, s[92:93]
	global_load_dword v148, v[18:19], off
	v_or_b32_e32 v142, v36, v151
	v_mov_b32_e32 v21, 0
	v_mov_b32_e32 v18, 0
	v_mov_b32_e32 v19, 0
	s_and_saveexec_b64 s[54:55], vcc
	s_cbranch_execz .LBB0_129
	v_mul_lo_u32 v18, v142, s30
	v_readlane_b32 s34, v253, 48
	v_ashrrev_i32_e32 v19, 31, v18
	v_readlane_b32 s35, v253, 49
	v_lshl_add_u64 v[20:21], v[140:141], 0, v[42:43]
	s_nop 0
	v_lshl_add_u64 v[18:19], v[18:19], 2, s[34:35]
	v_lshl_add_u64 v[18:19], v[20:21], 2, v[18:19]
	global_load_dwordx4 v[18:21], v[18:19], off offset:256 nt

; __device__ __forceinline__ void transpose_tile2(const float* tsrc, u16* tdst, int tK, int tN, int tNpad, int tile, u16* sm, const bool rp0 = false, const bool rp1 = false, const bool upperm = false, const float* gk = nullptr) {
;     ...
; #pragma unroll
;     for (int i = 0; i < 4; ++i) {
;       const int nsrc0 = upperm ? (((n0s[t] >> 7) & 1) * DFF + 128 * (n0s[t] >> 8) + (n0s[t] & 127)) : n0s[t];
;       const int k = r + 16 * i, n = nsrc0 + c4 * 4;
;       v[t][i] = make_float4(0.f, 0.f, 0.f, 0.f);
;       if (n < tN) v[t][i] = *(const float4*)(tsrc + (size_t)(k0s[t] + k) * tN + n);
;       if (gk) { const float gs = gk[k0s[t] + k]; v[t][i].x *= gs; v[t][i].y *= gs; v[t][i].z *= gs; v[t][i].w *= gs; }
.LBB0_131:
	s_andn2_saveexec_b64 s[54:55], s[4:5]
	s_cbranch_execz .LBB0_168
	v_add_u32_e32 v2, 0xfffff900, v119
	s_mov_b32 s4, 0x2e8ba2e9
	v_mul_hi_i32 v3, v2, s4
	v_lshrrev_b32_e32 v4, 31, v3
	v_ashrrev_i32_e32 v3, 4, v3
	v_add_u32_e32 v3, v3, v4
	s_movk_i32 s4, 0xffa8
	v_mad_u64_u32 v[36:37], s[4:5], v3, s4, v[2:3]
	v_lshlrev_b32_e32 v2, 5, v36
	v_and_b32_e32 v2, 0xffffff80, v2
	v_lshlrev_b32_e32 v34, 6, v3
	v_add_u32_e32 v18, v2, v164
	v_mov_b32_e32 v39, v38
	s_mov_b64 s[52:53], s[70:71]
	s_mov_b64 s[48:49], s[68:69]
	v_cmp_gt_i32_e64 s[6:7], s30, v18
	v_ashrrev_i32_e32 v19, 31, v18
	v_or_b32_e32 v6, v34, v40
	v_mov_b64_e32 v[4:5], v[38:39]
	v_mov_b64_e32 v[2:3], v[38:39]
	s_and_saveexec_b64 s[4:5], s[6:7]
	s_cbranch_execz .LBB0_134
	v_mul_lo_u32 v2, v6, s30
	v_readlane_b32 s56, v253, 2
	v_ashrrev_i32_e32 v3, 31, v2
	v_readlane_b32 s68, v253, 14
	v_readlane_b32 s69, v253, 15
	v_readlane_b32 s57, v253, 3
	v_readlane_b32 s58, v253, 4
	v_lshl_add_u64 v[2:3], v[2:3], 2, s[68:69]
	v_lshl_add_u64 v[2:3], v[18:19], 2, v[2:3]
	global_load_dwordx4 v[2:5], v[2:3], off nt
	v_readlane_b32 s59, v253, 5
	v_readlane_b32 s60, v253, 6
	v_readlane_b32 s61, v253, 7
	v_readlane_b32 s62, v253, 8
	v_readlane_b32 s63, v253, 9
	v_readlane_b32 s64, v253, 10
	v_readlane_b32 s65, v253, 11
	v_readlane_b32 s66, v253, 12
	v_readlane_b32 s67, v253, 13
	v_readlane_b32 s70, v253, 16
	v_readlane_b32 s71, v253, 17

; __device__ __forceinline__ void transpose_tile2(const float* tsrc, u16* tdst, int tK, int tN, int tNpad, int tile, u16* sm, const bool rp0 = false, const bool rp1 = false, const bool upperm = false, const float* gk = nullptr) {
;     ...
; #pragma unroll
;     for (int i = 0; i < 4; ++i) {
;       const int nsrc0 = upperm ? (((n0s[t] >> 7) & 1) * DFF + 128 * (n0s[t] >> 8) + (n0s[t] & 127)) : n0s[t];
;       const int k = r + 16 * i, n = nsrc0 + c4 * 4;
;       v[t][i] = make_float4(0.f, 0.f, 0.f, 0.f);
;       if (n < tN) v[t][i] = *(const float4*)(tsrc + (size_t)(k0s[t] + k) * tN + n);
;       if (gk) { const float gs = gk[k0s[t] + k]; v[t][i].x *= gs; v[t][i].y *= gs; v[t][i].z *= gs; v[t][i].w *= gs; }
.LBB0_136:
	v_mov_b32_e32 v39, v38
	v_mov_b64_e32 v[8:9], v[38:39]
	v_mov_b64_e32 v[6:7], v[38:39]
	s_and_saveexec_b64 vcc, s[6:7]
	s_cbranch_execz .LBB0_138
	v_or_b32_e32 v6, v34, v149
	v_mul_lo_u32 v6, v6, s30
	v_readlane_b32 s56, v253, 2
	v_ashrrev_i32_e32 v7, 31, v6
	v_readlane_b32 s68, v253, 14
	v_readlane_b32 s69, v253, 15
	v_readlane_b32 s57, v253, 3
	v_readlane_b32 s58, v253, 4
	v_lshl_add_u64 v[6:7], v[6:7], 2, s[68:69]
	v_lshl_add_u64 v[6:7], v[18:19], 2, v[6:7]
	global_load_dwordx4 v[6:9], v[6:7], off nt
	v_readlane_b32 s59, v253, 5
	v_readlane_b32 s60, v253, 6
	v_readlane_b32 s61, v253, 7
	v_readlane_b32 s62, v253, 8
	v_readlane_b32 s63, v253, 9
	v_readlane_b32 s64, v253, 10
	v_readlane_b32 s65, v253, 11
	v_readlane_b32 s66, v253, 12
	v_readlane_b32 s67, v253, 13
	v_readlane_b32 s70, v253, 16
	v_readlane_b32 s71, v253, 17

; __device__ __forceinline__ void transpose_tile2(const float* tsrc, u16* tdst, int tK, int tN, int tNpad, int tile, u16* sm, const bool rp0 = false, const bool rp1 = false, const bool upperm = false, const float* gk = nullptr) {
;     ...
; #pragma unroll
;     for (int i = 0; i < 4; ++i) {
;       const int nsrc0 = upperm ? (((n0s[t] >> 7) & 1) * DFF + 128 * (n0s[t] >> 8) + (n0s[t] & 127)) : n0s[t];
;       const int k = r + 16 * i, n = nsrc0 + c4 * 4;
;       v[t][i] = make_float4(0.f, 0.f, 0.f, 0.f);
;       if (n < tN) v[t][i] = *(const float4*)(tsrc + (size_t)(k0s[t] + k) * tN + n);
;       if (gk) { const float gs = gk[k0s[t] + k]; v[t][i].x *= gs; v[t][i].y *= gs; v[t][i].z *= gs; v[t][i].w *= gs; }
.LBB0_140:
	v_mov_b32_e32 v39, v38
	v_mov_b64_e32 v[12:13], v[38:39]
	v_mov_b64_e32 v[10:11], v[38:39]
	s_and_saveexec_b64 vcc, s[6:7]
	s_cbranch_execz .LBB0_142
	v_or_b32_e32 v10, v34, v150
	v_mul_lo_u32 v10, v10, s30
	v_readlane_b32 s56, v253, 2
	v_ashrrev_i32_e32 v11, 31, v10
	v_readlane_b32 s68, v253, 14
	v_readlane_b32 s69, v253, 15
	v_readlane_b32 s57, v253, 3
	v_readlane_b32 s58, v253, 4
	v_lshl_add_u64 v[10:11], v[10:11], 2, s[68:69]
	v_lshl_add_u64 v[10:11], v[18:19], 2, v[10:11]
	global_load_dwordx4 v[10:13], v[10:11], off nt
	v_readlane_b32 s59, v253, 5
	v_readlane_b32 s60, v253, 6
	v_readlane_b32 s61, v253, 7
	v_readlane_b32 s62, v253, 8
	v_readlane_b32 s63, v253, 9
	v_readlane_b32 s64, v253, 10
	v_readlane_b32 s65, v253, 11
	v_readlane_b32 s66, v253, 12
	v_readlane_b32 s67, v253, 13
	v_readlane_b32 s70, v253, 16
	v_readlane_b32 s71, v253, 17

; __device__ __forceinline__ void transpose_tile2(const float* tsrc, u16* tdst, int tK, int tN, int tNpad, int tile, u16* sm, const bool rp0 = false, const bool rp1 = false, const bool upperm = false, const float* gk = nullptr) {
;     ...
; #pragma unroll
;     for (int i = 0; i < 4; ++i) {
;       const int nsrc0 = upperm ? (((n0s[t] >> 7) & 1) * DFF + 128 * (n0s[t] >> 8) + (n0s[t] & 127)) : n0s[t];
;       const int k = r + 16 * i, n = nsrc0 + c4 * 4;
;       v[t][i] = make_float4(0.f, 0.f, 0.f, 0.f);
;       if (n < tN) v[t][i] = *(const float4*)(tsrc + (size_t)(k0s[t] + k) * tN + n);
;       if (gk) { const float gs = gk[k0s[t] + k]; v[t][i].x *= gs; v[t][i].y *= gs; v[t][i].z *= gs; v[t][i].w *= gs; }
.LBB0_144:
	v_mov_b32_e32 v39, v38
	v_mov_b64_e32 v[16:17], v[38:39]
	v_mov_b64_e32 v[14:15], v[38:39]
	s_and_saveexec_b64 vcc, s[6:7]
	s_cbranch_execz .LBB0_146
	v_or_b32_e32 v14, v34, v151
	v_mul_lo_u32 v14, v14, s30
	v_readlane_b32 s56, v253, 2
	v_ashrrev_i32_e32 v15, 31, v14
	v_readlane_b32 s68, v253, 14
	v_readlane_b32 s69, v253, 15
	v_readlane_b32 s57, v253, 3
	v_readlane_b32 s58, v253, 4
	v_lshl_add_u64 v[14:15], v[14:15], 2, s[68:69]
	v_lshl_add_u64 v[14:15], v[18:19], 2, v[14:15]
	global_load_dwordx4 v[14:17], v[14:15], off nt
	v_readlane_b32 s59, v253, 5
	v_readlane_b32 s60, v253, 6
	v_readlane_b32 s61, v253, 7
	v_readlane_b32 s62, v253, 8
	v_readlane_b32 s63, v253, 9
	v_readlane_b32 s64, v253, 10
	v_readlane_b32 s65, v253, 11
	v_readlane_b32 s66, v253, 12
	v_readlane_b32 s67, v253, 13
	v_readlane_b32 s70, v253, 16
	v_readlane_b32 s71, v253, 17

; __device__ __forceinline__ void transpose_tile2(const float* tsrc, u16* tdst, int tK, int tN, int tNpad, int tile, u16* sm, const bool rp0 = false, const bool rp1 = false, const bool upperm = false, const float* gk = nullptr) {
;     ...
; #pragma unroll
;     for (int i = 0; i < 4; ++i) {
;       const int nsrc0 = upperm ? (((n0s[t] >> 7) & 1) * DFF + 128 * (n0s[t] >> 8) + (n0s[t] & 127)) : n0s[t];
;       const int k = r + 16 * i, n = nsrc0 + c4 * 4;
;       v[t][i] = make_float4(0.f, 0.f, 0.f, 0.f);
;       if (n < tN) v[t][i] = *(const float4*)(tsrc + (size_t)(k0s[t] + k) * tN + n);
;       if (gk) { const float gs = gk[k0s[t] + k]; v[t][i].x *= gs; v[t][i].y *= gs; v[t][i].z *= gs; v[t][i].w *= gs; }
.LBB0_148:
	v_add_u32_e32 v18, 0xfffff901, v119
	s_mov_b32 s6, 0x2e8ba2e9
	v_mul_hi_i32 v19, v18, s6
	v_lshrrev_b32_e32 v20, 31, v19
	v_ashrrev_i32_e32 v19, 4, v19
	v_add_u32_e32 v19, v19, v20
	s_movk_i32 s6, 0xffa8
	v_mad_u64_u32 v[130:131], s[6:7], v19, s6, v[18:19]
	v_lshlrev_b32_e32 v128, 6, v19
	v_bfe_i32 v18, v18, 1, 1
	v_lshlrev_b32_e32 v19, 5, v130
	v_and_b32_e32 v18, 0xb00, v18
	v_and_b32_e32 v19, 0xffffff80, v19
	v_add_u32_e32 v132, v19, v18
	v_or_b32_e32 v18, v132, v160
	v_mov_b32_e32 v39, v38
	v_cmp_gt_i32_e64 s[6:7], s30, v18
	v_ashrrev_i32_e32 v133, 31, v132
	v_or_b32_e32 v22, v128, v40
	v_mov_b64_e32 v[20:21], v[38:39]
	v_mov_b64_e32 v[18:19], v[38:39]
	s_and_saveexec_b64 vcc, s[6:7]
	s_cbranch_execz .LBB0_150
	v_mul_lo_u32 v18, v22, s30
	v_readlane_b32 s56, v253, 2
	v_ashrrev_i32_e32 v19, 31, v18
	v_readlane_b32 s68, v253, 14
	v_readlane_b32 s69, v253, 15
	v_lshl_add_u64 v[20:21], v[132:133], 0, v[42:43]
	v_readlane_b32 s57, v253, 3
	v_lshl_add_u64 v[18:19], v[18:19], 2, s[68:69]
	v_lshl_add_u64 v[18:19], v[20:21], 2, v[18:19]
	global_load_dwordx4 v[18:21], v[18:19], off offset:256 nt
	v_readlane_b32 s58, v253, 4
	v_readlane_b32 s59, v253, 5
	v_readlane_b32 s60, v253, 6
	v_readlane_b32 s61, v253, 7
	v_readlane_b32 s62, v253, 8
	v_readlane_b32 s63, v253, 9
	v_readlane_b32 s64, v253, 10
	v_readlane_b32 s65, v253, 11
	v_readlane_b32 s66, v253, 12
	v_readlane_b32 s67, v253, 13
	v_readlane_b32 s70, v253, 16
	v_readlane_b32 s71, v253, 17

; __device__ __forceinline__ void transpose_tile2(const float* tsrc, u16* tdst, int tK, int tN, int tNpad, int tile, u16* sm, const bool rp0 = false, const bool rp1 = false, const bool upperm = false, const float* gk = nullptr) {
;     ...
; #pragma unroll
;     for (int i = 0; i < 4; ++i) {
;       const int nsrc0 = upperm ? (((n0s[t] >> 7) & 1) * DFF + 128 * (n0s[t] >> 8) + (n0s[t] & 127)) : n0s[t];
;       const int k = r + 16 * i, n = nsrc0 + c4 * 4;
;       v[t][i] = make_float4(0.f, 0.f, 0.f, 0.f);
;       if (n < tN) v[t][i] = *(const float4*)(tsrc + (size_t)(k0s[t] + k) * tN + n);
;       if (gk) { const float gs = gk[k0s[t] + k]; v[t][i].x *= gs; v[t][i].y *= gs; v[t][i].z *= gs; v[t][i].w *= gs; }
.LBB0_152:
	v_mov_b32_e32 v39, v38
	v_mov_b64_e32 v[24:25], v[38:39]
	v_mov_b64_e32 v[22:23], v[38:39]
	s_and_saveexec_b64 vcc, s[6:7]
	s_cbranch_execz .LBB0_154
	v_or_b32_e32 v22, v128, v149
	v_mul_lo_u32 v22, v22, s30
	v_readlane_b32 s56, v253, 2
	v_ashrrev_i32_e32 v23, 31, v22
	v_readlane_b32 s68, v253, 14
	v_readlane_b32 s69, v253, 15
	v_lshl_add_u64 v[24:25], v[132:133], 0, v[42:43]
	v_readlane_b32 s57, v253, 3
	v_lshl_add_u64 v[22:23], v[22:23], 2, s[68:69]
	v_lshl_add_u64 v[22:23], v[24:25], 2, v[22:23]
	global_load_dwordx4 v[22:25], v[22:23], off offset:256 nt
	v_readlane_b32 s58, v253, 4
	v_readlane_b32 s59, v253, 5
	v_readlane_b32 s60, v253, 6
	v_readlane_b32 s61, v253, 7
	v_readlane_b32 s62, v253, 8
	v_readlane_b32 s63, v253, 9
	v_readlane_b32 s64, v253, 10
	v_readlane_b32 s65, v253, 11
	v_readlane_b32 s66, v253, 12
	v_readlane_b32 s67, v253, 13
	v_readlane_b32 s70, v253, 16
	v_readlane_b32 s71, v253, 17

; __device__ __forceinline__ void transpose_tile2(const float* tsrc, u16* tdst, int tK, int tN, int tNpad, int tile, u16* sm, const bool rp0 = false, const bool rp1 = false, const bool upperm = false, const float* gk = nullptr) {
;     ...
; #pragma unroll
;     for (int i = 0; i < 4; ++i) {
;       const int nsrc0 = upperm ? (((n0s[t] >> 7) & 1) * DFF + 128 * (n0s[t] >> 8) + (n0s[t] & 127)) : n0s[t];
;       const int k = r + 16 * i, n = nsrc0 + c4 * 4;
;       v[t][i] = make_float4(0.f, 0.f, 0.f, 0.f);
;       if (n < tN) v[t][i] = *(const float4*)(tsrc + (size_t)(k0s[t] + k) * tN + n);
;       if (gk) { const float gs = gk[k0s[t] + k]; v[t][i].x *= gs; v[t][i].y *= gs; v[t][i].z *= gs; v[t][i].w *= gs; }
.LBB0_156:
	v_mov_b32_e32 v39, v38
	v_mov_b64_e32 v[28:29], v[38:39]
	v_mov_b64_e32 v[26:27], v[38:39]
	s_and_saveexec_b64 vcc, s[6:7]
	s_cbranch_execz .LBB0_158
	v_or_b32_e32 v26, v128, v150
	v_mul_lo_u32 v26, v26, s30
	v_readlane_b32 s56, v253, 2
	v_ashrrev_i32_e32 v27, 31, v26
	v_readlane_b32 s68, v253, 14
	v_readlane_b32 s69, v253, 15
	v_lshl_add_u64 v[28:29], v[132:133], 0, v[42:43]
	v_readlane_b32 s57, v253, 3
	v_lshl_add_u64 v[26:27], v[26:27], 2, s[68:69]
	v_lshl_add_u64 v[26:27], v[28:29], 2, v[26:27]
	global_load_dwordx4 v[26:29], v[26:27], off offset:256 nt
	v_readlane_b32 s58, v253, 4
	v_readlane_b32 s59, v253, 5
	v_readlane_b32 s60, v253, 6
	v_readlane_b32 s61, v253, 7
	v_readlane_b32 s62, v253, 8
	v_readlane_b32 s63, v253, 9
	v_readlane_b32 s64, v253, 10
	v_readlane_b32 s65, v253, 11
	v_readlane_b32 s66, v253, 12
	v_readlane_b32 s67, v253, 13
	v_readlane_b32 s70, v253, 16
	v_readlane_b32 s71, v253, 17

; __device__ __forceinline__ void transpose_tile2(const float* tsrc, u16* tdst, int tK, int tN, int tNpad, int tile, u16* sm, const bool rp0 = false, const bool rp1 = false, const bool upperm = false, const float* gk = nullptr) {
;     ...
; #pragma unroll
;     for (int i = 0; i < 4; ++i) {
;       const int nsrc0 = upperm ? (((n0s[t] >> 7) & 1) * DFF + 128 * (n0s[t] >> 8) + (n0s[t] & 127)) : n0s[t];
;       const int k = r + 16 * i, n = nsrc0 + c4 * 4;
;       v[t][i] = make_float4(0.f, 0.f, 0.f, 0.f);
;       if (n < tN) v[t][i] = *(const float4*)(tsrc + (size_t)(k0s[t] + k) * tN + n);
;       if (gk) { const float gs = gk[k0s[t] + k]; v[t][i].x *= gs; v[t][i].y *= gs; v[t][i].z *= gs; v[t][i].w *= gs; }
.LBB0_160:
	v_mov_b32_e32 v39, v38
	v_mov_b64_e32 v[32:33], v[38:39]
	v_mov_b64_e32 v[30:31], v[38:39]
	s_and_saveexec_b64 s[4:5], s[6:7]
	s_cbranch_execz .LBB0_162
	v_or_b32_e32 v30, v128, v151
	v_mul_lo_u32 v30, v30, s30
	v_readlane_b32 s56, v253, 2
	v_ashrrev_i32_e32 v31, 31, v30
	v_readlane_b32 s68, v253, 14
	v_readlane_b32 s69, v253, 15
	v_lshl_add_u64 v[32:33], v[132:133], 0, v[42:43]
	v_readlane_b32 s57, v253, 3
	v_lshl_add_u64 v[30:31], v[30:31], 2, s[68:69]
	v_lshl_add_u64 v[30:31], v[32:33], 2, v[30:31]
	global_load_dwordx4 v[30:33], v[30:31], off offset:256 nt
	v_readlane_b32 s58, v253, 4
	v_readlane_b32 s59, v253, 5
	v_readlane_b32 s60, v253, 6
	v_readlane_b32 s61, v253, 7
	v_readlane_b32 s62, v253, 8
	v_readlane_b32 s63, v253, 9
	v_readlane_b32 s64, v253, 10
	v_readlane_b32 s65, v253, 11
	v_readlane_b32 s66, v253, 12
	v_readlane_b32 s67, v253, 13
	v_readlane_b32 s70, v253, 16
	v_readlane_b32 s71, v253, 17

; __device__ __forceinline__ void transpose_tile2(const float* tsrc, u16* tdst, int tK, int tN, int tNpad, int tile, u16* sm, const bool rp0 = false, const bool rp1 = false, const bool upperm = false, const float* gk = nullptr) {
;     ...
; #pragma unroll
;     for (int i = 0; i < 4; ++i) {
;       const int nsrc0 = upperm ? (((n0s[t] >> 7) & 1) * DFF + 128 * (n0s[t] >> 8) + (n0s[t] & 127)) : n0s[t];
;       const int k = r + 16 * i, n = nsrc0 + c4 * 4;
;       v[t][i] = make_float4(0.f, 0.f, 0.f, 0.f);
;       if (n < tN) v[t][i] = *(const float4*)(tsrc + (size_t)(k0s[t] + k) * tN + n);
;       if (gk) { const float gs = gk[k0s[t] + k]; v[t][i].x *= gs; v[t][i].y *= gs; v[t][i].z *= gs; v[t][i].w *= gs; }
;     }
;   }
; #pragma unroll
;   for (int t = 0; t < 2; ++t)
; #pragma unroll
;     for (int i = 0; i < 4; ++i) {
;       const int k = r + 16 * i;
;       u16* d = sm + t * 64 * LDSP;
;       const uint32_t p01 = pack2(v[t][i].x, v[t][i].y), p23 = pack2(v[t][i].z, v[t][i].w);
.LBB0_169:
	s_andn2_saveexec_b64 s[4:5], s[40:41]
	s_cbranch_execz .LBB0_187
	v_add_u32_e32 v3, 0xfffffa00, v119
	v_ashrrev_i32_e32 v2, 31, v3
	v_lshrrev_b32_e32 v2, 28, v2
	v_add_u32_e32 v2, v3, v2
	v_ashrrev_i32_e32 v4, 4, v2
	v_lshlrev_b32_e32 v2, 6, v4
	v_lshlrev_b32_e32 v4, 10, v4
	v_lshlrev_b32_e32 v3, 6, v3
	v_sub_u32_e32 v8, v3, v4
	v_or_b32_e32 v4, v8, v42
	v_cmp_gt_i32_e32 vcc, s84, v4
	v_mov_b32_e32 v3, 0
	v_ashrrev_i32_e32 v5, 31, v4
	v_mov_b32_e32 v9, 0
	v_mov_b32_e32 v10, 0
	s_and_saveexec_b64 s[6:7], vcc
	s_cbranch_execz .LBB0_172
	v_or_b32_e32 v6, v2, v40
	v_ashrrev_i32_e32 v7, 31, v6
	v_readlane_b32 s52, v253, 2
	v_lshlrev_b64 v[6:7], 12, v[6:7]
	v_readlane_b32 s60, v253, 10
	v_readlane_b32 s61, v253, 11
	v_readlane_b32 s56, v253, 6
	v_readlane_b32 s57, v253, 7
	v_lshl_add_u64 v[6:7], s[60:61], 0, v[6:7]
	v_lshl_add_u64 v[6:7], v[4:5], 2, v[6:7]
	global_load_dwordx4 v[10:13], v[6:7], off nt
	v_readlane_b32 s58, v253, 8
	v_readlane_b32 s59, v253, 9
	v_readlane_b32 s62, v253, 12
	v_readlane_b32 s63, v253, 13
	v_readlane_b32 s64, v253, 14
	v_readlane_b32 s65, v253, 15
	v_readlane_b32 s64, v253, 40
	v_readlane_b32 s56, v253, 32
	v_readlane_b32 s65, v253, 41
	v_readlane_b32 s58, v253, 34
	v_readlane_b32 s59, v253, 35
	v_readlane_b32 s53, v253, 3
	v_readlane_b32 s54, v253, 4
	v_readlane_b32 s55, v253, 5
	v_readlane_b32 s66, v253, 16
	v_readlane_b32 s67, v253, 17
	v_readlane_b32 s57, v253, 33
	v_readlane_b32 s60, v253, 36
	v_readlane_b32 s61, v253, 37
	v_readlane_b32 s62, v253, 38
	v_readlane_b32 s63, v253, 39
	s_waitcnt vmcnt(0)
	v_cvt_pk_bf16_f32 v10, v10, v11
	v_cvt_pk_bf16_f32 v9, v12, v13
.LBB0_172:
	s_or_b64 exec, exec, s[6:7]
	v_mov_b32_e32 v11, 0
	s_and_saveexec_b64 s[6:7], vcc
	s_cbranch_execz .LBB0_174
	v_or_b32_e32 v6, v2, v149
	v_ashrrev_i32_e32 v7, 31, v6
	v_readlane_b32 s52, v253, 2
	v_lshlrev_b64 v[6:7], 12, v[6:7]
	v_readlane_b32 s60, v253, 10
	v_readlane_b32 s61, v253, 11
	v_readlane_b32 s56, v253, 6
	v_readlane_b32 s57, v253, 7
	v_lshl_add_u64 v[6:7], s[60:61], 0, v[6:7]
	v_lshl_add_u64 v[6:7], v[4:5], 2, v[6:7]
	global_load_dwordx4 v[12:15], v[6:7], off nt
	v_readlane_b32 s58, v253, 8
	v_readlane_b32 s59, v253, 9
	v_readlane_b32 s62, v253, 12
	v_readlane_b32 s63, v253, 13
	v_readlane_b32 s64, v253, 14
	v_readlane_b32 s65, v253, 15
	v_readlane_b32 s64, v253, 40
	v_readlane_b32 s56, v253, 32
	v_readlane_b32 s65, v253, 41
	v_readlane_b32 s58, v253, 34
	v_readlane_b32 s59, v253, 35
	v_readlane_b32 s53, v253, 3
	v_readlane_b32 s54, v253, 4
	v_readlane_b32 s55, v253, 5
	v_readlane_b32 s66, v253, 16
	v_readlane_b32 s67, v253, 17
	v_readlane_b32 s57, v253, 33
	v_readlane_b32 s60, v253, 36
	v_readlane_b32 s61, v253, 37
	v_readlane_b32 s62, v253, 38
	v_readlane_b32 s63, v253, 39
	s_waitcnt vmcnt(0)
	v_cvt_pk_bf16_f32 v11, v12, v13
	v_cvt_pk_bf16_f32 v3, v14, v15
.LBB0_174:
	s_or_b64 exec, exec, s[6:7]
	v_mov_b32_e32 v12, 0
	v_mov_b32_e32 v13, 0
	v_mov_b32_e32 v14, 0
	s_and_saveexec_b64 s[6:7], vcc
	s_cbranch_execz .LBB0_176
	v_or_b32_e32 v6, v2, v150
	v_ashrrev_i32_e32 v7, 31, v6
	v_readlane_b32 s52, v253, 2
	v_lshlrev_b64 v[6:7], 12, v[6:7]
	v_readlane_b32 s60, v253, 10
	v_readlane_b32 s61, v253, 11
	v_readlane_b32 s56, v253, 6
	v_readlane_b32 s57, v253, 7
	v_lshl_add_u64 v[6:7], s[60:61], 0, v[6:7]
	v_lshl_add_u64 v[6:7], v[4:5], 2, v[6:7]
	global_load_dwordx4 v[14:17], v[6:7], off nt
	v_readlane_b32 s58, v253, 8
	v_readlane_b32 s59, v253, 9
	v_readlane_b32 s62, v253, 12
	v_readlane_b32 s63, v253, 13
	v_readlane_b32 s64, v253, 14
	v_readlane_b32 s65, v253, 15
	v_readlane_b32 s64, v253, 40
	v_readlane_b32 s56, v253, 32
	v_readlane_b32 s65, v253, 41
	v_readlane_b32 s58, v253, 34
	v_readlane_b32 s59, v253, 35
	v_readlane_b32 s53, v253, 3
	v_readlane_b32 s54, v253, 4
	v_readlane_b32 s55, v253, 5
	v_readlane_b32 s66, v253, 16
	v_readlane_b32 s67, v253, 17
	v_readlane_b32 s57, v253, 33
	v_readlane_b32 s60, v253, 36
	v_readlane_b32 s61, v253, 37
	v_readlane_b32 s62, v253, 38
	v_readlane_b32 s63, v253, 39
	s_waitcnt vmcnt(0)
	v_cvt_pk_bf16_f32 v14, v14, v15
	v_cvt_pk_bf16_f32 v13, v16, v17
.LBB0_176:
	s_or_b64 exec, exec, s[6:7]
	v_mov_b32_e32 v16, 0
	s_and_saveexec_b64 s[6:7], vcc
	s_cbranch_execz .LBB0_178
	v_or_b32_e32 v6, v2, v151
	v_ashrrev_i32_e32 v7, 31, v6
	v_readlane_b32 s52, v253, 2
	v_lshlrev_b64 v[6:7], 12, v[6:7]
	v_readlane_b32 s60, v253, 10
	v_readlane_b32 s61, v253, 11
	v_readlane_b32 s56, v253, 6
	v_readlane_b32 s57, v253, 7
	v_lshl_add_u64 v[6:7], s[60:61], 0, v[6:7]
	v_lshl_add_u64 v[4:5], v[4:5], 2, v[6:7]
	global_load_dwordx4 v[4:7], v[4:5], off nt
	v_readlane_b32 s58, v253, 8
	v_readlane_b32 s59, v253, 9
	v_readlane_b32 s62, v253, 12
	v_readlane_b32 s63, v253, 13
	v_readlane_b32 s64, v253, 14
	v_readlane_b32 s65, v253, 15
	v_readlane_b32 s64, v253, 40
	v_readlane_b32 s56, v253, 32
	v_readlane_b32 s65, v253, 41
	v_readlane_b32 s58, v253, 34
	v_readlane_b32 s59, v253, 35
	v_readlane_b32 s53, v253, 3
	v_readlane_b32 s54, v253, 4
	v_readlane_b32 s55, v253, 5
	v_readlane_b32 s66, v253, 16
	v_readlane_b32 s67, v253, 17
	v_readlane_b32 s57, v253, 33
	v_readlane_b32 s60, v253, 36
	v_readlane_b32 s61, v253, 37
	v_readlane_b32 s62, v253, 38
	v_readlane_b32 s63, v253, 39
	s_waitcnt vmcnt(0)
	v_cvt_pk_bf16_f32 v16, v4, v5
	v_cvt_pk_bf16_f32 v12, v6, v7
; __device__ __forceinline__ void transpose_tile2(const float* tsrc, u16* tdst, int tK, int tN, int tNpad, int tile, u16* sm, const bool rp0 = false, const bool rp1 = false, const bool upperm = false, const float* gk = nullptr) {
;     ...
; #pragma unroll
;     for (int i = 0; i < 4; ++i) {
;       const int nsrc0 = upperm ? (((n0s[t] >> 7) & 1) * DFF + 128 * (n0s[t] >> 8) + (n0s[t] & 127)) : n0s[t];
;       const int k = r + 16 * i, n = nsrc0 + c4 * 4;
;       v[t][i] = make_float4(0.f, 0.f, 0.f, 0.f);
;       if (n < tN) v[t][i] = *(const float4*)(tsrc + (size_t)(k0s[t] + k) * tN + n);
;       if (gk) { const float gs = gk[k0s[t] + k]; v[t][i].x *= gs; v[t][i].y *= gs; v[t][i].z *= gs; v[t][i].w *= gs; }
;     }
;   }
; #pragma unroll
;   for (int t = 0; t < 2; ++t)
; #pragma unroll
;     for (int i = 0; i < 4; ++i) {
;       const int k = r + 16 * i;
;       u16* d = sm + t * 64 * LDSP;
;       const uint32_t p01 = pack2(v[t][i].x, v[t][i].y), p23 = pack2(v[t][i].z, v[t][i].w);
.LBB0_178:
	s_or_b64 exec, exec, s[6:7]
	v_add_u32_e32 v5, 0xfffffa01, v119
	v_ashrrev_i32_e32 v4, 31, v5
	v_lshrrev_b32_e32 v4, 28, v4
	v_add_u32_e32 v4, v5, v4
	v_ashrrev_i32_e32 v6, 4, v4
	v_lshlrev_b32_e32 v4, 6, v6
	v_lshlrev_b32_e32 v6, 10, v6
	v_lshlrev_b32_e32 v5, 6, v5
	v_sub_u32_e32 v15, v5, v6
	v_or_b32_e32 v6, v15, v42
	v_cmp_gt_i32_e32 vcc, s84, v6
	v_mov_b32_e32 v5, 0
	v_ashrrev_i32_e32 v7, 31, v6
	v_mov_b32_e32 v17, 0
	v_mov_b32_e32 v18, 0
	s_and_saveexec_b64 s[6:7], vcc
	s_cbranch_execz .LBB0_180
	v_or_b32_e32 v18, v4, v40
	v_ashrrev_i32_e32 v19, 31, v18
	v_readlane_b32 s52, v253, 2
	v_lshlrev_b64 v[18:19], 12, v[18:19]
	v_readlane_b32 s60, v253, 10
	v_readlane_b32 s61, v253, 11
	v_readlane_b32 s56, v253, 6
	v_readlane_b32 s57, v253, 7
	v_lshl_add_u64 v[18:19], s[60:61], 0, v[18:19]
	v_lshl_add_u64 v[18:19], v[6:7], 2, v[18:19]
	global_load_dwordx4 v[18:21], v[18:19], off nt
	v_readlane_b32 s58, v253, 8
	v_readlane_b32 s59, v253, 9
	v_readlane_b32 s62, v253, 12
	v_readlane_b32 s63, v253, 13
	v_readlane_b32 s64, v253, 14
	v_readlane_b32 s65, v253, 15
	v_readlane_b32 s64, v253, 40
	v_readlane_b32 s56, v253, 32
	v_readlane_b32 s65, v253, 41
	v_readlane_b32 s58, v253, 34
	v_readlane_b32 s59, v253, 35
	v_readlane_b32 s53, v253, 3
	v_readlane_b32 s54, v253, 4
	v_readlane_b32 s55, v253, 5
	v_readlane_b32 s66, v253, 16
	v_readlane_b32 s67, v253, 17
	v_readlane_b32 s57, v253, 33
	v_readlane_b32 s60, v253, 36
	v_readlane_b32 s61, v253, 37
	v_readlane_b32 s62, v253, 38
	v_readlane_b32 s63, v253, 39
	s_waitcnt vmcnt(0)
	v_cvt_pk_bf16_f32 v18, v18, v19
	v_cvt_pk_bf16_f32 v17, v20, v21
.LBB0_180:
	s_or_b64 exec, exec, s[6:7]
	v_mov_b32_e32 v19, 0
	s_and_saveexec_b64 s[6:7], vcc
	s_cbranch_execz .LBB0_182
	v_or_b32_e32 v20, v4, v149
	v_ashrrev_i32_e32 v21, 31, v20
	v_readlane_b32 s52, v253, 2
	v_lshlrev_b64 v[20:21], 12, v[20:21]
	v_readlane_b32 s60, v253, 10
	v_readlane_b32 s61, v253, 11
	v_readlane_b32 s56, v253, 6
	v_readlane_b32 s57, v253, 7
	v_lshl_add_u64 v[20:21], s[60:61], 0, v[20:21]
	v_lshl_add_u64 v[20:21], v[6:7], 2, v[20:21]
	global_load_dwordx4 v[20:23], v[20:21], off nt
	v_readlane_b32 s58, v253, 8
	v_readlane_b32 s59, v253, 9
	v_readlane_b32 s62, v253, 12
	v_readlane_b32 s63, v253, 13
	v_readlane_b32 s64, v253, 14
	v_readlane_b32 s65, v253, 15
	v_readlane_b32 s64, v253, 40
	v_readlane_b32 s56, v253, 32
	v_readlane_b32 s65, v253, 41
	v_readlane_b32 s58, v253, 34
	v_readlane_b32 s59, v253, 35
	v_readlane_b32 s53, v253, 3
	v_readlane_b32 s54, v253, 4
	v_readlane_b32 s55, v253, 5
	v_readlane_b32 s66, v253, 16
	v_readlane_b32 s67, v253, 17
	v_readlane_b32 s57, v253, 33
	v_readlane_b32 s60, v253, 36
	v_readlane_b32 s61, v253, 37
	v_readlane_b32 s62, v253, 38
	v_readlane_b32 s63, v253, 39
	s_waitcnt vmcnt(0)
	v_cvt_pk_bf16_f32 v19, v20, v21
	v_cvt_pk_bf16_f32 v5, v22, v23
.LBB0_182:
	s_or_b64 exec, exec, s[6:7]
	v_mov_b32_e32 v20, 0
	v_mov_b32_e32 v21, 0
	v_mov_b32_e32 v22, 0
	s_and_saveexec_b64 s[6:7], vcc
	s_cbranch_execz .LBB0_184
	v_or_b32_e32 v22, v4, v150
	v_ashrrev_i32_e32 v23, 31, v22
	v_readlane_b32 s52, v253, 2
	v_lshlrev_b64 v[22:23], 12, v[22:23]
	v_readlane_b32 s60, v253, 10
	v_readlane_b32 s61, v253, 11
	v_readlane_b32 s56, v253, 6
	v_readlane_b32 s57, v253, 7
	v_lshl_add_u64 v[22:23], s[60:61], 0, v[22:23]
	v_lshl_add_u64 v[22:23], v[6:7], 2, v[22:23]
	global_load_dwordx4 v[22:25], v[22:23], off nt
	v_readlane_b32 s58, v253, 8
	v_readlane_b32 s59, v253, 9
	v_readlane_b32 s62, v253, 12
	v_readlane_b32 s63, v253, 13
	v_readlane_b32 s64, v253, 14
	v_readlane_b32 s65, v253, 15
	v_readlane_b32 s64, v253, 40
	v_readlane_b32 s56, v253, 32
	v_readlane_b32 s65, v253, 41
	v_readlane_b32 s58, v253, 34
	v_readlane_b32 s59, v253, 35
	v_readlane_b32 s53, v253, 3
	v_readlane_b32 s54, v253, 4
	v_readlane_b32 s55, v253, 5
	v_readlane_b32 s66, v253, 16
	v_readlane_b32 s67, v253, 17
	v_readlane_b32 s57, v253, 33
	v_readlane_b32 s60, v253, 36
	v_readlane_b32 s61, v253, 37
	v_readlane_b32 s62, v253, 38
	v_readlane_b32 s63, v253, 39
	s_waitcnt vmcnt(0)
	v_cvt_pk_bf16_f32 v22, v22, v23
	v_cvt_pk_bf16_f32 v21, v24, v25
.LBB0_184:
	s_or_b64 exec, exec, s[6:7]
	v_mov_b32_e32 v23, 0
	s_and_saveexec_b64 s[6:7], vcc
	s_cbranch_execz .LBB0_186
	v_or_b32_e32 v24, v4, v151
	v_ashrrev_i32_e32 v25, 31, v24
	v_readlane_b32 s52, v253, 2
	v_lshlrev_b64 v[24:25], 12, v[24:25]
	v_readlane_b32 s60, v253, 10
	v_readlane_b32 s61, v253, 11
	v_readlane_b32 s56, v253, 6
	v_readlane_b32 s57, v253, 7
	v_lshl_add_u64 v[24:25], s[60:61], 0, v[24:25]
	v_lshl_add_u64 v[6:7], v[6:7], 2, v[24:25]
	global_load_dwordx4 v[24:27], v[6:7], off nt
	v_readlane_b32 s58, v253, 8
	v_readlane_b32 s59, v253, 9
	v_readlane_b32 s62, v253, 12
	v_readlane_b32 s63, v253, 13
	v_readlane_b32 s64, v253, 14
	v_readlane_b32 s65, v253, 15
	v_readlane_b32 s64, v253, 40
	v_readlane_b32 s56, v253, 32
	v_readlane_b32 s65, v253, 41
	v_readlane_b32 s58, v253, 34
	v_readlane_b32 s59, v253, 35
	v_readlane_b32 s53, v253, 3
	v_readlane_b32 s54, v253, 4
	v_readlane_b32 s55, v253, 5
	v_readlane_b32 s66, v253, 16
	v_readlane_b32 s67, v253, 17
	v_readlane_b32 s57, v253, 33
	v_readlane_b32 s60, v253, 36
	v_readlane_b32 s61, v253, 37
	v_readlane_b32 s62, v253, 38
	v_readlane_b32 s63, v253, 39
	s_waitcnt vmcnt(0)
	v_cvt_pk_bf16_f32 v23, v24, v25
	v_cvt_pk_bf16_f32 v20, v26, v27

; __device__ __forceinline__ void transpose_tile2(const float* tsrc, u16* tdst, int tK, int tN, int tNpad, int tile, u16* sm, const bool rp0 = false, const bool rp1 = false, const bool upperm = false, const float* gk = nullptr) {
;     ...
; #pragma unroll
;     for (int i = 0; i < 4; ++i) {
;       const int nsrc0 = upperm ? (((n0s[t] >> 7) & 1) * DFF + 128 * (n0s[t] >> 8) + (n0s[t] & 127)) : n0s[t];
;       const int k = r + 16 * i, n = nsrc0 + c4 * 4;
;       v[t][i] = make_float4(0.f, 0.f, 0.f, 0.f);
;       if (n < tN) v[t][i] = *(const float4*)(tsrc + (size_t)(k0s[t] + k) * tN + n);
;       if (gk) { const float gs = gk[k0s[t] + k]; v[t][i].x *= gs; v[t][i].y *= gs; v[t][i].z *= gs; v[t][i].w *= gs; }
.LBB0_188:
	s_andn2_saveexec_b64 s[40:41], s[50:51]
	s_cbranch_execz .LBB0_206
	v_add_u32_e32 v2, 0xfffffc00, v119
	v_ashrrev_i32_e32 v3, 31, v2
	v_lshrrev_b32_e32 v3, 27, v3
	v_add_u32_e32 v3, v2, v3
	v_ashrrev_i32_e32 v3, 5, v3
	v_lshlrev_b32_e32 v34, 6, v3
	v_lshlrev_b32_e32 v3, 11, v3
	v_lshlrev_b32_e32 v2, 6, v2
	v_sub_u32_e32 v37, v2, v3
	v_or_b32_e32 v18, v37, v42
	v_cmp_gt_i32_e32 vcc, s29, v18
	v_or_b32_e32 v6, v34, v40
	v_mov_b32_e32 v8, 0
	v_ashrrev_i32_e32 v19, 31, v18
	v_mov_b32_e32 v4, 0
	v_mov_b32_e32 v5, 0
	v_mov_b32_e32 v2, 0
	v_mov_b32_e32 v3, 0
	s_and_saveexec_b64 s[4:5], vcc
	s_cbranch_execz .LBB0_191
	v_mul_lo_u32 v2, v6, s29
	v_ashrrev_i32_e32 v3, 31, v2
	v_lshl_add_u64 v[2:3], v[2:3], 2, s[22:23]
	v_lshl_add_u64 v[2:3], v[18:19], 2, v[2:3]
	global_load_dwordx4 v[2:5], v[2:3], off nt
.LBB0_191:
	s_or_b64 exec, exec, s[4:5]
	v_ashrrev_i32_e32 v7, 31, v6
	v_lshl_add_u64 v[6:7], v[6:7], 2, s[16:17]
	global_load_dword v128, v[6:7], off
	v_or_b32_e32 v10, v34, v149
	v_mov_b32_e32 v9, 0
	v_mov_b32_e32 v6, 0
	v_mov_b32_e32 v7, 0
	s_and_saveexec_b64 s[4:5], vcc
	s_cbranch_execz .LBB0_193
	v_mul_lo_u32 v6, v10, s29
	v_ashrrev_i32_e32 v7, 31, v6
	v_lshl_add_u64 v[6:7], v[6:7], 2, s[22:23]
	v_lshl_add_u64 v[6:7], v[18:19], 2, v[6:7]
	global_load_dwordx4 v[6:9], v[6:7], off nt
.LBB0_193:
	s_or_b64 exec, exec, s[4:5]
	v_ashrrev_i32_e32 v11, 31, v10
	v_lshl_add_u64 v[10:11], v[10:11], 2, s[16:17]
	global_load_dword v130, v[10:11], off
	v_or_b32_e32 v14, v34, v150
	v_mov_b32_e32 v16, 0
	v_mov_b32_e32 v12, 0
	v_mov_b32_e32 v13, 0
	v_mov_b32_e32 v10, 0
	v_mov_b32_e32 v11, 0
	s_and_saveexec_b64 s[4:5], vcc
	s_cbranch_execz .LBB0_195
	v_mul_lo_u32 v10, v14, s29
	v_ashrrev_i32_e32 v11, 31, v10
	v_lshl_add_u64 v[10:11], v[10:11], 2, s[22:23]
	v_lshl_add_u64 v[10:11], v[18:19], 2, v[10:11]
	global_load_dwordx4 v[10:13], v[10:11], off nt
.LBB0_195:
	s_or_b64 exec, exec, s[4:5]
	v_ashrrev_i32_e32 v15, 31, v14
	v_lshl_add_u64 v[14:15], v[14:15], 2, s[16:17]
	global_load_dword v132, v[14:15], off
	v_or_b32_e32 v20, v34, v151
	v_mov_b32_e32 v17, 0
	v_mov_b32_e32 v14, 0
	v_mov_b32_e32 v15, 0
	s_and_saveexec_b64 s[4:5], vcc
	s_cbranch_execz .LBB0_197
	v_mul_lo_u32 v14, v20, s29
	v_ashrrev_i32_e32 v15, 31, v14
	v_lshl_add_u64 v[14:15], v[14:15], 2, s[22:23]
	v_lshl_add_u64 v[14:15], v[18:19], 2, v[14:15]
	global_load_dwordx4 v[14:17], v[14:15], off nt
.LBB0_197:
	s_or_b64 exec, exec, s[4:5]
	v_ashrrev_i32_e32 v21, 31, v20
	v_lshl_add_u64 v[18:19], v[20:21], 2, s[16:17]
	global_load_dword v134, v[18:19], off
	v_add_u32_e32 v18, 0xfffffc01, v119
	v_ashrrev_i32_e32 v19, 31, v18
	v_lshrrev_b32_e32 v19, 27, v19
	v_add_u32_e32 v19, v18, v19
	v_ashrrev_i32_e32 v19, 5, v19
	v_lshlrev_b32_e32 v36, 6, v19
	v_lshlrev_b32_e32 v19, 11, v19
	v_lshlrev_b32_e32 v18, 6, v18
	v_sub_u32_e32 v39, v18, v19
	v_or_b32_e32 v138, v39, v42
	v_cmp_gt_i32_e32 vcc, s29, v138
	v_or_b32_e32 v18, v36, v40
	v_mov_b32_e32 v28, 0
	v_ashrrev_i32_e32 v139, 31, v138
	v_mov_b32_e32 v24, 0
	v_mov_b32_e32 v25, 0
	v_mov_b32_e32 v22, 0
	v_mov_b32_e32 v23, 0
	s_and_saveexec_b64 s[4:5], vcc
	s_cbranch_execz .LBB0_199
	v_mul_lo_u32 v20, v18, s29
	v_ashrrev_i32_e32 v21, 31, v20
	v_lshl_add_u64 v[20:21], v[20:21], 2, s[22:23]
	v_lshl_add_u64 v[20:21], v[138:139], 2, v[20:21]
	global_load_dwordx4 v[22:25], v[20:21], off nt
.LBB0_199:
	s_or_b64 exec, exec, s[4:5]
	v_ashrrev_i32_e32 v19, 31, v18
	v_lshl_add_u64 v[18:19], v[18:19], 2, s[16:17]
	global_load_dword v140, v[18:19], off
	v_or_b32_e32 v18, v36, v149
	v_mov_b32_e32 v29, 0
	v_mov_b32_e32 v26, 0
	v_mov_b32_e32 v27, 0
	s_and_saveexec_b64 s[4:5], vcc
	s_cbranch_execz .LBB0_201
	v_mul_lo_u32 v20, v18, s29
	v_ashrrev_i32_e32 v21, 31, v20
	v_lshl_add_u64 v[20:21], v[20:21], 2, s[22:23]
	v_lshl_add_u64 v[20:21], v[138:139], 2, v[20:21]
	global_load_dwordx4 v[26:29], v[20:21], off nt
.LBB0_201:
	s_or_b64 exec, exec, s[4:5]
	v_ashrrev_i32_e32 v19, 31, v18
	v_lshl_add_u64 v[18:19], v[18:19], 2, s[16:17]
	global_load_dword v142, v[18:19], off
	v_or_b32_e32 v18, v36, v150
	v_mov_b32_e32 v20, 0
	v_mov_b32_e32 v32, 0
	v_mov_b32_e32 v33, 0
	v_mov_b32_e32 v30, 0
	v_mov_b32_e32 v31, 0
	s_and_saveexec_b64 s[4:5], vcc
	s_cbranch_execz .LBB0_203
	v_mul_lo_u32 v30, v18, s29
	v_ashrrev_i32_e32 v31, 31, v30
	v_lshl_add_u64 v[30:31], v[30:31], 2, s[22:23]
	v_lshl_add_u64 v[30:31], v[138:139], 2, v[30:31]
	global_load_dwordx4 v[30:33], v[30:31], off nt
.LBB0_203:
	s_or_b64 exec, exec, s[4:5]
	v_ashrrev_i32_e32 v19, 31, v18
	v_lshl_add_u64 v[18:19], v[18:19], 2, s[16:17]
	global_load_dword v144, v[18:19], off
	v_or_b32_e32 v136, v36, v151
	v_mov_b32_e32 v21, 0
	v_mov_b32_e32 v18, 0
	v_mov_b32_e32 v19, 0
	s_and_saveexec_b64 s[4:5], vcc
	s_cbranch_execz .LBB0_205
	v_mul_lo_u32 v18, v136, s29
	v_ashrrev_i32_e32 v19, 31, v18
	v_lshl_add_u64 v[18:19], v[18:19], 2, s[22:23]
	v_lshl_add_u64 v[18:19], v[138:139], 2, v[18:19]
	global_load_dwordx4 v[18:21], v[18:19], off nt

; __device__ __forceinline__ void transpose_tile2(const float* tsrc, u16* tdst, int tK, int tN, int tNpad, int tile, u16* sm, const bool rp0 = false, const bool rp1 = false, const bool upperm = false, const float* gk = nullptr) {
;     ...
; #pragma unroll
;     for (int i = 0; i < 4; ++i) {
;       const int nsrc0 = upperm ? (((n0s[t] >> 7) & 1) * DFF + 128 * (n0s[t] >> 8) + (n0s[t] & 127)) : n0s[t];
;       const int k = r + 16 * i, n = nsrc0 + c4 * 4;
;       v[t][i] = make_float4(0.f, 0.f, 0.f, 0.f);
;       if (n < tN) v[t][i] = *(const float4*)(tsrc + (size_t)(k0s[t] + k) * tN + n);
;       if (gk) { const float gs = gk[k0s[t] + k]; v[t][i].x *= gs; v[t][i].y *= gs; v[t][i].z *= gs; v[t][i].w *= gs; }
;     }
;   }
; #pragma unroll
;   for (int t = 0; t < 2; ++t)
; #pragma unroll
;     for (int i = 0; i < 4; ++i) {
;       const int k = r + 16 * i;
;       u16* d = sm + t * 64 * LDSP;
;       const uint32_t p01 = pack2(v[t][i].x, v[t][i].y), p23 = pack2(v[t][i].z, v[t][i].w);
.LBB0_207:
	s_andn2_saveexec_b64 s[4:5], s[38:39]
	s_cbranch_execz .LBB0_225
	v_add_u32_e32 v3, 0xfffffd00, v119
	v_ashrrev_i32_e32 v2, 31, v3
	v_lshrrev_b32_e32 v2, 28, v2
	v_add_u32_e32 v2, v3, v2
	v_ashrrev_i32_e32 v4, 4, v2
	v_lshlrev_b32_e32 v2, 6, v4
	v_lshlrev_b32_e32 v4, 10, v4
	v_lshlrev_b32_e32 v3, 6, v3
	v_sub_u32_e32 v8, v3, v4
	v_or_b32_e32 v4, v8, v42
	v_cmp_gt_i32_e32 vcc, s84, v4
	v_mov_b32_e32 v3, 0
	v_ashrrev_i32_e32 v5, 31, v4
	v_mov_b32_e32 v9, 0
	v_mov_b32_e32 v10, 0
	s_and_saveexec_b64 s[6:7], vcc
	s_cbranch_execz .LBB0_210
	v_or_b32_e32 v6, v2, v40
	v_ashrrev_i32_e32 v7, 31, v6
	v_lshlrev_b64 v[6:7], 12, v[6:7]
	v_lshl_add_u64 v[6:7], s[20:21], 0, v[6:7]
	v_lshl_add_u64 v[6:7], v[4:5], 2, v[6:7]
	global_load_dwordx4 v[10:13], v[6:7], off nt
	s_waitcnt vmcnt(0)
	v_cvt_pk_bf16_f32 v10, v10, v11
	v_cvt_pk_bf16_f32 v9, v12, v13
.LBB0_210:
	s_or_b64 exec, exec, s[6:7]
	v_mov_b32_e32 v11, 0
	s_and_saveexec_b64 s[6:7], vcc
	s_cbranch_execz .LBB0_212
	v_or_b32_e32 v6, v2, v149
	v_ashrrev_i32_e32 v7, 31, v6
	v_lshlrev_b64 v[6:7], 12, v[6:7]
	v_lshl_add_u64 v[6:7], s[20:21], 0, v[6:7]
	v_lshl_add_u64 v[6:7], v[4:5], 2, v[6:7]
	global_load_dwordx4 v[12:15], v[6:7], off nt
	s_waitcnt vmcnt(0)
	v_cvt_pk_bf16_f32 v11, v12, v13
	v_cvt_pk_bf16_f32 v3, v14, v15
.LBB0_212:
	s_or_b64 exec, exec, s[6:7]
	v_mov_b32_e32 v13, 0
	v_mov_b32_e32 v14, 0
	v_mov_b32_e32 v15, 0
	s_and_saveexec_b64 s[6:7], vcc
	s_cbranch_execz .LBB0_214
	v_or_b32_e32 v6, v2, v150
	v_ashrrev_i32_e32 v7, 31, v6
	v_lshlrev_b64 v[6:7], 12, v[6:7]
	v_lshl_add_u64 v[6:7], s[20:21], 0, v[6:7]
	v_lshl_add_u64 v[6:7], v[4:5], 2, v[6:7]
	global_load_dwordx4 v[14:17], v[6:7], off nt
	s_waitcnt vmcnt(0)
	v_cvt_pk_bf16_f32 v15, v14, v15
	v_cvt_pk_bf16_f32 v14, v16, v17
.LBB0_214:
	s_or_b64 exec, exec, s[6:7]
	v_mov_b32_e32 v16, 0
	s_and_saveexec_b64 s[6:7], vcc
	s_cbranch_execz .LBB0_216
	v_or_b32_e32 v6, v2, v151
	v_ashrrev_i32_e32 v7, 31, v6
	v_lshlrev_b64 v[6:7], 12, v[6:7]
	v_lshl_add_u64 v[6:7], s[20:21], 0, v[6:7]
	v_lshl_add_u64 v[4:5], v[4:5], 2, v[6:7]
	global_load_dwordx4 v[4:7], v[4:5], off nt
	s_waitcnt vmcnt(0)
	v_cvt_pk_bf16_f32 v16, v4, v5
	v_cvt_pk_bf16_f32 v13, v6, v7
.LBB0_216:
	s_or_b64 exec, exec, s[6:7]
	v_add_u32_e32 v5, 0xfffffd01, v119
	v_ashrrev_i32_e32 v4, 31, v5
	v_lshrrev_b32_e32 v4, 28, v4
	v_add_u32_e32 v4, v5, v4
	v_ashrrev_i32_e32 v6, 4, v4
	v_lshlrev_b32_e32 v4, 6, v6
	v_lshlrev_b32_e32 v6, 10, v6
	v_lshlrev_b32_e32 v5, 6, v5
	v_sub_u32_e32 v12, v5, v6
	v_or_b32_e32 v6, v12, v42
	v_cmp_gt_i32_e32 vcc, s84, v6
	v_mov_b32_e32 v5, 0
	v_ashrrev_i32_e32 v7, 31, v6
	v_mov_b32_e32 v17, 0
	v_mov_b32_e32 v18, 0
	s_and_saveexec_b64 s[6:7], vcc
	s_cbranch_execz .LBB0_218
	v_or_b32_e32 v18, v4, v40
	v_ashrrev_i32_e32 v19, 31, v18
	v_lshlrev_b64 v[18:19], 12, v[18:19]
	v_lshl_add_u64 v[18:19], s[20:21], 0, v[18:19]
	v_lshl_add_u64 v[18:19], v[6:7], 2, v[18:19]
	global_load_dwordx4 v[18:21], v[18:19], off nt
	s_waitcnt vmcnt(0)
	v_cvt_pk_bf16_f32 v18, v18, v19
	v_cvt_pk_bf16_f32 v17, v20, v21
.LBB0_218:
	s_or_b64 exec, exec, s[6:7]
	v_mov_b32_e32 v19, 0
	s_and_saveexec_b64 s[6:7], vcc
	s_cbranch_execz .LBB0_220
	v_or_b32_e32 v20, v4, v149
	v_ashrrev_i32_e32 v21, 31, v20
	v_lshlrev_b64 v[20:21], 12, v[20:21]
	v_lshl_add_u64 v[20:21], s[20:21], 0, v[20:21]
	v_lshl_add_u64 v[20:21], v[6:7], 2, v[20:21]
	global_load_dwordx4 v[20:23], v[20:21], off nt
	s_waitcnt vmcnt(0)
	v_cvt_pk_bf16_f32 v19, v20, v21
	v_cvt_pk_bf16_f32 v5, v22, v23
.LBB0_220:
	s_or_b64 exec, exec, s[6:7]
	v_mov_b32_e32 v20, 0
	v_mov_b32_e32 v21, 0
	v_mov_b32_e32 v22, 0
	s_and_saveexec_b64 s[6:7], vcc
	s_cbranch_execz .LBB0_222
	v_or_b32_e32 v22, v4, v150
	v_ashrrev_i32_e32 v23, 31, v22
	v_lshlrev_b64 v[22:23], 12, v[22:23]
	v_lshl_add_u64 v[22:23], s[20:21], 0, v[22:23]
	v_lshl_add_u64 v[22:23], v[6:7], 2, v[22:23]
	global_load_dwordx4 v[22:25], v[22:23], off nt
	s_waitcnt vmcnt(0)
	v_cvt_pk_bf16_f32 v22, v22, v23
	v_cvt_pk_bf16_f32 v21, v24, v25
.LBB0_222:
	s_or_b64 exec, exec, s[6:7]
	v_mov_b32_e32 v23, 0
	s_and_saveexec_b64 s[6:7], vcc
	s_cbranch_execz .LBB0_224
	v_or_b32_e32 v24, v4, v151
	v_ashrrev_i32_e32 v25, 31, v24
	v_lshlrev_b64 v[24:25], 12, v[24:25]
	v_lshl_add_u64 v[24:25], s[20:21], 0, v[24:25]
	v_lshl_add_u64 v[6:7], v[6:7], 2, v[24:25]
	global_load_dwordx4 v[24:27], v[6:7], off nt
	s_waitcnt vmcnt(0)
	v_cvt_pk_bf16_f32 v23, v24, v25
	v_cvt_pk_bf16_f32 v20, v26, v27

; __device__ __forceinline__ void transpose_tile2(const float* tsrc, u16* tdst, int tK, int tN, int tNpad, int tile, u16* sm, const bool rp0 = false, const bool rp1 = false, const bool upperm = false, const float* gk = nullptr) {
;     ...
; #pragma unroll
;     for (int i = 0; i < 4; ++i) {
;       const int nsrc0 = upperm ? (((n0s[t] >> 7) & 1) * DFF + 128 * (n0s[t] >> 8) + (n0s[t] & 127)) : n0s[t];
;       const int k = r + 16 * i, n = nsrc0 + c4 * 4;
;       v[t][i] = make_float4(0.f, 0.f, 0.f, 0.f);
;       if (n < tN) v[t][i] = *(const float4*)(tsrc + (size_t)(k0s[t] + k) * tN + n);
;       if (gk) { const float gs = gk[k0s[t] + k]; v[t][i].x *= gs; v[t][i].y *= gs; v[t][i].z *= gs; v[t][i].w *= gs; }
;     }
;   }
; #pragma unroll
;   for (int t = 0; t < 2; ++t)
; #pragma unroll
;     for (int i = 0; i < 4; ++i) {
;       const int k = r + 16 * i;
;       u16* d = sm + t * 64 * LDSP;
;       const uint32_t p01 = pack2(v[t][i].x, v[t][i].y), p23 = pack2(v[t][i].z, v[t][i].w);
.LBB0_226:
	s_andn2_saveexec_b64 s[4:5], s[94:95]
	s_cbranch_execz .LBB0_10
	v_mul_hi_i32 v2, v1, s78
	v_lshrrev_b32_e32 v3, 31, v2
	v_ashrrev_i32_e32 v2, 2, v2
	v_add_u32_e32 v2, v2, v3
	v_mul_lo_u32 v3, v2, s79
	v_add_lshl_u32 v8, v3, v119, 6
	v_or_b32_e32 v4, v8, v42
	v_lshlrev_b32_e32 v2, 6, v2
	v_cmp_gt_i32_e32 vcc, s80, v4
	v_mov_b32_e32 v3, 0
	v_ashrrev_i32_e32 v5, 31, v4
	v_mov_b32_e32 v9, 0
	v_mov_b32_e32 v10, 0
	s_and_saveexec_b64 s[6:7], vcc
	s_cbranch_execz .LBB0_229
	v_or_b32_e32 v9, v2, v40
	v_mov_b64_e32 v[6:7], s[18:19]
	v_mad_i64_i32 v[6:7], s[34:35], v9, s81, v[6:7]
	v_lshl_add_u64 v[6:7], v[4:5], 2, v[6:7]
	global_load_dwordx4 v[10:13], v[6:7], off nt
	s_waitcnt vmcnt(0)
	v_cvt_pk_bf16_f32 v10, v10, v11
	v_cvt_pk_bf16_f32 v9, v12, v13
.LBB0_229:
	s_or_b64 exec, exec, s[6:7]
	v_mov_b32_e32 v12, 0
	s_and_saveexec_b64 s[6:7], vcc
	s_cbranch_execz .LBB0_231
	v_or_b32_e32 v3, v2, v149
	v_mov_b64_e32 v[6:7], s[18:19]
	v_mad_i64_i32 v[6:7], s[34:35], v3, s81, v[6:7]
	v_lshl_add_u64 v[6:7], v[4:5], 2, v[6:7]
	global_load_dwordx4 v[12:15], v[6:7], off nt
	s_waitcnt vmcnt(0)
	v_cvt_pk_bf16_f32 v12, v12, v13
	v_cvt_pk_bf16_f32 v3, v14, v15
.LBB0_231:
	s_or_b64 exec, exec, s[6:7]
	v_mov_b32_e32 v13, 0
	v_mov_b32_e32 v14, 0
	v_mov_b32_e32 v15, 0
	s_and_saveexec_b64 s[6:7], vcc
	s_cbranch_execz .LBB0_233
	v_or_b32_e32 v11, v2, v150
	v_mov_b64_e32 v[6:7], s[18:19]
	v_mad_i64_i32 v[6:7], s[34:35], v11, s81, v[6:7]
	v_lshl_add_u64 v[6:7], v[4:5], 2, v[6:7]
	global_load_dwordx4 v[14:17], v[6:7], off nt
	s_waitcnt vmcnt(0)
	v_cvt_pk_bf16_f32 v15, v14, v15
	v_cvt_pk_bf16_f32 v14, v16, v17
.LBB0_233:
	s_or_b64 exec, exec, s[6:7]
	v_mov_b32_e32 v16, 0
	s_and_saveexec_b64 s[6:7], vcc
	s_cbranch_execz .LBB0_235
	v_or_b32_e32 v11, v2, v151
	v_mov_b64_e32 v[6:7], s[18:19]
	v_mad_i64_i32 v[6:7], s[34:35], v11, s81, v[6:7]
	v_lshl_add_u64 v[4:5], v[4:5], 2, v[6:7]
	global_load_dwordx4 v[4:7], v[4:5], off nt
	s_waitcnt vmcnt(0)
	v_cvt_pk_bf16_f32 v16, v4, v5
	v_cvt_pk_bf16_f32 v13, v6, v7
.LBB0_235:
	s_or_b64 exec, exec, s[6:7]
	v_or_b32_e32 v5, 1, v119
	v_mul_hi_i32 v4, v5, s78
	v_lshrrev_b32_e32 v6, 31, v4
	v_ashrrev_i32_e32 v4, 3, v4
	v_add_u32_e32 v4, v4, v6
	v_mul_lo_u32 v6, v4, s79
	v_add_lshl_u32 v11, v6, v5, 6
	v_or_b32_e32 v6, v11, v42
	v_lshlrev_b32_e32 v4, 6, v4
	v_cmp_gt_i32_e32 vcc, s80, v6
	v_mov_b32_e32 v5, 0
	v_ashrrev_i32_e32 v7, 31, v6
	v_mov_b32_e32 v17, 0
	v_mov_b32_e32 v18, 0
	s_and_saveexec_b64 s[6:7], vcc
	s_cbranch_execz .LBB0_237
	v_or_b32_e32 v17, v4, v40
	v_mov_b64_e32 v[18:19], s[18:19]
	v_mad_i64_i32 v[18:19], s[34:35], v17, s81, v[18:19]
	v_lshl_add_u64 v[18:19], v[6:7], 2, v[18:19]
	global_load_dwordx4 v[18:21], v[18:19], off nt
	s_waitcnt vmcnt(0)
	v_cvt_pk_bf16_f32 v18, v18, v19
	v_cvt_pk_bf16_f32 v17, v20, v21
.LBB0_237:
	s_or_b64 exec, exec, s[6:7]
	v_mov_b32_e32 v19, 0
	s_and_saveexec_b64 s[6:7], vcc
	s_cbranch_execz .LBB0_239
	v_or_b32_e32 v5, v4, v149
	v_mov_b64_e32 v[20:21], s[18:19]
	v_mad_i64_i32 v[20:21], s[34:35], v5, s81, v[20:21]
	v_lshl_add_u64 v[20:21], v[6:7], 2, v[20:21]
	global_load_dwordx4 v[20:23], v[20:21], off nt
	s_waitcnt vmcnt(0)
	v_cvt_pk_bf16_f32 v19, v20, v21
	v_cvt_pk_bf16_f32 v5, v22, v23
.LBB0_239:
	s_or_b64 exec, exec, s[6:7]
	v_mov_b32_e32 v20, 0
	v_mov_b32_e32 v21, 0
	v_mov_b32_e32 v22, 0
	s_and_saveexec_b64 s[6:7], vcc
	s_cbranch_execz .LBB0_241
	v_or_b32_e32 v21, v4, v150
	v_mov_b64_e32 v[22:23], s[18:19]
	v_mad_i64_i32 v[22:23], s[34:35], v21, s81, v[22:23]
	v_lshl_add_u64 v[22:23], v[6:7], 2, v[22:23]
	global_load_dwordx4 v[22:25], v[22:23], off nt
	s_waitcnt vmcnt(0)
	v_cvt_pk_bf16_f32 v22, v22, v23
	v_cvt_pk_bf16_f32 v21, v24, v25
.LBB0_241:
	s_or_b64 exec, exec, s[6:7]
	v_mov_b32_e32 v23, 0
	s_and_saveexec_b64 s[6:7], vcc
	s_cbranch_execz .LBB0_9
	v_or_b32_e32 v20, v4, v151
	v_mov_b64_e32 v[24:25], s[18:19]
	v_mad_i64_i32 v[24:25], s[34:35], v20, s81, v[24:25]
	v_lshl_add_u64 v[6:7], v[6:7], 2, v[24:25]
	global_load_dwordx4 v[24:27], v[6:7], off nt
	s_waitcnt vmcnt(0)
	v_cvt_pk_bf16_f32 v23, v24, v25
	v_cvt_pk_bf16_f32 v20, v26, v27
	s_branch .LBB0_9

; #define PG8_STAGE(bufoff, gbase, voff) do { _Pragma("unroll") for (int _i = 0; _i < 2; ++_i) \
;     __builtin_amdgcn_global_load_lds((const unsigned*)((const char*)(gbase) + (voff)[_i]), (LAS unsigned*)(lds + (bufoff) + ldsw + _i * 8192), 16, 0, 0); } while (0)
; #define PG8_LDB(dst, b, h) do { \
;     PG8_DSR(dst[0][0], baddr, ((b) * 2 + (h)) * PG_HTB + 0 * 2048 + 0);    PG8_DSR(dst[0][1], baddr, ((b) * 2 + (h)) * PG_HTB + 0 * 2048 + 1024); \
;     PG8_DSR(dst[1][0], baddr, ((b) * 2 + (h)) * PG_HTB + 1 * 2048 + 0);    PG8_DSR(dst[1][1], baddr, ((b) * 2 + (h)) * PG_HTB + 1 * 2048 + 1024); } while (0)
; #define PG8_MMA(ai, bj, At, Bt) do { __builtin_amdgcn_s_setprio(1); _Pragma("unroll") for (int m = 0; m < 4; ++m) _Pragma("unroll") for (int n = 0; n < 2; ++n) _Pragma("unroll") for (int k = 0; k < 2; ++k) \
;     acc[ai][bj][m][n] = __builtin_amdgcn_mfma_f32_16x16x32_bf16(Bt[n][k], At[m][k], acc[ai][bj][m][n], 0, 0, 0); __builtin_amdgcn_s_setprio(0); } while (0)
; #define PG8_WAIT_V(n) asm volatile("s_waitcnt vmcnt(" #n ")" ::: "memory")
; #define PG8_WAIT_L(n) asm volatile("s_waitcnt lgkmcnt(" #n ")" ::: "memory")
; #define PG8_WAIT_L0 asm volatile("s_waitcnt lgkmcnt(0)" \
;     : "+v"(At[0][0]), "+v"(At[0][1]), "+v"(At[1][0]), "+v"(At[1][1]), "+v"(At[2][0]), "+v"(At[2][1]), "+v"(At[3][0]), "+v"(At[3][1]), \
;       "+v"(B0[0][0]), "+v"(B0[0][1]), "+v"(B0[1][0]), "+v"(B0[1][1]), "+v"(B1[0][0]), "+v"(B1[0][1]), "+v"(B1[1][0]), "+v"(B1[1][1]) :: "memory")
; #define PG8_BAR __builtin_amdgcn_s_barrier()
; #define PG8_SCHED __builtin_amdgcn_sched_barrier(0)
; template <class Epi>
; __device__ __forceinline__ void gemm_phase(LAS unsigned char* lds, const Gemm g, const StaticOrder& S, const Epi& E) {
;     ...
;       PG8_LDB(B0, 0, 0); PG8_SCHED; PG8_LDA(At, 0, 0); PG8_STAGE(PG8_SA(1, 1), a1 + hstep, voffA);
;       PG8_WAIT_L(8); PG8_BAR; PG8_WAIT_L0; PG8_MMA(0, 0, At, B0); PG8_BAR; PG8_SCHED;
;       PG8_LDB(B1, 0, 1); PG8_STAGE(PG8_SB(0, 0), b2, voffA);
;       PG8_BAR; PG8_WAIT_L0; PG8_MMA(0, 1, At, B1); PG8_BAR;
;       PG8_LDA(At, 0, 1); PG8_STAGE(PG8_SA(0, 0), a2, voffA);
;       PG8_BAR; PG8_WAIT_L0; PG8_MMA(1, 0, At, B0); PG8_BAR; PG8_SCHED;
;       PG8_STAGE(PG8_SB(0, 1), b2 + hstep, voffA);
;       PG8_WAIT_V(6); PG8_BAR; PG8_MMA(1, 1, At, B1); PG8_BAR;
.LBB0_402:
	ds_read_b128 v[144:147], v220 offset:0
	ds_read_b128 v[148:151], v220 offset:0x400
	ds_read_b128 v[152:155], v220 offset:0x800
	s_add_u32 s35, s26, 0xfffc0080
	ds_read_b128 v[156:159], v220 offset:0xc00
	s_addc_u32 s36, s27, -1
	s_cmp_eq_u32 s34, 12
	s_cselect_b32 s41, s17, s36
	s_cselect_b32 s40, s23, s35
	ds_read_b128 v[160:163], v219 offset:0
	ds_read_b128 v[164:167], v219 offset:0x400
	ds_read_b128 v[168:171], v219 offset:0x800
	ds_read_b128 v[172:175], v219 offset:0xc00
	ds_read_b128 v[176:179], v219 offset:0x1000
	ds_read_b128 v[180:183], v219 offset:0x1400
	ds_read_b128 v[184:187], v219 offset:0x1800
	s_mov_b32 m0, s63
	ds_read_b128 v[188:191], v219 offset:0x1c00
	v_lshl_add_u64 v[206:207], s[26:27], 0, v[198:199]
	global_load_lds_dwordx4 v[206:207], off
	v_lshl_add_u64 v[206:207], s[26:27], 0, v[200:201]
	s_mov_b32 m0, s66
	s_cselect_b32 s39, s11, s78
	global_load_lds_dwordx4 v[206:207], off
	s_waitcnt lgkmcnt(8)
	s_barrier
	s_waitcnt lgkmcnt(0)
	s_cselect_b32 s38, s76, s77
	s_setprio 1
	v_mfma_f32_16x16x32_bf16 v[0:3], v[144:147], v[160:163], v[140:143]
	v_mfma_f32_16x16x32_bf16 v[4:7], v[152:155], v[160:163], v[136:139]
	v_mfma_f32_16x16x32_bf16 v[8:11], v[144:147], v[168:171], v[124:127]
	v_mfma_f32_16x16x32_bf16 v[12:15], v[152:155], v[168:171], v[120:123]
	v_mfma_f32_16x16x32_bf16 v[108:111], v[144:147], v[176:179], v[108:111]
	v_mfma_f32_16x16x32_bf16 v[104:107], v[152:155], v[176:179], v[104:107]
	v_mfma_f32_16x16x32_bf16 v[92:95], v[144:147], v[184:187], v[92:95]
	v_mfma_f32_16x16x32_bf16 v[88:91], v[152:155], v[184:187], v[88:91]
	v_mfma_f32_16x16x32_bf16 v[0:3], v[148:151], v[164:167], v[0:3]
	v_mfma_f32_16x16x32_bf16 v[4:7], v[156:159], v[164:167], v[4:7]
	v_mfma_f32_16x16x32_bf16 v[8:11], v[148:151], v[172:175], v[8:11]
	v_mfma_f32_16x16x32_bf16 v[12:15], v[156:159], v[172:175], v[12:15]
	v_mfma_f32_16x16x32_bf16 v[108:111], v[148:151], v[180:183], v[108:111]
	v_mfma_f32_16x16x32_bf16 v[104:107], v[156:159], v[180:183], v[104:107]
	v_mfma_f32_16x16x32_bf16 v[92:95], v[148:151], v[188:191], v[92:95]
	v_mfma_f32_16x16x32_bf16 v[88:91], v[156:159], v[188:191], v[88:91]
	s_setprio 0
	s_barrier
	ds_read_b128 v[120:123], v220 offset:0x4000
	ds_read_b128 v[124:127], v220 offset:0x4400
	ds_read_b128 v[136:139], v220 offset:0x4800
	s_mov_b32 m0, s25
	ds_read_b128 v[140:143], v220 offset:0x4c00
	v_lshl_add_u64 v[206:207], s[38:39], 0, v[194:195]
	global_load_lds_dwordx4 v[206:207], off
	v_lshl_add_u64 v[208:209], s[38:39], 0, v[196:197]
	s_mov_b32 m0, s28
	s_nop 0
	global_load_lds_dwordx4 v[208:209], off
	s_barrier
	s_waitcnt lgkmcnt(0)
	s_setprio 1
	v_mfma_f32_16x16x32_bf16 v[132:135], v[120:123], v[160:163], v[132:135]
	v_mfma_f32_16x16x32_bf16 v[128:131], v[136:139], v[160:163], v[128:131]
	v_mfma_f32_16x16x32_bf16 v[116:119], v[120:123], v[168:171], v[116:119]
	v_mfma_f32_16x16x32_bf16 v[112:115], v[136:139], v[168:171], v[112:115]
	v_mfma_f32_16x16x32_bf16 v[100:103], v[120:123], v[176:179], v[100:103]
	v_mfma_f32_16x16x32_bf16 v[96:99], v[136:139], v[176:179], v[96:99]
	v_mfma_f32_16x16x32_bf16 v[84:87], v[120:123], v[184:187], v[84:87]
	v_mfma_f32_16x16x32_bf16 v[80:83], v[136:139], v[184:187], v[80:83]
	v_mfma_f32_16x16x32_bf16 v[132:135], v[124:127], v[164:167], v[132:135]
	v_mfma_f32_16x16x32_bf16 v[128:131], v[140:143], v[164:167], v[128:131]
	v_mfma_f32_16x16x32_bf16 v[116:119], v[124:127], v[172:175], v[116:119]
	v_mfma_f32_16x16x32_bf16 v[112:115], v[140:143], v[172:175], v[112:115]
	v_mfma_f32_16x16x32_bf16 v[100:103], v[124:127], v[180:183], v[100:103]
	v_mfma_f32_16x16x32_bf16 v[96:99], v[140:143], v[180:183], v[96:99]
	v_mfma_f32_16x16x32_bf16 v[84:87], v[124:127], v[188:191], v[84:87]
	v_mfma_f32_16x16x32_bf16 v[80:83], v[140:143], v[188:191], v[80:83]
	s_setprio 0
	s_barrier
	ds_read_b128 v[160:163], v219 offset:0x4000
	ds_read_b128 v[164:167], v219 offset:0x4400
	ds_read_b128 v[168:171], v219 offset:0x4800
	ds_read_b128 v[172:175], v219 offset:0x4c00
	ds_read_b128 v[176:179], v219 offset:0x5000
	ds_read_b128 v[180:183], v219 offset:0x5400
	ds_read_b128 v[184:187], v219 offset:0x5800
	s_mov_b32 m0, s3
	ds_read_b128 v[188:191], v219 offset:0x5c00
	v_lshl_add_u64 v[210:211], s[40:41], 0, v[194:195]
	global_load_lds_dwordx4 v[210:211], off
	v_lshl_add_u64 v[212:213], s[40:41], 0, v[196:197]
	s_mov_b32 m0, s29
	s_nop 0
	global_load_lds_dwordx4 v[212:213], off
	s_barrier
	s_waitcnt lgkmcnt(0)
	s_setprio 1
	v_mfma_f32_16x16x32_bf16 v[76:79], v[144:147], v[160:163], v[76:79]
	v_mfma_f32_16x16x32_bf16 v[72:75], v[152:155], v[160:163], v[72:75]
	v_mfma_f32_16x16x32_bf16 v[60:63], v[144:147], v[168:171], v[60:63]
	v_mfma_f32_16x16x32_bf16 v[56:59], v[152:155], v[168:171], v[56:59]
	v_mfma_f32_16x16x32_bf16 v[44:47], v[144:147], v[176:179], v[44:47]
	v_mfma_f32_16x16x32_bf16 v[40:43], v[152:155], v[176:179], v[40:43]
	v_mfma_f32_16x16x32_bf16 v[28:31], v[144:147], v[184:187], v[28:31]
	v_mfma_f32_16x16x32_bf16 v[24:27], v[152:155], v[184:187], v[24:27]
	v_mfma_f32_16x16x32_bf16 v[76:79], v[148:151], v[164:167], v[76:79]
	v_mfma_f32_16x16x32_bf16 v[72:75], v[156:159], v[164:167], v[72:75]
	v_mfma_f32_16x16x32_bf16 v[60:63], v[148:151], v[172:175], v[60:63]
	v_mfma_f32_16x16x32_bf16 v[56:59], v[156:159], v[172:175], v[56:59]
	v_mfma_f32_16x16x32_bf16 v[44:47], v[148:151], v[180:183], v[44:47]
	v_mfma_f32_16x16x32_bf16 v[40:43], v[156:159], v[180:183], v[40:43]
	v_mfma_f32_16x16x32_bf16 v[28:31], v[148:151], v[188:191], v[28:31]
	v_mfma_f32_16x16x32_bf16 v[24:27], v[156:159], v[188:191], v[24:27]
	s_setprio 0
	s_barrier
; #define PG8_STAGE(bufoff, gbase, voff) do { _Pragma("unroll") for (int _i = 0; _i < 2; ++_i) \
;     __builtin_amdgcn_global_load_lds((const unsigned*)((const char*)(gbase) + (voff)[_i]), (LAS unsigned*)(lds + (bufoff) + ldsw + _i * 8192), 16, 0, 0); } while (0)
; #define PG8_LDB(dst, b, h) do { \
;     PG8_DSR(dst[0][0], baddr, ((b) * 2 + (h)) * PG_HTB + 0 * 2048 + 0);    PG8_DSR(dst[0][1], baddr, ((b) * 2 + (h)) * PG_HTB + 0 * 2048 + 1024); \
;     PG8_DSR(dst[1][0], baddr, ((b) * 2 + (h)) * PG_HTB + 1 * 2048 + 0);    PG8_DSR(dst[1][1], baddr, ((b) * 2 + (h)) * PG_HTB + 1 * 2048 + 1024); } while (0)
; #define PG8_MMA(ai, bj, At, Bt) do { __builtin_amdgcn_s_setprio(1); _Pragma("unroll") for (int m = 0; m < 4; ++m) _Pragma("unroll") for (int n = 0; n < 2; ++n) _Pragma("unroll") for (int k = 0; k < 2; ++k) \
;     acc[ai][bj][m][n] = __builtin_amdgcn_mfma_f32_16x16x32_bf16(Bt[n][k], At[m][k], acc[ai][bj][m][n], 0, 0, 0); __builtin_amdgcn_s_setprio(0); } while (0)
; #define PG8_WAIT_V(n) asm volatile("s_waitcnt vmcnt(" #n ")" ::: "memory")
; #define PG8_WAIT_L(n) asm volatile("s_waitcnt lgkmcnt(" #n ")" ::: "memory")
; #define PG8_WAIT_L0 asm volatile("s_waitcnt lgkmcnt(0)" \
;     : "+v"(At[0][0]), "+v"(At[0][1]), "+v"(At[1][0]), "+v"(At[1][1]), "+v"(At[2][0]), "+v"(At[2][1]), "+v"(At[3][0]), "+v"(At[3][1]), \
;       "+v"(B0[0][0]), "+v"(B0[0][1]), "+v"(B0[1][0]), "+v"(B0[1][1]), "+v"(B1[0][0]), "+v"(B1[0][1]), "+v"(B1[1][0]), "+v"(B1[1][1]) :: "memory")
; #define PG8_BAR __builtin_amdgcn_s_barrier()
; #define PG8_SCHED __builtin_amdgcn_sched_barrier(0)
; template <class Epi>
; __device__ __forceinline__ void gemm_phase(LAS unsigned char* lds, const Gemm g, const StaticOrder& S, const Epi& E) {
;     ...
;       PG8_WAIT_V(6); PG8_BAR; PG8_MMA(1, 1, At, B1); PG8_BAR;
;       PG8_LDB(B0, 1, 0); PG8_SCHED; PG8_LDA(At, 1, 0); PG8_STAGE(PG8_SA(0, 1), a2 + hstep, voffA);
;       PG8_WAIT_L(8); PG8_BAR; PG8_WAIT_L0; PG8_MMA(0, 0, At, B0); PG8_BAR; PG8_SCHED;
;       PG8_LDB(B1, 1, 1); PG8_STAGE(PG8_SB(1, 0), b3, voffA);
;       PG8_BAR; PG8_WAIT_L0; PG8_MMA(0, 1, At, B1); PG8_BAR;
;       PG8_LDA(At, 1, 1); PG8_STAGE(PG8_SA(1, 0), a3, voffA);
;       PG8_BAR; PG8_WAIT_L0; PG8_MMA(1, 0, At, B0); PG8_BAR; PG8_SCHED;
;       PG8_STAGE(PG8_SB(1, 1), b3 + hstep, voffA);
	s_add_u32 s80, s38, 0x40000
	s_addc_u32 s81, s39, 0
	s_mov_b32 m0, s30
	v_lshl_add_u64 v[144:145], s[80:81], 0, v[194:195]
	global_load_lds_dwordx4 v[144:145], off
	v_lshl_add_u64 v[144:145], s[80:81], 0, v[196:197]
	s_mov_b32 m0, s31
	s_nop 0
	global_load_lds_dwordx4 v[144:145], off
	s_waitcnt vmcnt(6)
	s_barrier
	s_setprio 1
	v_mfma_f32_16x16x32_bf16 v[68:71], v[120:123], v[160:163], v[68:71]
	v_mfma_f32_16x16x32_bf16 v[64:67], v[136:139], v[160:163], v[64:67]
	v_mfma_f32_16x16x32_bf16 v[52:55], v[120:123], v[168:171], v[52:55]
	v_mfma_f32_16x16x32_bf16 v[48:51], v[136:139], v[168:171], v[48:51]
	v_mfma_f32_16x16x32_bf16 v[36:39], v[120:123], v[176:179], v[36:39]
	v_mfma_f32_16x16x32_bf16 v[32:35], v[136:139], v[176:179], v[32:35]
	v_mfma_f32_16x16x32_bf16 v[20:23], v[120:123], v[184:187], v[20:23]
	v_mfma_f32_16x16x32_bf16 v[16:19], v[136:139], v[184:187], v[16:19]
	v_mfma_f32_16x16x32_bf16 v[68:71], v[124:127], v[164:167], v[68:71]
	v_mfma_f32_16x16x32_bf16 v[64:67], v[140:143], v[164:167], v[64:67]
	v_mfma_f32_16x16x32_bf16 v[52:55], v[124:127], v[172:175], v[52:55]
	v_mfma_f32_16x16x32_bf16 v[48:51], v[140:143], v[172:175], v[48:51]
	v_mfma_f32_16x16x32_bf16 v[36:39], v[124:127], v[180:183], v[36:39]
	v_mfma_f32_16x16x32_bf16 v[32:35], v[140:143], v[180:183], v[32:35]
	v_mfma_f32_16x16x32_bf16 v[20:23], v[124:127], v[188:191], v[20:23]
	v_mfma_f32_16x16x32_bf16 v[16:19], v[140:143], v[188:191], v[16:19]
	s_setprio 0
	s_barrier
	ds_read_b128 v[144:147], v220 offset:0x8000
	ds_read_b128 v[148:151], v220 offset:0x8400
	ds_read_b128 v[152:155], v220 offset:0x8800
	ds_read_b128 v[156:159], v220 offset:0x8c00
	ds_read_b128 v[160:163], v219 offset:0x8000
	ds_read_b128 v[164:167], v219 offset:0x8400
	ds_read_b128 v[168:171], v219 offset:0x8800
	ds_read_b128 v[172:175], v219 offset:0x8c00
	ds_read_b128 v[176:179], v219 offset:0x9000
	ds_read_b128 v[180:183], v219 offset:0x9400
	s_add_u32 s40, s40, 0x40000
	ds_read_b128 v[184:187], v219 offset:0x9800
	s_addc_u32 s41, s41, 0
	s_mov_b32 m0, s46
	ds_read_b128 v[188:191], v219 offset:0x9c00
	v_lshl_add_u64 v[214:215], s[40:41], 0, v[194:195]
	global_load_lds_dwordx4 v[214:215], off
	v_lshl_add_u64 v[214:215], s[40:41], 0, v[196:197]
	s_mov_b32 m0, s47
	s_nop 0
	global_load_lds_dwordx4 v[214:215], off
	s_waitcnt lgkmcnt(8)
	s_barrier
	s_waitcnt lgkmcnt(0)
	s_setprio 1
	v_mfma_f32_16x16x32_bf16 v[0:3], v[144:147], v[160:163], v[0:3]
	v_mfma_f32_16x16x32_bf16 v[140:143], v[148:151], v[164:167], v[0:3]
	v_mfma_f32_16x16x32_bf16 v[0:3], v[152:155], v[160:163], v[4:7]
	v_mfma_f32_16x16x32_bf16 v[136:139], v[156:159], v[164:167], v[0:3]
	v_mfma_f32_16x16x32_bf16 v[0:3], v[144:147], v[168:171], v[8:11]
	v_mfma_f32_16x16x32_bf16 v[124:127], v[148:151], v[172:175], v[0:3]
	v_mfma_f32_16x16x32_bf16 v[0:3], v[152:155], v[168:171], v[12:15]
	v_mfma_f32_16x16x32_bf16 v[120:123], v[156:159], v[172:175], v[0:3]
	v_mfma_f32_16x16x32_bf16 v[0:3], v[144:147], v[176:179], v[108:111]
	v_mfma_f32_16x16x32_bf16 v[108:111], v[148:151], v[180:183], v[0:3]
	v_mfma_f32_16x16x32_bf16 v[0:3], v[152:155], v[176:179], v[104:107]
	v_mfma_f32_16x16x32_bf16 v[104:107], v[156:159], v[180:183], v[0:3]
	v_mfma_f32_16x16x32_bf16 v[0:3], v[144:147], v[184:187], v[92:95]
	v_mfma_f32_16x16x32_bf16 v[92:95], v[148:151], v[188:191], v[0:3]
	v_mfma_f32_16x16x32_bf16 v[0:3], v[152:155], v[184:187], v[88:91]
	v_mfma_f32_16x16x32_bf16 v[88:91], v[156:159], v[188:191], v[0:3]
	s_setprio 0
	s_barrier
	ds_read_b128 v[12:15], v220 offset:0xc000
	ds_read_b128 v[8:11], v220 offset:0xc400
	ds_read_b128 v[4:7], v220 offset:0xc800
	s_mov_b32 m0, s48
	ds_read_b128 v[0:3], v220 offset:0xcc00
	v_lshl_add_u64 v[206:207], v[206:207], 0, s[8:9]
	global_load_lds_dwordx4 v[206:207], off
	v_lshl_add_u64 v[206:207], v[208:209], 0, s[8:9]
	s_mov_b32 m0, s49
	s_nop 0
	global_load_lds_dwordx4 v[206:207], off
	s_barrier
	s_waitcnt lgkmcnt(0)
	s_setprio 1
	v_mfma_f32_16x16x32_bf16 v[132:135], v[12:15], v[160:163], v[132:135]
	v_mfma_f32_16x16x32_bf16 v[128:131], v[4:7], v[160:163], v[128:131]
	v_mfma_f32_16x16x32_bf16 v[116:119], v[12:15], v[168:171], v[116:119]
	v_mfma_f32_16x16x32_bf16 v[112:115], v[4:7], v[168:171], v[112:115]
	v_mfma_f32_16x16x32_bf16 v[100:103], v[12:15], v[176:179], v[100:103]
	v_mfma_f32_16x16x32_bf16 v[96:99], v[4:7], v[176:179], v[96:99]
	v_mfma_f32_16x16x32_bf16 v[84:87], v[12:15], v[184:187], v[84:87]
	v_mfma_f32_16x16x32_bf16 v[80:83], v[4:7], v[184:187], v[80:83]
	v_mfma_f32_16x16x32_bf16 v[132:135], v[8:11], v[164:167], v[132:135]
	v_mfma_f32_16x16x32_bf16 v[128:131], v[0:3], v[164:167], v[128:131]
	v_mfma_f32_16x16x32_bf16 v[116:119], v[8:11], v[172:175], v[116:119]
	v_mfma_f32_16x16x32_bf16 v[112:115], v[0:3], v[172:175], v[112:115]
	v_mfma_f32_16x16x32_bf16 v[100:103], v[8:11], v[180:183], v[100:103]
	v_mfma_f32_16x16x32_bf16 v[96:99], v[0:3], v[180:183], v[96:99]
	v_mfma_f32_16x16x32_bf16 v[84:87], v[8:11], v[188:191], v[84:87]
	v_mfma_f32_16x16x32_bf16 v[80:83], v[0:3], v[188:191], v[80:83]
	s_setprio 0
	s_barrier
	ds_read_b128 v[160:163], v219 offset:0xc000
	ds_read_b128 v[164:167], v219 offset:0xc400
	ds_read_b128 v[168:171], v219 offset:0xc800
	ds_read_b128 v[172:175], v219 offset:0xcc00
	ds_read_b128 v[176:179], v219 offset:0xd000
	ds_read_b128 v[180:183], v219 offset:0xd400
	ds_read_b128 v[184:187], v219 offset:0xd800
	s_mov_b32 m0, s50
	ds_read_b128 v[188:191], v219 offset:0xdc00
	v_lshl_add_u64 v[206:207], v[210:211], 0, s[8:9]
	global_load_lds_dwordx4 v[206:207], off
	v_lshl_add_u64 v[206:207], v[212:213], 0, s[8:9]
	s_mov_b32 m0, s51
	s_nop 0
	global_load_lds_dwordx4 v[206:207], off
	s_barrier
; #define PG8_STAGE(bufoff, gbase, voff) do { _Pragma("unroll") for (int _i = 0; _i < 2; ++_i) \
;     __builtin_amdgcn_global_load_lds((const unsigned*)((const char*)(gbase) + (voff)[_i]), (LAS unsigned*)(lds + (bufoff) + ldsw + _i * 8192), 16, 0, 0); } while (0)
; #define PG8_MMA(ai, bj, At, Bt) do { __builtin_amdgcn_s_setprio(1); _Pragma("unroll") for (int m = 0; m < 4; ++m) _Pragma("unroll") for (int n = 0; n < 2; ++n) _Pragma("unroll") for (int k = 0; k < 2; ++k) \
;     acc[ai][bj][m][n] = __builtin_amdgcn_mfma_f32_16x16x32_bf16(Bt[n][k], At[m][k], acc[ai][bj][m][n], 0, 0, 0); __builtin_amdgcn_s_setprio(0); } while (0)
; #define PG8_WAIT_V(n) asm volatile("s_waitcnt vmcnt(" #n ")" ::: "memory")
; #define PG8_BAR __builtin_amdgcn_s_barrier()
; template <class Epi>
; __device__ __forceinline__ void gemm_phase(LAS unsigned char* lds, const Gemm g, const StaticOrder& S, const Epi& E) {
;     ...
;       PG8_STAGE(PG8_SB(1, 1), b3 + hstep, voffA);
;       PG8_WAIT_V(6); PG8_BAR; PG8_MMA(1, 1, At, B1); PG8_BAR;
	s_waitcnt lgkmcnt(0)
	s_setprio 1
	v_mfma_f32_16x16x32_bf16 v[76:79], v[144:147], v[160:163], v[76:79]
	v_mfma_f32_16x16x32_bf16 v[72:75], v[152:155], v[160:163], v[72:75]
	v_mfma_f32_16x16x32_bf16 v[60:63], v[144:147], v[168:171], v[60:63]
	v_mfma_f32_16x16x32_bf16 v[56:59], v[152:155], v[168:171], v[56:59]
	v_mfma_f32_16x16x32_bf16 v[44:47], v[144:147], v[176:179], v[44:47]
	v_mfma_f32_16x16x32_bf16 v[40:43], v[152:155], v[176:179], v[40:43]
	v_mfma_f32_16x16x32_bf16 v[28:31], v[144:147], v[184:187], v[28:31]
	v_mfma_f32_16x16x32_bf16 v[24:27], v[152:155], v[184:187], v[24:27]
	v_mfma_f32_16x16x32_bf16 v[76:79], v[148:151], v[164:167], v[76:79]
	v_mfma_f32_16x16x32_bf16 v[72:75], v[156:159], v[164:167], v[72:75]
	v_mfma_f32_16x16x32_bf16 v[60:63], v[148:151], v[172:175], v[60:63]
	v_mfma_f32_16x16x32_bf16 v[56:59], v[156:159], v[172:175], v[56:59]
	v_mfma_f32_16x16x32_bf16 v[44:47], v[148:151], v[180:183], v[44:47]
	v_mfma_f32_16x16x32_bf16 v[40:43], v[156:159], v[180:183], v[40:43]
	v_mfma_f32_16x16x32_bf16 v[28:31], v[148:151], v[188:191], v[28:31]
	v_mfma_f32_16x16x32_bf16 v[24:27], v[156:159], v[188:191], v[24:27]
	s_setprio 0
	s_barrier
	s_add_u32 s38, s38, 0x40080
	s_addc_u32 s39, s39, 0
	s_mov_b32 m0, s58
	v_lshl_add_u64 v[144:145], s[38:39], 0, v[194:195]
	global_load_lds_dwordx4 v[144:145], off
	v_lshl_add_u64 v[144:145], s[38:39], 0, v[196:197]
	s_mov_b32 m0, s59
	s_nop 0
	global_load_lds_dwordx4 v[144:145], off
	s_waitcnt vmcnt(6)
	s_barrier
	s_setprio 1
	v_mfma_f32_16x16x32_bf16 v[68:71], v[12:15], v[160:163], v[68:71]
	v_mfma_f32_16x16x32_bf16 v[64:67], v[4:7], v[160:163], v[64:67]
	v_mfma_f32_16x16x32_bf16 v[52:55], v[12:15], v[168:171], v[52:55]
	v_mfma_f32_16x16x32_bf16 v[48:51], v[4:7], v[168:171], v[48:51]
	v_mfma_f32_16x16x32_bf16 v[36:39], v[12:15], v[176:179], v[36:39]
	v_mfma_f32_16x16x32_bf16 v[32:35], v[4:7], v[176:179], v[32:35]
	v_mfma_f32_16x16x32_bf16 v[20:23], v[12:15], v[184:187], v[20:23]
	v_mfma_f32_16x16x32_bf16 v[16:19], v[4:7], v[184:187], v[16:19]
	v_mfma_f32_16x16x32_bf16 v[68:71], v[8:11], v[164:167], v[68:71]
	v_mfma_f32_16x16x32_bf16 v[64:67], v[0:3], v[164:167], v[64:67]
	v_mfma_f32_16x16x32_bf16 v[52:55], v[8:11], v[172:175], v[52:55]
	v_mfma_f32_16x16x32_bf16 v[48:51], v[0:3], v[172:175], v[48:51]
	v_mfma_f32_16x16x32_bf16 v[36:39], v[8:11], v[180:183], v[36:39]
	v_mfma_f32_16x16x32_bf16 v[32:35], v[0:3], v[180:183], v[32:35]
	v_mfma_f32_16x16x32_bf16 v[20:23], v[8:11], v[188:191], v[20:23]
	v_mfma_f32_16x16x32_bf16 v[16:19], v[0:3], v[188:191], v[16:19]
	s_setprio 0
	s_add_i32 s34, s34, 2
	s_add_u32 s26, s26, 0x100
	s_addc_u32 s27, s27, 0
	s_add_u32 s77, s77, 0x100
	s_addc_u32 s78, s78, 0
	s_cmp_gt_u32 s34, 13
	s_barrier
	s_cbranch_scc0 .LBB0_402
; __device__ __forceinline__ uint2 pack4(f32x4 v) { return make_uint2(pack2(v[0], v[1]), pack2(v[2], v[3])); }
;   __device__ __forceinline__ void operator()(const AccT& acc, const Unit& u, int wr, int wc, int fr, int fq) const {
;     ...
;     for (int ai = 0; ai < 2; ++ai) {
;       f32x4 rv[4][2][2];
; #pragma unroll
;       for (int m = 0; m < 4; ++m) {
;         const size_t ro = (size_t)EPI_ROW(u, ai, m) * DM;
; #pragma unroll
;         for (int bj = 0; bj < 2; ++bj)
; #pragma unroll
;           for (int n = 0; n < 2; ++n) {
;             if (RF32) rv[m][bj][n] = *(const f32x4*)(resid32 + ro + EPI_COL(u, bj, n));
;             else {
;               const uint2 pk = *(const uint2*)(xb + ro + EPI_COL(u, bj, n));
;               rv[m][bj][n] = (f32x4){__uint_as_float(pk.x << 16), __uint_as_float(pk.x & 0xffff0000u), __uint_as_float(pk.y << 16), __uint_as_float(pk.y & 0xffff0000u)};
;             }
;           }
;       }
; #pragma unroll
;       for (int m = 0; m < 4; ++m) {
;         const int row = EPI_ROW(u, ai, m);
;         const size_t ro = (size_t)row * DM;
;         float ss = 0.f;
; #pragma unroll
;         for (int bj = 0; bj < 2; ++bj)
; #pragma unroll
;           for (int n = 0; n < 2; ++n) {
;             const f32x4 x = rv[m][bj][n] + acc[ai][bj][m][n];
;             ss += x[0] * x[0] + x[1] * x[1] + x[2] * x[2] + x[3] * x[3];
;             *(uint2*)(xb + ro + EPI_COL(u, bj, n)) = pack4(x);
;           }
;         ss += __shfl_xor(ss, 16);
;         ss += __shfl_xor(ss, 32);
;         if (fq == 0) atomicAdd(rowss + row, (unsigned long long)(ss * SS_FIX + 0.5f));
	v_lshl_add_u32 v208, s22, 8, v218
	v_lshl_or_b32 v206, s24, 8, v221
	v_ashrrev_i32_e32 v209, 31, v208
	v_lshlrev_b64 v[144:145], 12, v[208:209]
	v_ashrrev_i32_e32 v207, 31, v206
	v_lshl_add_u64 v[144:145], s[12:13], 0, v[144:145]
	v_lshlrev_b64 v[210:211], 2, v[206:207]
	v_lshl_add_u64 v[144:145], v[144:145], 0, v[210:211]
	global_load_dwordx4 v[226:229], v[144:145], off nt
	global_load_dwordx4 v[230:233], v[144:145], off offset:64 nt
	global_load_dwordx4 v[234:237], v[144:145], off offset:512 nt
	global_load_dwordx4 v[238:241], v[144:145], off offset:576 nt
	v_or_b32_e32 v216, 16, v208
	v_or_b32_e32 v214, 32, v208
	v_or_b32_e32 v212, 48, v208
	v_ashrrev_i32_e32 v217, 31, v216
	v_ashrrev_i32_e32 v215, 31, v214
	v_ashrrev_i32_e32 v213, 31, v212
	v_lshlrev_b64 v[144:145], 12, v[216:217]
	v_lshlrev_b64 v[146:147], 12, v[214:215]
	v_lshlrev_b64 v[148:149], 12, v[212:213]
	v_lshl_add_u64 v[144:145], s[12:13], 0, v[144:145]
	v_lshl_add_u64 v[146:147], s[12:13], 0, v[146:147]
	v_lshl_add_u64 v[148:149], s[12:13], 0, v[148:149]
	v_lshl_add_u64 v[144:145], v[144:145], 0, v[210:211]
	v_lshl_add_u64 v[146:147], v[146:147], 0, v[210:211]
	v_lshl_add_u64 v[224:225], v[148:149], 0, v[210:211]
	global_load_dwordx4 v[188:191], v[144:145], off nt
	global_load_dwordx4 v[184:187], v[144:145], off offset:64 nt
	global_load_dwordx4 v[180:183], v[144:145], off offset:512 nt
	global_load_dwordx4 v[176:179], v[144:145], off offset:576 nt
	global_load_dwordx4 v[172:175], v[146:147], off nt
	global_load_dwordx4 v[168:171], v[146:147], off offset:64 nt
	global_load_dwordx4 v[164:167], v[146:147], off offset:512 nt
	global_load_dwordx4 v[160:163], v[146:147], off offset:576 nt
	global_load_dwordx4 v[156:159], v[224:225], off nt
	global_load_dwordx4 v[152:155], v[224:225], off offset:64 nt
	global_load_dwordx4 v[148:151], v[224:225], off offset:512 nt
	s_nop 0
	global_load_dwordx4 v[144:147], v[224:225], off offset:576 nt
	v_and_b32_e32 v224, 64, v222
	v_xor_b32_e32 v223, 16, v222
	v_add_u32_e32 v224, 64, v224
	v_xor_b32_e32 v225, 32, v222
	v_cmp_lt_i32_e32 vcc, v223, v224
	v_lshlrev_b64 v[242:243], 11, v[208:209]
	v_lshl_add_u64 v[242:243], s[54:55], 0, v[242:243]
	v_cndmask_b32_e32 v223, v222, v223, vcc
	v_cmp_lt_i32_e32 vcc, v225, v224
	v_lshlrev_b32_e32 v224, 2, v223
	v_lshl_add_u64 v[242:243], v[206:207], 1, v[242:243]
	v_cndmask_b32_e32 v225, v222, v225, vcc
	v_lshlrev_b32_e32 v223, 2, v225
	s_waitcnt vmcnt(0)
	v_pk_add_f32 v[140:141], v[140:141], v[226:227]
	v_pk_add_f32 v[136:137], v[136:137], v[230:231]
	v_pk_add_f32 v[132:133], v[132:133], v[234:235]
	v_pk_add_f32 v[226:227], v[128:129], v[238:239]
	v_mul_f32_e32 v225, v141, v141
	v_cvt_pk_bf16_f32 v128, v140, v141
	v_mul_f32_e32 v141, v137, v137
	v_pk_add_f32 v[142:143], v[142:143], v[228:229]
	v_pk_add_f32 v[138:139], v[138:139], v[232:233]
	v_cvt_pk_bf16_f32 v228, v136, v137
	v_mul_f32_e32 v137, v133, v133
	v_fmac_f32_e32 v225, v140, v140
	v_fmac_f32_e32 v141, v136, v136
	v_pk_add_f32 v[134:135], v[134:135], v[236:237]
	v_mul_f32_e32 v229, v227, v227
	v_fmac_f32_e32 v137, v132, v132
	v_fmac_f32_e32 v225, v142, v142
	v_fmac_f32_e32 v141, v138, v138
	v_pk_add_f32 v[130:131], v[130:131], v[240:241]
	v_cvt_pk_bf16_f32 v129, v142, v143
	v_fmac_f32_e32 v229, v226, v226
	v_fmac_f32_e32 v137, v134, v134
	v_fmac_f32_e32 v225, v143, v143
	v_fmac_f32_e32 v141, v139, v139
	global_store_dwordx2 v[242:243], v[128:129], off
	v_fmac_f32_e32 v229, v130, v130
	v_fmac_f32_e32 v137, v135, v135
	v_add_f32_e32 v128, v225, v141
	v_add_f32_e32 v128, v128, v137
	v_fmac_f32_e32 v229, v131, v131
	v_add_f32_e32 v128, v128, v229
	ds_bpermute_b32 v129, v224, v128
	v_cvt_pk_bf16_f32 v132, v132, v133
	v_cvt_pk_bf16_f32 v133, v134, v135
	v_cvt_pk_bf16_f32 v229, v138, v139
	global_store_dwordx2 v[242:243], v[132:133], off offset:256
	s_waitcnt lgkmcnt(0)
	v_add_f32_e32 v128, v128, v129
	ds_bpermute_b32 v129, v223, v128
	v_cvt_pk_bf16_f32 v132, v226, v227
	v_cvt_pk_bf16_f32 v133, v130, v131
	global_store_dwordx2 v[242:243], v[228:229], off offset:32
	global_store_dwordx2 v[242:243], v[132:133], off offset:288
	s_and_saveexec_b64 s[22:23], s[4:5]
	s_cbranch_execz .LBB0_405
	s_waitcnt lgkmcnt(0)
	v_add_f32_e32 v128, v128, v129
	v_fma_f32 v128, v128, s67, 0.5
	v_trunc_f32_e32 v128, v128
	v_mul_f32_e32 v129, 0x2f800000, v128
	v_floor_f32_e32 v129, v129
	v_fmac_f32_e32 v128, 0xcf800000, v129
	v_cvt_u32_f32_e32 v128, v128
	v_cvt_u32_f32_e32 v129, v129
	v_lshl_add_u64 v[130:131], v[208:209], 3, s[86:87]
	global_atomic_add_x2 v[130:131], v[128:129], off

; __device__ __forceinline__ uint2 pack4(f32x4 v) { return make_uint2(pack2(v[0], v[1]), pack2(v[2], v[3])); }
;   __device__ __forceinline__ void operator()(const AccT& acc, const Unit& u, int wr, int wc, int fr, int fq) const {
;     ...
;     for (int ai = 0; ai < 2; ++ai) {
;       f32x4 rv[4][2][2];
; #pragma unroll
;       for (int m = 0; m < 4; ++m) {
;         const size_t ro = (size_t)EPI_ROW(u, ai, m) * DM;
; #pragma unroll
;         for (int bj = 0; bj < 2; ++bj)
; #pragma unroll
;           for (int n = 0; n < 2; ++n) {
;             if (RF32) rv[m][bj][n] = *(const f32x4*)(resid32 + ro + EPI_COL(u, bj, n));
;             else {
;               const uint2 pk = *(const uint2*)(xb + ro + EPI_COL(u, bj, n));
;               rv[m][bj][n] = (f32x4){__uint_as_float(pk.x << 16), __uint_as_float(pk.x & 0xffff0000u), __uint_as_float(pk.y << 16), __uint_as_float(pk.y & 0xffff0000u)};
;             }
;           }
;       }
; #pragma unroll
;       for (int m = 0; m < 4; ++m) {
;         const int row = EPI_ROW(u, ai, m);
;         const size_t ro = (size_t)row * DM;
;         float ss = 0.f;
; #pragma unroll
;         for (int bj = 0; bj < 2; ++bj)
; #pragma unroll
;           for (int n = 0; n < 2; ++n) {
;             const f32x4 x = rv[m][bj][n] + acc[ai][bj][m][n];
;             ss += x[0] * x[0] + x[1] * x[1] + x[2] * x[2] + x[3] * x[3];
;             *(uint2*)(xb + ro + EPI_COL(u, bj, n)) = pack4(x);
;           }
;         ss += __shfl_xor(ss, 16);
;         ss += __shfl_xor(ss, 32);
;         if (fq == 0) atomicAdd(rowss + row, (unsigned long long)(ss * SS_FIX + 0.5f));
.LBB0_411:
	s_or_b64 exec, exec, s[22:23]
	v_add_u32_e32 v134, 0x80, v208
	v_ashrrev_i32_e32 v135, 31, v134
	s_waitcnt lgkmcnt(0)
	v_lshlrev_b64 v[80:81], 12, v[134:135]
	v_lshl_add_u64 v[80:81], s[12:13], 0, v[80:81]
	v_lshl_add_u64 v[80:81], v[80:81], 0, v[210:211]
	global_load_dwordx4 v[136:139], v[80:81], off nt
	global_load_dwordx4 v[140:143], v[80:81], off offset:64 nt
	global_load_dwordx4 v[144:147], v[80:81], off offset:512 nt
	global_load_dwordx4 v[148:151], v[80:81], off offset:576 nt
	v_add_u32_e32 v132, 0x90, v208
	v_add_u32_e32 v130, 0xa0, v208
	v_add_u32_e32 v128, 0xb0, v208
	v_ashrrev_i32_e32 v133, 31, v132
	v_ashrrev_i32_e32 v131, 31, v130
	v_ashrrev_i32_e32 v129, 31, v128
	v_lshlrev_b64 v[80:81], 12, v[132:133]
	v_lshlrev_b64 v[82:83], 12, v[130:131]
	v_lshlrev_b64 v[84:85], 12, v[128:129]
	v_lshl_add_u64 v[80:81], s[12:13], 0, v[80:81]
	v_lshl_add_u64 v[82:83], s[12:13], 0, v[82:83]
	v_lshl_add_u64 v[84:85], s[12:13], 0, v[84:85]
	v_lshl_add_u64 v[80:81], v[80:81], 0, v[210:211]
	v_lshl_add_u64 v[82:83], v[82:83], 0, v[210:211]
	v_lshl_add_u64 v[152:153], v[84:85], 0, v[210:211]
	global_load_dwordx4 v[124:127], v[80:81], off nt
	global_load_dwordx4 v[120:123], v[80:81], off offset:64 nt
	global_load_dwordx4 v[116:119], v[80:81], off offset:512 nt
	global_load_dwordx4 v[112:115], v[80:81], off offset:576 nt
	global_load_dwordx4 v[108:111], v[82:83], off nt
	global_load_dwordx4 v[104:107], v[82:83], off offset:64 nt
	global_load_dwordx4 v[100:103], v[82:83], off offset:512 nt
	global_load_dwordx4 v[96:99], v[82:83], off offset:576 nt
	global_load_dwordx4 v[92:95], v[152:153], off nt
	global_load_dwordx4 v[88:91], v[152:153], off offset:64 nt
	global_load_dwordx4 v[84:87], v[152:153], off offset:512 nt
	s_nop 0
	global_load_dwordx4 v[80:83], v[152:153], off offset:576 nt
	v_lshlrev_b64 v[152:153], 11, v[134:135]
	v_lshl_add_u64 v[152:153], s[54:55], 0, v[152:153]
	v_lshl_add_u64 v[152:153], v[206:207], 1, v[152:153]
	s_waitcnt vmcnt(15)
	v_pk_add_f32 v[76:77], v[76:77], v[136:137]
	s_waitcnt vmcnt(14)
	v_pk_add_f32 v[72:73], v[72:73], v[140:141]
	v_pk_add_f32 v[78:79], v[78:79], v[138:139]
	s_waitcnt vmcnt(13)
	v_pk_add_f32 v[68:69], v[68:69], v[144:145]
	s_waitcnt vmcnt(12)
	v_pk_add_f32 v[136:137], v[64:65], v[148:149]
	v_mul_f32_e32 v139, v77, v77
	v_cvt_pk_bf16_f32 v64, v76, v77
	v_mul_f32_e32 v77, v73, v73
	v_pk_add_f32 v[74:75], v[74:75], v[142:143]
	v_cvt_pk_bf16_f32 v138, v72, v73
	v_mul_f32_e32 v73, v69, v69
	v_fmac_f32_e32 v139, v76, v76
	v_fmac_f32_e32 v77, v72, v72
	v_pk_add_f32 v[70:71], v[70:71], v[146:147]
	v_mul_f32_e32 v140, v137, v137
	v_fmac_f32_e32 v73, v68, v68
	v_fmac_f32_e32 v139, v78, v78
	v_fmac_f32_e32 v77, v74, v74
	v_pk_add_f32 v[66:67], v[66:67], v[150:151]
	v_cvt_pk_bf16_f32 v65, v78, v79
	v_fmac_f32_e32 v140, v136, v136
	v_fmac_f32_e32 v73, v70, v70
	v_fmac_f32_e32 v139, v79, v79
	v_fmac_f32_e32 v77, v75, v75
	global_store_dwordx2 v[152:153], v[64:65], off
	v_fmac_f32_e32 v140, v66, v66
	v_fmac_f32_e32 v73, v71, v71
	v_add_f32_e32 v64, v139, v77
	v_add_f32_e32 v64, v64, v73
	v_fmac_f32_e32 v140, v67, v67
	v_add_f32_e32 v64, v64, v140
	ds_bpermute_b32 v65, v224, v64
	v_cvt_pk_bf16_f32 v68, v68, v69
	v_cvt_pk_bf16_f32 v69, v70, v71
	v_cvt_pk_bf16_f32 v139, v74, v75
	global_store_dwordx2 v[152:153], v[68:69], off offset:256
	s_waitcnt lgkmcnt(0)
	v_add_f32_e32 v64, v64, v65
	ds_bpermute_b32 v65, v223, v64
	v_cvt_pk_bf16_f32 v68, v136, v137
	v_cvt_pk_bf16_f32 v69, v66, v67
	global_store_dwordx2 v[152:153], v[138:139], off offset:32
	global_store_dwordx2 v[152:153], v[68:69], off offset:288
	s_and_saveexec_b64 s[22:23], s[4:5]
	s_cbranch_execz .LBB0_413
	s_waitcnt lgkmcnt(0)
	v_add_f32_e32 v64, v64, v65
	v_fma_f32 v64, v64, s67, 0.5
	v_trunc_f32_e32 v64, v64
	v_mul_f32_e32 v65, 0x2f800000, v64
	v_floor_f32_e32 v65, v65
	v_fmac_f32_e32 v64, 0xcf800000, v65
	v_cvt_u32_f32_e32 v64, v64
	v_cvt_u32_f32_e32 v65, v65
	v_lshl_add_u64 v[66:67], v[134:135], 3, s[86:87]
	global_atomic_add_x2 v[66:67], v[64:65], off
